# E52: counted lgkmcnt(6) waits before each P.V MFMA in both attention loops instead of lgkmcnt(0) per group of four
# speedup vs baseline: 1.0051x; 1.0051x over previous
; #define SBAR() __builtin_amdgcn_sched_barrier(0)
; #define SWRITE(b, i) do { STG_T() const int _sv = VSTV(), _sk = LDSK(); *(u32x4*)(V_lds + (b) * SHM_V + _sv) = sr_[i].vs0; *(u32x4*)(V_lds + (b) * SHM_V + _sv + 8192) = sr_[i].vs1; \
;     _Pragma("unroll") for (int _p = 0; _p < NP; ++_p) *(u32x4*)(K_lds + (b) * KT + _sk + _p * 128) = sr_[i].ks[_p]; } while (0)
; #define SWAIT() do { if constexpr (SD == 2) { if constexpr (NP == 1) asm volatile("s_waitcnt vmcnt(3)" ::: "memory"); else asm volatile("s_waitcnt vmcnt(5)" ::: "memory"); } else asm volatile("s_waitcnt vmcnt(0)" ::: "memory"); } while (0)
; #define RESC(a) do { if (__any((a) < 1.f)) { if (hi == 0) al_l[r32] = (a); asm volatile("s_waitcnt lgkmcnt(0)" ::: "memory"); \
;     _Pragma("unroll") for (int d = 0; d < 4; ++d) _Pragma("unroll") for (int r = 0; r < 16; ++r) o[d][r] *= al_l[crow(r, hi)]; } } while (0)
; template <int D0> __device__ __forceinline__ void pv_one_mi(f32x16& od, int vb, bf16x8 pa0, bf16x8 pa1, bf16x8 pa2, bf16x8 pa3, f32x16& q0) {
;   const s16x4 l0 = tr_read<v_rd_off(D0, 0, 0)>(vb), h0 = tr_read<v_rd_off(D0, 0, 1)>(vb), l1 = tr_read<v_rd_off(D0, 1, 0)>(vb), h1 = tr_read<v_rd_off(D0, 1, 1)>(vb);
;   const s16x4 l2 = tr_read<v_rd_off(D0, 2, 0)>(vb), h2 = tr_read<v_rd_off(D0, 2, 1)>(vb), l3 = tr_read<v_rd_off(D0, 3, 0)>(vb), h3 = tr_read<v_rd_off(D0, 3, 1)>(vb);
;   asm volatile("s_waitcnt lgkmcnt(0)" ::: "memory"); SBAR();
;     ...
;   od = __builtin_amdgcn_mfma_f32_32x32x16_bf16(pa0, PK(l0, h0), od, 0, 0, 0);
;   od = __builtin_amdgcn_mfma_f32_32x32x16_bf16(pa1, PK(l1, h1), od, 0, 0, 0);
;   od = __builtin_amdgcn_mfma_f32_32x32x16_bf16(pa2, PK(l2, h2), od, 0, 0, 0);
;   od = __builtin_amdgcn_mfma_f32_32x32x16_bf16(pa3, PK(l3, h3), od, 0, 0, 0);
;     ...
; #pragma unroll
;   for (int r = 4 * D0; r < 4 * D0 + 4; ++r) q0[r] = __builtin_amdgcn_exp2f(q0[r]);
; }
; __device__ __forceinline__ void pv_mi(f32x16* o, int vb, bf16x8 pa0, bf16x8 pa1, bf16x8 pa2, bf16x8 pa3, f32x16& q0) {
;   pv_one_mi<0>(o[0], vb, pa0, pa1, pa2, pa3, q0); pv_one_mi<1>(o[1], vb, pa0, pa1, pa2, pa3, q0);
;   pv_one_mi<2>(o[2], vb, pa0, pa1, pa2, pa3, q0); pv_one_mi<3>(o[3], vb, pa0, pa1, pa2, pa3, q0);
; }
; template <int NQK, int SD, bool MI> ...
;     ...
;     PVSM(vb0 + rp * SHM_V, pB0, pB1, mnB);
;     SWAIT(); SWRITE(rn, SE);
;     RESC(alB); __syncthreads(); ROT();
.LBB0_1270:
	v_cvt_pk_bf16_f32 v216, v175, v177
	v_cvt_pk_bf16_f32 v217, v178, v181
	v_cvt_pk_bf16_f32 v218, v182, v185
	v_cvt_pk_bf16_f32 v219, v189, v199
	v_cvt_pk_bf16_f32 v176, v176, v179
	v_cvt_pk_bf16_f32 v177, v180, v183
	v_cvt_pk_bf16_f32 v178, v184, v191
	v_cvt_pk_bf16_f32 v179, v198, v200
	v_cvt_pk_bf16_f32 v80, v80, v81
	v_cvt_pk_bf16_f32 v81, v82, v83
	v_cvt_pk_bf16_f32 v82, v201, v214
	v_cvt_pk_bf16_f32 v83, v215, v87
	v_cvt_pk_bf16_f32 v84, v84, v85
	v_cvt_pk_bf16_f32 v85, v86, v88
	v_cvt_pk_bf16_f32 v86, v89, v90
	v_cvt_pk_bf16_f32 v87, v91, v92
	s_cmp_lg_u32 16, -1
	s_cselect_b32 s8, 16, 0
	s_addk_i32 s8, 0x4000
	v_add_u32_e32 v173, s8, v171
	ds_read_b64_tr_b16 v[88:89], v173 offset:0
	ds_read_b64_tr_b16 v[90:91], v173 offset:0x800
	ds_read_b64_tr_b16 v[92:93], v173 offset:0x1000
	ds_read_b64_tr_b16 v[94:95], v173 offset:0x1800
	ds_read_b64_tr_b16 v[180:181], v173 offset:0x2000
	ds_read_b64_tr_b16 v[182:183], v173 offset:0x2800
	ds_read_b64_tr_b16 v[198:199], v173 offset:0x3000
	ds_read_b64_tr_b16 v[200:201], v173 offset:0x3800
	s_waitcnt lgkmcnt(6)
	s_nop 0
	v_mfma_f32_32x32x16_bf16 v[0:15], v[216:219], v[88:91], v[0:15]
	ds_read_b64_tr_b16 v[88:89], v173 offset:0x200
	ds_read_b64_tr_b16 v[90:91], v173 offset:0xa00
	s_waitcnt lgkmcnt(6)
	v_mfma_f32_32x32x16_bf16 v[0:15], v[176:179], v[92:95], v[0:15]
	ds_read_b64_tr_b16 v[92:93], v173 offset:0x1200
	ds_read_b64_tr_b16 v[94:95], v173 offset:0x1a00
	s_waitcnt lgkmcnt(6)
	v_mfma_f32_32x32x16_bf16 v[0:15], v[80:83], v[180:183], v[0:15]
	ds_read_b64_tr_b16 v[180:181], v173 offset:0x2200
	ds_read_b64_tr_b16 v[182:183], v173 offset:0x2a00
	s_waitcnt lgkmcnt(6)
	v_mfma_f32_32x32x16_bf16 v[0:15], v[84:87], v[198:201], v[0:15]
	ds_read_b64_tr_b16 v[198:199], v173 offset:0x3200
	ds_read_b64_tr_b16 v[200:201], v173 offset:0x3a00
	s_waitcnt lgkmcnt(6)
	v_mfma_f32_32x32x16_bf16 v[16:31], v[216:219], v[88:91], v[16:31]
	ds_read_b64_tr_b16 v[88:89], v173 offset:0x400
	ds_read_b64_tr_b16 v[90:91], v173 offset:0xc00
	s_waitcnt lgkmcnt(6)
	v_mfma_f32_32x32x16_bf16 v[16:31], v[176:179], v[92:95], v[16:31]
	ds_read_b64_tr_b16 v[92:93], v173 offset:0x1400
	ds_read_b64_tr_b16 v[94:95], v173 offset:0x1c00
	s_waitcnt lgkmcnt(6)
	v_mfma_f32_32x32x16_bf16 v[16:31], v[80:83], v[180:183], v[16:31]
	ds_read_b64_tr_b16 v[180:181], v173 offset:0x2400
	ds_read_b64_tr_b16 v[182:183], v173 offset:0x2c00
	s_waitcnt lgkmcnt(6)
	v_mfma_f32_32x32x16_bf16 v[16:31], v[84:87], v[198:201], v[16:31]
	ds_read_b64_tr_b16 v[198:199], v173 offset:0x3400
	ds_read_b64_tr_b16 v[200:201], v173 offset:0x3c00
	s_waitcnt lgkmcnt(6)
	v_mfma_f32_32x32x16_bf16 v[48:63], v[216:219], v[88:91], v[48:63]
	ds_read_b64_tr_b16 v[88:89], v173 offset:0x600
	ds_read_b64_tr_b16 v[90:91], v173 offset:0xe00
	s_waitcnt lgkmcnt(6)
	v_mfma_f32_32x32x16_bf16 v[48:63], v[176:179], v[92:95], v[48:63]
	ds_read_b64_tr_b16 v[92:93], v173 offset:0x1600
	ds_read_b64_tr_b16 v[94:95], v173 offset:0x1e00
	s_waitcnt lgkmcnt(6)
	v_mfma_f32_32x32x16_bf16 v[48:63], v[80:83], v[180:183], v[48:63]
	ds_read_b64_tr_b16 v[180:181], v173 offset:0x2600
	ds_read_b64_tr_b16 v[182:183], v173 offset:0x2e00
	s_waitcnt lgkmcnt(6)
	v_mfma_f32_32x32x16_bf16 v[48:63], v[84:87], v[198:201], v[48:63]
	ds_read_b64_tr_b16 v[198:199], v173 offset:0x3600
	ds_read_b64_tr_b16 v[200:201], v173 offset:0x3e00
	s_waitcnt lgkmcnt(0)
	v_mfma_f32_32x32x16_bf16 v[64:79], v[216:219], v[88:91], v[64:79]
	s_waitcnt vmcnt(3)
	v_cmp_gt_f32_e32 vcc, 1.0, v172
	s_waitcnt vmcnt(2)
	ds_write_b128 v168, v[146:149]
	s_waitcnt vmcnt(1)
	ds_write_b128 v168, v[150:153] offset:8192
	s_waitcnt vmcnt(0)
	ds_write_b128 v174, v[154:157]
	v_mfma_f32_32x32x16_bf16 v[64:79], v[176:179], v[92:95], v[64:79]
	v_mfma_f32_32x32x16_bf16 v[64:79], v[80:83], v[180:183], v[64:79]
	v_mfma_f32_32x32x16_bf16 v[64:79], v[84:87], v[198:201], v[64:79]
	s_cbranch_vccz .LBB0_1274
	s_and_saveexec_b64 s[8:9], s[6:7]
	ds_write_b32 v165, v172 offset:128
	s_or_b64 exec, exec, s[8:9]
	s_waitcnt lgkmcnt(0)
	v_add_u32_e32 v92, v164, v158
	ds_read_b128 v[80:83], v92 offset:224
	ds_read_b128 v[84:87], v92 offset:192
	ds_read_b128 v[88:91], v92 offset:160
	ds_read_b128 v[92:95], v92 offset:128
	s_waitcnt lgkmcnt(3)
	v_pk_mul_f32 v[12:13], v[12:13], v[80:81]
	s_waitcnt lgkmcnt(2)
	v_pk_mul_f32 v[8:9], v[8:9], v[84:85]
	s_waitcnt lgkmcnt(1)
	v_pk_mul_f32 v[4:5], v[4:5], v[88:89]
	v_pk_mul_f32 v[14:15], v[14:15], v[82:83]
	v_pk_mul_f32 v[10:11], v[10:11], v[86:87]
	v_pk_mul_f32 v[6:7], v[6:7], v[90:91]
	s_waitcnt lgkmcnt(0)
	v_pk_mul_f32 v[2:3], v[2:3], v[94:95]
	v_pk_mul_f32 v[0:1], v[0:1], v[92:93]
	v_pk_mul_f32 v[28:29], v[28:29], v[80:81]
	v_pk_mul_f32 v[24:25], v[24:25], v[84:85]
	v_pk_mul_f32 v[20:21], v[20:21], v[88:89]
	v_pk_mul_f32 v[30:31], v[30:31], v[82:83]
	v_pk_mul_f32 v[26:27], v[26:27], v[86:87]
	v_pk_mul_f32 v[22:23], v[22:23], v[90:91]
	v_pk_mul_f32 v[18:19], v[18:19], v[94:95]
	v_pk_mul_f32 v[16:17], v[16:17], v[92:93]
	v_pk_mul_f32 v[60:61], v[60:61], v[80:81]
	v_pk_mul_f32 v[56:57], v[56:57], v[84:85]
	v_pk_mul_f32 v[52:53], v[52:53], v[88:89]
	v_pk_mul_f32 v[62:63], v[62:63], v[82:83]
	v_pk_mul_f32 v[58:59], v[58:59], v[86:87]
	v_pk_mul_f32 v[54:55], v[54:55], v[90:91]
	v_pk_mul_f32 v[50:51], v[50:51], v[94:95]
	v_pk_mul_f32 v[48:49], v[48:49], v[92:93]
	v_pk_mul_f32 v[76:77], v[76:77], v[80:81]
	v_pk_mul_f32 v[72:73], v[72:73], v[84:85]
	v_pk_mul_f32 v[68:69], v[68:69], v[88:89]
	v_pk_mul_f32 v[78:79], v[78:79], v[82:83]
	v_pk_mul_f32 v[74:75], v[74:75], v[86:87]
	v_pk_mul_f32 v[70:71], v[70:71], v[90:91]
	v_pk_mul_f32 v[66:67], v[66:67], v[94:95]
	v_pk_mul_f32 v[64:65], v[64:65], v[92:93]

; #define SBAR() __builtin_amdgcn_sched_barrier(0)
; #define SWRITE(b, i) do { STG_T() const int _sv = VSTV(), _sk = LDSK(); *(u32x4*)(V_lds + (b) * SHM_V + _sv) = sr_[i].vs0; *(u32x4*)(V_lds + (b) * SHM_V + _sv + 8192) = sr_[i].vs1; \
;     _Pragma("unroll") for (int _p = 0; _p < NP; ++_p) *(u32x4*)(K_lds + (b) * KT + _sk + _p * 128) = sr_[i].ks[_p]; } while (0)
; #define SWAIT() do { if constexpr (SD == 2) { if constexpr (NP == 1) asm volatile("s_waitcnt vmcnt(3)" ::: "memory"); else asm volatile("s_waitcnt vmcnt(5)" ::: "memory"); } else asm volatile("s_waitcnt vmcnt(0)" ::: "memory"); } while (0)
; #define RESC(a) do { if (__any((a) < 1.f)) { if (hi == 0) al_l[r32] = (a); asm volatile("s_waitcnt lgkmcnt(0)" ::: "memory"); \
;     _Pragma("unroll") for (int d = 0; d < 4; ++d) _Pragma("unroll") for (int r = 0; r < 16; ++r) o[d][r] *= al_l[crow(r, hi)]; } } while (0)
; template <int D0> __device__ __forceinline__ void pv_one_mi(f32x16& od, int vb, bf16x8 pa0, bf16x8 pa1, bf16x8 pa2, bf16x8 pa3, f32x16& q0) {
;   const s16x4 l0 = tr_read<v_rd_off(D0, 0, 0)>(vb), h0 = tr_read<v_rd_off(D0, 0, 1)>(vb), l1 = tr_read<v_rd_off(D0, 1, 0)>(vb), h1 = tr_read<v_rd_off(D0, 1, 1)>(vb);
;   const s16x4 l2 = tr_read<v_rd_off(D0, 2, 0)>(vb), h2 = tr_read<v_rd_off(D0, 2, 1)>(vb), l3 = tr_read<v_rd_off(D0, 3, 0)>(vb), h3 = tr_read<v_rd_off(D0, 3, 1)>(vb);
;   asm volatile("s_waitcnt lgkmcnt(0)" ::: "memory"); SBAR();
;     ...
;   od = __builtin_amdgcn_mfma_f32_32x32x16_bf16(pa0, PK(l0, h0), od, 0, 0, 0);
;   od = __builtin_amdgcn_mfma_f32_32x32x16_bf16(pa1, PK(l1, h1), od, 0, 0, 0);
;   od = __builtin_amdgcn_mfma_f32_32x32x16_bf16(pa2, PK(l2, h2), od, 0, 0, 0);
;   od = __builtin_amdgcn_mfma_f32_32x32x16_bf16(pa3, PK(l3, h3), od, 0, 0, 0);
;     ...
; #pragma unroll
;   for (int r = 4 * D0; r < 4 * D0 + 4; ++r) q0[r] = __builtin_amdgcn_exp2f(q0[r]);
; }
; __device__ __forceinline__ void pv_mi(f32x16* o, int vb, bf16x8 pa0, bf16x8 pa1, bf16x8 pa2, bf16x8 pa3, f32x16& q0) {
;   pv_one_mi<0>(o[0], vb, pa0, pa1, pa2, pa3, q0); pv_one_mi<1>(o[1], vb, pa0, pa1, pa2, pa3, q0);
;   pv_one_mi<2>(o[2], vb, pa0, pa1, pa2, pa3, q0); pv_one_mi<3>(o[3], vb, pa0, pa1, pa2, pa3, q0);
; }
; template <int NQK, int SD, bool MI> ...
;     ...
;     PVSM(vb0 + rp * SHM_V, pA0, pA1, mnA);
;     SWAIT(); SWRITE(rn, SO);
;     RESC(alA); __syncthreads(); ROT();
.LBB0_1275:
	v_cvt_pk_bf16_f32 v128, v112, v146
	v_cvt_pk_bf16_f32 v129, v114, v147
	v_cvt_pk_bf16_f32 v130, v148, v149
	v_cvt_pk_bf16_f32 v131, v150, v151
	v_cvt_pk_bf16_f32 v110, v113, v115
	v_cvt_pk_bf16_f32 v111, v116, v117
	v_cvt_pk_bf16_f32 v112, v118, v119
	v_cvt_pk_bf16_f32 v113, v120, v121
	v_cvt_pk_bf16_f32 v114, v122, v123
	v_cvt_pk_bf16_f32 v115, v124, v99
	v_cvt_pk_bf16_f32 v116, v100, v125
	v_cvt_pk_bf16_f32 v117, v126, v127
	v_cvt_pk_bf16_f32 v100, v101, v102
	v_cvt_pk_bf16_f32 v101, v103, v104
	v_cvt_pk_bf16_f32 v102, v105, v106
	v_cvt_pk_bf16_f32 v103, v107, v108
	s_cmp_lg_u32 16, -1
	s_cselect_b32 s8, 16, 0
	s_add_i32 s8, s8, 0x8000
	v_add_u32_e32 v99, s8, v171
	ds_read_b64_tr_b16 v[104:105], v99 offset:0
	ds_read_b64_tr_b16 v[106:107], v99 offset:0x800
	ds_read_b64_tr_b16 v[118:119], v99 offset:0x1000
	ds_read_b64_tr_b16 v[120:121], v99 offset:0x1800
	ds_read_b64_tr_b16 v[122:123], v99 offset:0x2000
	ds_read_b64_tr_b16 v[124:125], v99 offset:0x2800
	ds_read_b64_tr_b16 v[132:133], v99 offset:0x3000
	ds_read_b64_tr_b16 v[134:135], v99 offset:0x3800
	s_waitcnt lgkmcnt(6)
	s_nop 0
	v_mfma_f32_32x32x16_bf16 v[0:15], v[128:131], v[104:107], v[0:15]
	ds_read_b64_tr_b16 v[104:105], v99 offset:0x200
	ds_read_b64_tr_b16 v[106:107], v99 offset:0xa00
	s_waitcnt lgkmcnt(6)
	v_mfma_f32_32x32x16_bf16 v[0:15], v[110:113], v[118:121], v[0:15]
	ds_read_b64_tr_b16 v[118:119], v99 offset:0x1200
	ds_read_b64_tr_b16 v[120:121], v99 offset:0x1a00
	s_waitcnt lgkmcnt(6)
	v_mfma_f32_32x32x16_bf16 v[0:15], v[114:117], v[122:125], v[0:15]
	ds_read_b64_tr_b16 v[122:123], v99 offset:0x2200
	ds_read_b64_tr_b16 v[124:125], v99 offset:0x2a00
	s_waitcnt lgkmcnt(6)
	v_mfma_f32_32x32x16_bf16 v[0:15], v[100:103], v[132:135], v[0:15]
	ds_read_b64_tr_b16 v[132:133], v99 offset:0x3200
	ds_read_b64_tr_b16 v[134:135], v99 offset:0x3a00
	s_waitcnt lgkmcnt(6)
	v_mfma_f32_32x32x16_bf16 v[16:31], v[128:131], v[104:107], v[16:31]
	ds_read_b64_tr_b16 v[104:105], v99 offset:0x400
	ds_read_b64_tr_b16 v[106:107], v99 offset:0xc00
	s_waitcnt lgkmcnt(6)
	v_mfma_f32_32x32x16_bf16 v[16:31], v[110:113], v[118:121], v[16:31]
	ds_read_b64_tr_b16 v[118:119], v99 offset:0x1400
	ds_read_b64_tr_b16 v[120:121], v99 offset:0x1c00
	s_waitcnt lgkmcnt(6)
	v_mfma_f32_32x32x16_bf16 v[16:31], v[114:117], v[122:125], v[16:31]
	ds_read_b64_tr_b16 v[122:123], v99 offset:0x2400
	ds_read_b64_tr_b16 v[124:125], v99 offset:0x2c00
	s_waitcnt lgkmcnt(6)
	v_mfma_f32_32x32x16_bf16 v[16:31], v[100:103], v[132:135], v[16:31]
	ds_read_b64_tr_b16 v[132:133], v99 offset:0x3400
	ds_read_b64_tr_b16 v[134:135], v99 offset:0x3c00
	s_waitcnt lgkmcnt(6)
	v_mfma_f32_32x32x16_bf16 v[48:63], v[128:131], v[104:107], v[48:63]
	ds_read_b64_tr_b16 v[104:105], v99 offset:0x600
	ds_read_b64_tr_b16 v[106:107], v99 offset:0xe00
	s_waitcnt lgkmcnt(6)
	v_mfma_f32_32x32x16_bf16 v[48:63], v[110:113], v[118:121], v[48:63]
	ds_read_b64_tr_b16 v[118:119], v99 offset:0x1600
	ds_read_b64_tr_b16 v[120:121], v99 offset:0x1e00
	s_waitcnt lgkmcnt(6)
	v_mfma_f32_32x32x16_bf16 v[48:63], v[114:117], v[122:125], v[48:63]
	ds_read_b64_tr_b16 v[122:123], v99 offset:0x2600
	ds_read_b64_tr_b16 v[124:125], v99 offset:0x2e00
	s_waitcnt lgkmcnt(6)
	v_mfma_f32_32x32x16_bf16 v[48:63], v[100:103], v[132:135], v[48:63]
	ds_read_b64_tr_b16 v[132:133], v99 offset:0x3600
	ds_read_b64_tr_b16 v[134:135], v99 offset:0x3e00
	s_waitcnt lgkmcnt(0)
	v_mfma_f32_32x32x16_bf16 v[64:79], v[128:131], v[104:107], v[64:79]
	v_cmp_gt_f32_e32 vcc, 1.0, v98
	v_mfma_f32_32x32x16_bf16 v[64:79], v[110:113], v[118:121], v[64:79]
	v_mfma_f32_32x32x16_bf16 v[64:79], v[114:117], v[122:125], v[64:79]
	v_mfma_f32_32x32x16_bf16 v[64:79], v[100:103], v[132:135], v[64:79]
	s_cbranch_vccz .LBB0_1279
	s_and_saveexec_b64 s[8:9], s[6:7]
	ds_write_b32 v165, v98 offset:128
	s_or_b64 exec, exec, s[8:9]
	s_waitcnt lgkmcnt(0)
	v_add_u32_e32 v99, v164, v158
	ds_read_b128 v[100:103], v99 offset:224
	ds_read_b128 v[104:107], v99 offset:192
	ds_read_b128 v[108:111], v99 offset:160
	ds_read_b128 v[112:115], v99 offset:128
	s_waitcnt lgkmcnt(3)
	v_pk_mul_f32 v[12:13], v[12:13], v[100:101]
	s_waitcnt lgkmcnt(2)
	v_pk_mul_f32 v[8:9], v[8:9], v[104:105]
	s_waitcnt lgkmcnt(1)
	v_pk_mul_f32 v[4:5], v[4:5], v[108:109]
	v_pk_mul_f32 v[14:15], v[14:15], v[102:103]
	v_pk_mul_f32 v[10:11], v[10:11], v[106:107]
	v_pk_mul_f32 v[6:7], v[6:7], v[110:111]
	s_waitcnt lgkmcnt(0)
	v_pk_mul_f32 v[2:3], v[2:3], v[114:115]
	v_pk_mul_f32 v[0:1], v[0:1], v[112:113]
	v_pk_mul_f32 v[28:29], v[28:29], v[100:101]
	v_pk_mul_f32 v[24:25], v[24:25], v[104:105]
	v_pk_mul_f32 v[20:21], v[20:21], v[108:109]
	v_pk_mul_f32 v[30:31], v[30:31], v[102:103]
	v_pk_mul_f32 v[26:27], v[26:27], v[106:107]
	v_pk_mul_f32 v[22:23], v[22:23], v[110:111]
	v_pk_mul_f32 v[18:19], v[18:19], v[114:115]
	v_pk_mul_f32 v[16:17], v[16:17], v[112:113]
	v_pk_mul_f32 v[60:61], v[60:61], v[100:101]
	v_pk_mul_f32 v[56:57], v[56:57], v[104:105]
	v_pk_mul_f32 v[52:53], v[52:53], v[108:109]
	v_pk_mul_f32 v[62:63], v[62:63], v[102:103]
	v_pk_mul_f32 v[58:59], v[58:59], v[106:107]
	v_pk_mul_f32 v[54:55], v[54:55], v[110:111]
	v_pk_mul_f32 v[50:51], v[50:51], v[114:115]
	v_pk_mul_f32 v[48:49], v[48:49], v[112:113]
	v_pk_mul_f32 v[76:77], v[76:77], v[100:101]
	v_pk_mul_f32 v[72:73], v[72:73], v[104:105]
	v_pk_mul_f32 v[68:69], v[68:69], v[108:109]
	v_pk_mul_f32 v[78:79], v[78:79], v[102:103]
	v_pk_mul_f32 v[74:75], v[74:75], v[106:107]
	v_pk_mul_f32 v[70:71], v[70:71], v[110:111]
	v_pk_mul_f32 v[66:67], v[66:67], v[114:115]
	v_pk_mul_f32 v[64:65], v[64:65], v[112:113]
; #define SBAR() __builtin_amdgcn_sched_barrier(0)
; #define PK4(P, BASE, OUT) do { u32x4 w = {cvtb(P[BASE + 0], P[BASE + 1]), cvtb(P[BASE + 2], P[BASE + 3]), \
;     cvtb(P[BASE + 4], P[BASE + 5]), cvtb(P[BASE + 6], P[BASE + 7])}; OUT = *reinterpret_cast<bf16x8*>(&w); } while (0)
; __device__ __forceinline__ void finishSM(f32x16& p0, f32x16& p1, float alpha, float& l_reg, bf16x8& pa0, bf16x8& pa1, bf16x8& pa2, bf16x8& pa3) {
; #pragma unroll
;   for (int r = 0; r < 16; ++r) p1[r] = __builtin_amdgcn_exp2f(p1[r]);
;   float ps = 0;
; #pragma unroll
;   for (int r = 0; r < 16; ++r) ps += p0[r];
; #pragma unroll
;   for (int r = 0; r < 16; ++r) ps += p1[r];
;   { auto rr = __builtin_amdgcn_permlane32_swap(__float_as_uint(ps), __float_as_uint(ps), false, false);
;     ps = __uint_as_float(rr[0]) + __uint_as_float(rr[1]); }
;   l_reg = l_reg * alpha + ps;
;     ...
;   PK4(p0, 0, pa0); PK4(p0, 8, pa1); PK4(p1, 0, pa2); PK4(p1, 8, pa3);
;     ...
; }
; template <int D0> __device__ __forceinline__ void pv_one(f32x16& od, int vb, bf16x8 pa0, bf16x8 pa1, bf16x8 pa2, bf16x8 pa3) {
;   const s16x4 l0 = tr_read<v_rd_off(D0, 0, 0)>(vb), h0 = tr_read<v_rd_off(D0, 0, 1)>(vb), l1 = tr_read<v_rd_off(D0, 1, 0)>(vb), h1 = tr_read<v_rd_off(D0, 1, 1)>(vb);
;   const s16x4 l2 = tr_read<v_rd_off(D0, 2, 0)>(vb), h2 = tr_read<v_rd_off(D0, 2, 1)>(vb), l3 = tr_read<v_rd_off(D0, 3, 0)>(vb), h3 = tr_read<v_rd_off(D0, 3, 1)>(vb);
;   asm volatile("s_waitcnt lgkmcnt(0)" ::: "memory"); SBAR();
;     ...
;   od = __builtin_amdgcn_mfma_f32_32x32x16_bf16(pa0, PK(l0, h0), od, 0, 0, 0);
;   od = __builtin_amdgcn_mfma_f32_32x32x16_bf16(pa1, PK(l1, h1), od, 0, 0, 0);
;   od = __builtin_amdgcn_mfma_f32_32x32x16_bf16(pa2, PK(l2, h2), od, 0, 0, 0);
;   od = __builtin_amdgcn_mfma_f32_32x32x16_bf16(pa3, PK(l3, h3), od, 0, 0, 0);
;     ...
; }
.LBB0_1279:
	v_exp_f32_e32 v80, v80
	v_exp_f32_e32 v81, v81
	v_exp_f32_e32 v82, v82
	v_exp_f32_e32 v83, v83
	v_exp_f32_e32 v84, v84
	v_exp_f32_e32 v99, v32
	v_add_f32_e32 v32, 0, v80
	v_exp_f32_e32 v85, v85
	v_add_f32_e32 v32, v81, v32
	v_exp_f32_e32 v86, v86
	v_add_f32_e32 v32, v82, v32
	v_exp_f32_e32 v87, v87
	v_add_f32_e32 v32, v83, v32
	v_exp_f32_e32 v88, v88
	v_add_f32_e32 v32, v84, v32
	v_exp_f32_e32 v89, v89
	v_add_f32_e32 v32, v85, v32
	v_exp_f32_e32 v90, v90
	v_add_f32_e32 v32, v86, v32
	v_exp_f32_e32 v91, v91
	v_add_f32_e32 v32, v87, v32
	v_exp_f32_e32 v92, v92
	v_add_f32_e32 v32, v88, v32
	v_exp_f32_e32 v93, v93
	v_add_f32_e32 v32, v89, v32
	v_exp_f32_e32 v94, v94
	v_add_f32_e32 v32, v90, v32
	v_exp_f32_e32 v95, v95
	v_add_f32_e32 v32, v91, v32
	v_add_f32_e32 v32, v92, v32
	v_exp_f32_e32 v100, v33
	v_add_f32_e32 v32, v93, v32
	v_exp_f32_e32 v101, v34
	v_add_f32_e32 v32, v94, v32
	v_exp_f32_e32 v102, v35
	v_add_f32_e32 v32, v95, v32
	v_exp_f32_e32 v103, v36
	v_add_f32_e32 v32, v99, v32
	v_exp_f32_e32 v104, v37
	v_add_f32_e32 v32, v100, v32
	v_exp_f32_e32 v105, v38
	v_add_f32_e32 v32, v101, v32
	v_exp_f32_e32 v106, v39
	v_add_f32_e32 v32, v102, v32
	v_exp_f32_e32 v107, v40
	v_add_f32_e32 v32, v103, v32
	v_exp_f32_e32 v108, v41
	v_add_f32_e32 v32, v104, v32
	v_exp_f32_e32 v109, v42
	v_add_f32_e32 v32, v105, v32
	v_exp_f32_e32 v110, v43
	v_add_f32_e32 v32, v106, v32
	v_exp_f32_e32 v111, v44
	v_add_f32_e32 v32, v107, v32
	v_exp_f32_e32 v112, v45
	v_add_f32_e32 v32, v108, v32
	v_exp_f32_e32 v46, v46
	v_add_f32_e32 v32, v109, v32
	v_exp_f32_e32 v47, v47
	v_add_f32_e32 v32, v110, v32
	v_add_f32_e32 v32, v111, v32
	v_add_f32_e32 v32, v112, v32
	v_add_f32_e32 v32, v46, v32
	v_add_f32_e32 v32, v47, v32
	v_mov_b32_e32 v33, v32
	s_nop 1
	v_permlane32_swap_b32_e32 v32, v33
	v_cvt_pk_bf16_f32 v34, v80, v81
	v_cvt_pk_bf16_f32 v35, v82, v83
	v_cvt_pk_bf16_f32 v36, v84, v85
	v_cvt_pk_bf16_f32 v37, v86, v87
	v_cvt_pk_bf16_f32 v38, v88, v89
	v_cvt_pk_bf16_f32 v39, v90, v91
	v_cvt_pk_bf16_f32 v40, v92, v93
	v_cvt_pk_bf16_f32 v41, v94, v95
	v_cvt_pk_bf16_f32 v42, v99, v100
	v_cvt_pk_bf16_f32 v43, v101, v102
	v_cvt_pk_bf16_f32 v44, v103, v104
	v_cvt_pk_bf16_f32 v45, v105, v106
	v_cvt_pk_bf16_f32 v80, v107, v108
	v_cvt_pk_bf16_f32 v81, v109, v110
	v_cvt_pk_bf16_f32 v82, v111, v112
	v_cvt_pk_bf16_f32 v83, v46, v47
	ds_read_b64_tr_b16 v[84:85], v167 offset:0
	ds_read_b64_tr_b16 v[86:87], v167 offset:0x800
	ds_read_b64_tr_b16 v[88:89], v167 offset:0x1000
	ds_read_b64_tr_b16 v[90:91], v167 offset:0x1800
	ds_read_b64_tr_b16 v[92:93], v167 offset:0x2000
	ds_read_b64_tr_b16 v[94:95], v167 offset:0x2800
	ds_read_b64_tr_b16 v[100:101], v167 offset:0x3000
	ds_read_b64_tr_b16 v[102:103], v167 offset:0x3800
	s_waitcnt lgkmcnt(6)
	s_nop 0
	v_mfma_f32_32x32x16_bf16 v[0:15], v[34:37], v[84:87], v[0:15]
	ds_read_b64_tr_b16 v[84:85], v167 offset:0x200
	ds_read_b64_tr_b16 v[86:87], v167 offset:0xa00
	s_waitcnt lgkmcnt(6)
	v_mfma_f32_32x32x16_bf16 v[0:15], v[38:41], v[88:91], v[0:15]
	ds_read_b64_tr_b16 v[88:89], v167 offset:0x1200
	ds_read_b64_tr_b16 v[90:91], v167 offset:0x1a00
	s_waitcnt lgkmcnt(6)
	v_mfma_f32_32x32x16_bf16 v[0:15], v[42:45], v[92:95], v[0:15]
	ds_read_b64_tr_b16 v[92:93], v167 offset:0x2200
	ds_read_b64_tr_b16 v[94:95], v167 offset:0x2a00
	s_waitcnt lgkmcnt(6)
	v_mfma_f32_32x32x16_bf16 v[0:15], v[80:83], v[100:103], v[0:15]
	ds_read_b64_tr_b16 v[100:101], v167 offset:0x3200
	ds_read_b64_tr_b16 v[102:103], v167 offset:0x3a00
	s_waitcnt lgkmcnt(6)
	v_mfma_f32_32x32x16_bf16 v[16:31], v[34:37], v[84:87], v[16:31]
	ds_read_b64_tr_b16 v[84:85], v167 offset:0x400
	ds_read_b64_tr_b16 v[86:87], v167 offset:0xc00
	s_waitcnt lgkmcnt(6)
	v_mfma_f32_32x32x16_bf16 v[16:31], v[38:41], v[88:91], v[16:31]
	ds_read_b64_tr_b16 v[88:89], v167 offset:0x1400
	ds_read_b64_tr_b16 v[90:91], v167 offset:0x1c00
	s_waitcnt lgkmcnt(6)
	v_mfma_f32_32x32x16_bf16 v[16:31], v[42:45], v[92:95], v[16:31]
	ds_read_b64_tr_b16 v[92:93], v167 offset:0x2400
	ds_read_b64_tr_b16 v[94:95], v167 offset:0x2c00
	s_waitcnt lgkmcnt(6)
	v_mfma_f32_32x32x16_bf16 v[16:31], v[80:83], v[100:103], v[16:31]
	ds_read_b64_tr_b16 v[100:101], v167 offset:0x3400
	ds_read_b64_tr_b16 v[102:103], v167 offset:0x3c00
	s_waitcnt lgkmcnt(6)
	v_mfma_f32_32x32x16_bf16 v[48:63], v[34:37], v[84:87], v[48:63]
	ds_read_b64_tr_b16 v[84:85], v167 offset:0x600
	ds_read_b64_tr_b16 v[86:87], v167 offset:0xe00
	s_waitcnt lgkmcnt(6)
	v_mfma_f32_32x32x16_bf16 v[48:63], v[38:41], v[88:91], v[48:63]
	ds_read_b64_tr_b16 v[88:89], v167 offset:0x1600
	ds_read_b64_tr_b16 v[90:91], v167 offset:0x1e00
	s_waitcnt lgkmcnt(6)
	v_mfma_f32_32x32x16_bf16 v[48:63], v[42:45], v[92:95], v[48:63]
	ds_read_b64_tr_b16 v[92:93], v167 offset:0x2600
	ds_read_b64_tr_b16 v[94:95], v167 offset:0x2e00
	s_waitcnt lgkmcnt(6)
	v_mfma_f32_32x32x16_bf16 v[48:63], v[80:83], v[100:103], v[48:63]
	ds_read_b64_tr_b16 v[100:101], v167 offset:0x3600
	ds_read_b64_tr_b16 v[102:103], v167 offset:0x3e00
	s_waitcnt lgkmcnt(0)
	v_mfma_f32_32x32x16_bf16 v[64:79], v[34:37], v[84:87], v[64:79]
	v_mfma_f32_32x32x16_bf16 v[64:79], v[38:41], v[88:91], v[64:79]
	v_mfma_f32_32x32x16_bf16 v[64:79], v[42:45], v[92:95], v[64:79]
	v_mfma_f32_32x32x16_bf16 v[64:79], v[80:83], v[100:103], v[64:79]
	s_and_saveexec_b64 s[8:9], s[6:7]
	s_cbranch_execz .LBB0_1281
	v_add_f32_e32 v34, v161, v162
	v_add_f32_e32 v34, 0, v34
	v_add_f32_e32 v35, v169, v170
	v_fmac_f32_e32 v35, v34, v163
	v_add_f32_e32 v34, v96, v97
	v_fmac_f32_e32 v34, v35, v172
	v_add_f32_e32 v32, v32, v33
	v_fmac_f32_e32 v32, v34, v98
	ds_write_b32 v165, v32

; #define SBAR() __builtin_amdgcn_sched_barrier(0)
; #define SWRITE(b, i) do { STG_T() const int _sv = VSTV(), _sk = LDSK(); *(u32x4*)(V_lds + (b) * SHM_V + _sv) = sr_[i].vs0; *(u32x4*)(V_lds + (b) * SHM_V + _sv + 8192) = sr_[i].vs1; \
;     _Pragma("unroll") for (int _p = 0; _p < NP; ++_p) *(u32x4*)(K_lds + (b) * KT + _sk + _p * 128) = sr_[i].ks[_p]; } while (0)
; #define SWAIT() do { if constexpr (SD == 2) { if constexpr (NP == 1) asm volatile("s_waitcnt vmcnt(3)" ::: "memory"); else asm volatile("s_waitcnt vmcnt(5)" ::: "memory"); } else asm volatile("s_waitcnt vmcnt(0)" ::: "memory"); } while (0)
; #define ROT() do { const int _r = rp; rp = rc; rc = rn; rn = _r; } while (0)
; template <int D0> __device__ __forceinline__ void pv_one_mi(f32x16& od, int vb, bf16x8 pa0, bf16x8 pa1, bf16x8 pa2, bf16x8 pa3, f32x16& q0) {
;   const s16x4 l0 = tr_read<v_rd_off(D0, 0, 0)>(vb), h0 = tr_read<v_rd_off(D0, 0, 1)>(vb), l1 = tr_read<v_rd_off(D0, 1, 0)>(vb), h1 = tr_read<v_rd_off(D0, 1, 1)>(vb);
;   const s16x4 l2 = tr_read<v_rd_off(D0, 2, 0)>(vb), h2 = tr_read<v_rd_off(D0, 2, 1)>(vb), l3 = tr_read<v_rd_off(D0, 3, 0)>(vb), h3 = tr_read<v_rd_off(D0, 3, 1)>(vb);
;   asm volatile("s_waitcnt lgkmcnt(0)" ::: "memory"); SBAR();
;     ...
;   od = __builtin_amdgcn_mfma_f32_32x32x16_bf16(pa0, PK(l0, h0), od, 0, 0, 0);
;   od = __builtin_amdgcn_mfma_f32_32x32x16_bf16(pa1, PK(l1, h1), od, 0, 0, 0);
;   od = __builtin_amdgcn_mfma_f32_32x32x16_bf16(pa2, PK(l2, h2), od, 0, 0, 0);
;   od = __builtin_amdgcn_mfma_f32_32x32x16_bf16(pa3, PK(l3, h3), od, 0, 0, 0);
;     ...
; #pragma unroll
;   for (int r = 4 * D0; r < 4 * D0 + 4; ++r) q0[r] = __builtin_amdgcn_exp2f(q0[r]);
; }
; __device__ __forceinline__ void pv_mi(f32x16* o, int vb, bf16x8 pa0, bf16x8 pa1, bf16x8 pa2, bf16x8 pa3, f32x16& q0) {
;   pv_one_mi<0>(o[0], vb, pa0, pa1, pa2, pa3, q0); pv_one_mi<1>(o[1], vb, pa0, pa1, pa2, pa3, q0);
;   pv_one_mi<2>(o[2], vb, pa0, pa1, pa2, pa3, q0); pv_one_mi<3>(o[3], vb, pa0, pa1, pa2, pa3, q0);
; }
; template <int NQK, int SD, bool MI> ...
;     ...
;   for (int j = 1; j + 1 < NT; j += 2) {
;     SBAR(); QKT(pB0, pB1, K_lds + rc * KT);
;     finishSM(pA0, pA1, alA, l_reg, pa0, pa1, pa2, pa3); DECIDE(pB0, pB1, mnB, alB); SBAR();
;     SLOAD(SO, (j + SD) * 64); SBAR();
;     PVSM(vb0 + rp * SHM_V, pB0, pB1, mnB);
;     SWAIT(); SWRITE(rn, SE);
;     RESC(alB); __syncthreads(); ROT();
.LBB0_1288:
	v_cvt_pk_bf16_f32 v232, v175, v176
	v_cvt_pk_bf16_f32 v233, v177, v178
	v_cvt_pk_bf16_f32 v234, v179, v181
	v_cvt_pk_bf16_f32 v235, v183, v185
	v_cvt_pk_bf16_f32 v236, v180, v182
	v_cvt_pk_bf16_f32 v237, v184, v227
	v_cvt_pk_bf16_f32 v238, v228, v229
	v_cvt_pk_bf16_f32 v239, v230, v174
	v_cvt_pk_bf16_f32 v228, v96, v97
	v_cvt_pk_bf16_f32 v229, v215, v99
	v_cvt_pk_bf16_f32 v230, v100, v101
	v_cvt_pk_bf16_f32 v231, v102, v103
	v_cvt_pk_bf16_f32 v96, v98, v104
	v_cvt_pk_bf16_f32 v97, v105, v106
	v_cvt_pk_bf16_f32 v98, v107, v108
	v_cvt_pk_bf16_f32 v99, v109, v110
	s_add_i32 s8, s13, 0xfffe8000
	s_add_i32 s9, s12, 0xfffe0000
	s_mov_b32 s38, s30
	s_mov_b32 s39, s31
	s_add_i32 s10, s13, 0xffff0000
	buffer_load_dwordx4 v[174:177], v216, s[28:31], s8 offen
	buffer_load_dwordx4 v[178:181], v216, s[28:31], s10 offen
	buffer_load_dwordx4 v[182:185], v217, s[36:39], s9 offen
	s_lshl_b32 s10, s58, 14
	v_add_u32_e32 v215, s10, v214
	ds_read_b64_tr_b16 v[100:101], v215 offset:0
	ds_read_b64_tr_b16 v[102:103], v215 offset:0x800
	ds_read_b64_tr_b16 v[104:105], v215 offset:0x1000
	ds_read_b64_tr_b16 v[106:107], v215 offset:0x1800
	ds_read_b64_tr_b16 v[108:109], v215 offset:0x2000
	ds_read_b64_tr_b16 v[110:111], v215 offset:0x2800
	ds_read_b64_tr_b16 v[240:241], v215 offset:0x3000
	ds_read_b64_tr_b16 v[242:243], v215 offset:0x3800
	s_waitcnt lgkmcnt(6)
	s_nop 0
	v_mfma_f32_32x32x16_bf16 v[0:15], v[232:235], v[100:103], v[0:15]
	ds_read_b64_tr_b16 v[100:101], v215 offset:0x200
	ds_read_b64_tr_b16 v[102:103], v215 offset:0xa00
	s_waitcnt lgkmcnt(6)
	v_mfma_f32_32x32x16_bf16 v[0:15], v[236:239], v[104:107], v[0:15]
	ds_read_b64_tr_b16 v[104:105], v215 offset:0x1200
	ds_read_b64_tr_b16 v[106:107], v215 offset:0x1a00
	s_waitcnt lgkmcnt(6)
	v_mfma_f32_32x32x16_bf16 v[0:15], v[228:231], v[108:111], v[0:15]
	ds_read_b64_tr_b16 v[108:109], v215 offset:0x2200
	ds_read_b64_tr_b16 v[110:111], v215 offset:0x2a00
	s_waitcnt lgkmcnt(6)
	v_mfma_f32_32x32x16_bf16 v[0:15], v[96:99], v[240:243], v[0:15]
	ds_read_b64_tr_b16 v[240:241], v215 offset:0x3200
	ds_read_b64_tr_b16 v[242:243], v215 offset:0x3a00
	s_waitcnt lgkmcnt(6)
	v_mfma_f32_32x32x16_bf16 v[48:63], v[232:235], v[100:103], v[48:63]
	ds_read_b64_tr_b16 v[100:101], v215 offset:0x400
	ds_read_b64_tr_b16 v[102:103], v215 offset:0xc00
	s_waitcnt lgkmcnt(6)
	v_mfma_f32_32x32x16_bf16 v[48:63], v[236:239], v[104:107], v[48:63]
	ds_read_b64_tr_b16 v[104:105], v215 offset:0x1400
	ds_read_b64_tr_b16 v[106:107], v215 offset:0x1c00
	s_waitcnt lgkmcnt(6)
	v_mfma_f32_32x32x16_bf16 v[48:63], v[228:231], v[108:111], v[48:63]
	ds_read_b64_tr_b16 v[108:109], v215 offset:0x2400
	ds_read_b64_tr_b16 v[110:111], v215 offset:0x2c00
	s_waitcnt lgkmcnt(6)
	v_mfma_f32_32x32x16_bf16 v[48:63], v[96:99], v[240:243], v[48:63]
	ds_read_b64_tr_b16 v[240:241], v215 offset:0x3400
	ds_read_b64_tr_b16 v[242:243], v215 offset:0x3c00
	s_waitcnt lgkmcnt(6)
	v_mfma_f32_32x32x16_bf16 v[32:47], v[232:235], v[100:103], v[32:47]
	ds_read_b64_tr_b16 v[100:101], v215 offset:0x600
	ds_read_b64_tr_b16 v[102:103], v215 offset:0xe00
	s_waitcnt lgkmcnt(6)
	v_mfma_f32_32x32x16_bf16 v[32:47], v[236:239], v[104:107], v[32:47]
	ds_read_b64_tr_b16 v[104:105], v215 offset:0x1600
	ds_read_b64_tr_b16 v[106:107], v215 offset:0x1e00
	s_waitcnt lgkmcnt(6)
	v_mfma_f32_32x32x16_bf16 v[32:47], v[228:231], v[108:111], v[32:47]
	ds_read_b64_tr_b16 v[108:109], v215 offset:0x2600
	ds_read_b64_tr_b16 v[110:111], v215 offset:0x2e00
	s_waitcnt lgkmcnt(6)
	v_mfma_f32_32x32x16_bf16 v[32:47], v[96:99], v[240:243], v[32:47]
	ds_read_b64_tr_b16 v[240:241], v215 offset:0x3600
	ds_read_b64_tr_b16 v[242:243], v215 offset:0x3e00
	s_waitcnt lgkmcnt(0)
	v_mfma_f32_32x32x16_bf16 v[16:31], v[232:235], v[100:103], v[16:31]
	s_waitcnt vmcnt(3)
	s_lshl_b32 s16, s59, 14
	v_add_u32_e32 v100, s16, v218
	s_mul_i32 s11, s59, 0x2400
	s_waitcnt vmcnt(5)
	ds_write_b128 v100, v[162:165]
	s_waitcnt vmcnt(4)
	ds_write_b128 v100, v[166:169] offset:8192
	v_add_u32_e32 v100, s11, v219
	v_cmp_gt_f32_e32 vcc, 1.0, v226
	v_mfma_f32_32x32x16_bf16 v[16:31], v[236:239], v[104:107], v[16:31]
	s_waitcnt vmcnt(3)
	ds_write_b128 v100, v[170:173] offset:49152
	v_mfma_f32_32x32x16_bf16 v[16:31], v[228:231], v[108:111], v[16:31]
	v_mfma_f32_32x32x16_bf16 v[16:31], v[96:99], v[240:243], v[16:31]
	s_cbranch_vccz .LBB0_1292
	s_and_saveexec_b64 s[8:9], s[6:7]
	ds_write_b32 v199, v226 offset:128
	s_or_b64 exec, exec, s[8:9]
	s_waitcnt lgkmcnt(0)
	v_add_u32_e32 v108, v191, v198
	ds_read_b128 v[96:99], v108 offset:224
	ds_read_b128 v[100:103], v108 offset:192
	ds_read_b128 v[104:107], v108 offset:160
	ds_read_b128 v[108:111], v108 offset:128
	s_waitcnt lgkmcnt(3)
	v_pk_mul_f32 v[12:13], v[12:13], v[96:97]
	s_waitcnt lgkmcnt(2)
	v_pk_mul_f32 v[8:9], v[8:9], v[100:101]
	s_waitcnt lgkmcnt(1)
	v_pk_mul_f32 v[4:5], v[4:5], v[104:105]
	v_pk_mul_f32 v[14:15], v[14:15], v[98:99]
	v_pk_mul_f32 v[10:11], v[10:11], v[102:103]
	v_pk_mul_f32 v[6:7], v[6:7], v[106:107]
	s_waitcnt lgkmcnt(0)
	v_pk_mul_f32 v[2:3], v[2:3], v[110:111]
	v_pk_mul_f32 v[0:1], v[0:1], v[108:109]
	v_pk_mul_f32 v[60:61], v[60:61], v[96:97]
	v_pk_mul_f32 v[56:57], v[56:57], v[100:101]
	v_pk_mul_f32 v[52:53], v[52:53], v[104:105]
	v_pk_mul_f32 v[62:63], v[62:63], v[98:99]
	v_pk_mul_f32 v[58:59], v[58:59], v[102:103]
	v_pk_mul_f32 v[54:55], v[54:55], v[106:107]
	v_pk_mul_f32 v[50:51], v[50:51], v[110:111]
	v_pk_mul_f32 v[48:49], v[48:49], v[108:109]
	v_pk_mul_f32 v[44:45], v[44:45], v[96:97]
	v_pk_mul_f32 v[40:41], v[40:41], v[100:101]
	v_pk_mul_f32 v[36:37], v[36:37], v[104:105]
	v_pk_mul_f32 v[46:47], v[46:47], v[98:99]
	v_pk_mul_f32 v[42:43], v[42:43], v[102:103]
	v_pk_mul_f32 v[38:39], v[38:39], v[106:107]
	v_pk_mul_f32 v[34:35], v[34:35], v[110:111]
	v_pk_mul_f32 v[32:33], v[32:33], v[108:109]
	v_pk_mul_f32 v[28:29], v[28:29], v[96:97]
	v_pk_mul_f32 v[24:25], v[24:25], v[100:101]
	v_pk_mul_f32 v[20:21], v[20:21], v[104:105]
	v_pk_mul_f32 v[30:31], v[30:31], v[98:99]
	v_pk_mul_f32 v[26:27], v[26:27], v[102:103]
	v_pk_mul_f32 v[22:23], v[22:23], v[106:107]
	v_pk_mul_f32 v[18:19], v[18:19], v[110:111]
	v_pk_mul_f32 v[16:17], v[16:17], v[108:109]

; #define SBAR() __builtin_amdgcn_sched_barrier(0)
; #define SWRITE(b, i) do { STG_T() const int _sv = VSTV(), _sk = LDSK(); *(u32x4*)(V_lds + (b) * SHM_V + _sv) = sr_[i].vs0; *(u32x4*)(V_lds + (b) * SHM_V + _sv + 8192) = sr_[i].vs1; \
;     _Pragma("unroll") for (int _p = 0; _p < NP; ++_p) *(u32x4*)(K_lds + (b) * KT + _sk + _p * 128) = sr_[i].ks[_p]; } while (0)
; #define SWAIT() do { if constexpr (SD == 2) { if constexpr (NP == 1) asm volatile("s_waitcnt vmcnt(3)" ::: "memory"); else asm volatile("s_waitcnt vmcnt(5)" ::: "memory"); } else asm volatile("s_waitcnt vmcnt(0)" ::: "memory"); } while (0)
; #define ROT() do { const int _r = rp; rp = rc; rc = rn; rn = _r; } while (0)
; template <int D0> __device__ __forceinline__ void pv_one_mi(f32x16& od, int vb, bf16x8 pa0, bf16x8 pa1, bf16x8 pa2, bf16x8 pa3, f32x16& q0) {
;   const s16x4 l0 = tr_read<v_rd_off(D0, 0, 0)>(vb), h0 = tr_read<v_rd_off(D0, 0, 1)>(vb), l1 = tr_read<v_rd_off(D0, 1, 0)>(vb), h1 = tr_read<v_rd_off(D0, 1, 1)>(vb);
;   const s16x4 l2 = tr_read<v_rd_off(D0, 2, 0)>(vb), h2 = tr_read<v_rd_off(D0, 2, 1)>(vb), l3 = tr_read<v_rd_off(D0, 3, 0)>(vb), h3 = tr_read<v_rd_off(D0, 3, 1)>(vb);
;   asm volatile("s_waitcnt lgkmcnt(0)" ::: "memory"); SBAR();
;     ...
;   od = __builtin_amdgcn_mfma_f32_32x32x16_bf16(pa0, PK(l0, h0), od, 0, 0, 0);
;   od = __builtin_amdgcn_mfma_f32_32x32x16_bf16(pa1, PK(l1, h1), od, 0, 0, 0);
;   od = __builtin_amdgcn_mfma_f32_32x32x16_bf16(pa2, PK(l2, h2), od, 0, 0, 0);
;   od = __builtin_amdgcn_mfma_f32_32x32x16_bf16(pa3, PK(l3, h3), od, 0, 0, 0);
;     ...
; #pragma unroll
;   for (int r = 4 * D0; r < 4 * D0 + 4; ++r) q0[r] = __builtin_amdgcn_exp2f(q0[r]);
; }
; __device__ __forceinline__ void pv_mi(f32x16* o, int vb, bf16x8 pa0, bf16x8 pa1, bf16x8 pa2, bf16x8 pa3, f32x16& q0) {
;   pv_one_mi<0>(o[0], vb, pa0, pa1, pa2, pa3, q0); pv_one_mi<1>(o[1], vb, pa0, pa1, pa2, pa3, q0);
;   pv_one_mi<2>(o[2], vb, pa0, pa1, pa2, pa3, q0); pv_one_mi<3>(o[3], vb, pa0, pa1, pa2, pa3, q0);
; }
; template <int NQK, int SD, bool MI> ...
;     ...
;     SBAR(); QKT(pA0, pA1, K_lds + rc * KT);
;     finishSM(pB0, pB1, alB, l_reg, pa0, pa1, pa2, pa3); DECIDE(pA0, pA1, mnA, alA); SBAR();
;     if (SD == 1 || j + 3 < NT) SLOAD(SE, (j + 1 + SD) * 64); SBAR();
;     PVSM(vb0 + rp * SHM_V, pA0, pA1, mnA);
;     SWAIT(); SWRITE(rn, SO);
;     RESC(alA); __syncthreads(); ROT();
.LBB0_1295:
	v_cvt_pk_bf16_f32 v250, v227, v229
	v_cvt_pk_bf16_f32 v251, v230, v233
	v_cvt_pk_bf16_f32 v252, v234, v237
	v_cvt_pk_bf16_f32 v253, v238, v241
	v_cvt_pk_bf16_f32 v228, v228, v231
	v_cvt_pk_bf16_f32 v229, v232, v235
	v_cvt_pk_bf16_f32 v230, v236, v239
	v_cvt_pk_bf16_f32 v231, v240, v242
	v_cvt_pk_bf16_f32 v232, v243, v244
	v_cvt_pk_bf16_f32 v233, v245, v115
	v_cvt_pk_bf16_f32 v234, v246, v247
	v_cvt_pk_bf16_f32 v235, v248, v119
	v_cvt_pk_bf16_f32 v116, v116, v117
	v_cvt_pk_bf16_f32 v117, v118, v120
	v_cvt_pk_bf16_f32 v118, v121, v122
	v_cvt_pk_bf16_f32 v119, v123, v124
	v_lshl_add_u32 v115, s15, 14, v214
	ds_read_b64_tr_b16 v[120:121], v115 offset:0
	ds_read_b64_tr_b16 v[122:123], v115 offset:0x800
	ds_read_b64_tr_b16 v[124:125], v115 offset:0x1000
	ds_read_b64_tr_b16 v[126:127], v115 offset:0x1800
	ds_read_b64_tr_b16 v[236:237], v115 offset:0x2000
	ds_read_b64_tr_b16 v[238:239], v115 offset:0x2800
	ds_read_b64_tr_b16 v[240:241], v115 offset:0x3000
	ds_read_b64_tr_b16 v[242:243], v115 offset:0x3800
	s_waitcnt lgkmcnt(6)
	s_nop 0
	v_mfma_f32_32x32x16_bf16 v[0:15], v[250:253], v[120:123], v[0:15]
	ds_read_b64_tr_b16 v[120:121], v115 offset:0x200
	ds_read_b64_tr_b16 v[122:123], v115 offset:0xa00
	s_waitcnt lgkmcnt(6)
	v_mfma_f32_32x32x16_bf16 v[0:15], v[228:231], v[124:127], v[0:15]
	ds_read_b64_tr_b16 v[124:125], v115 offset:0x1200
	ds_read_b64_tr_b16 v[126:127], v115 offset:0x1a00
	s_waitcnt lgkmcnt(6)
	v_mfma_f32_32x32x16_bf16 v[0:15], v[232:235], v[236:239], v[0:15]
	ds_read_b64_tr_b16 v[236:237], v115 offset:0x2200
	ds_read_b64_tr_b16 v[238:239], v115 offset:0x2a00
	s_waitcnt lgkmcnt(6)
	v_mfma_f32_32x32x16_bf16 v[0:15], v[116:119], v[240:243], v[0:15]
	ds_read_b64_tr_b16 v[240:241], v115 offset:0x3200
	ds_read_b64_tr_b16 v[242:243], v115 offset:0x3a00
	s_waitcnt lgkmcnt(6)
	v_mfma_f32_32x32x16_bf16 v[48:63], v[250:253], v[120:123], v[48:63]
	ds_read_b64_tr_b16 v[120:121], v115 offset:0x400
	ds_read_b64_tr_b16 v[122:123], v115 offset:0xc00
	s_waitcnt lgkmcnt(6)
	v_mfma_f32_32x32x16_bf16 v[48:63], v[228:231], v[124:127], v[48:63]
	ds_read_b64_tr_b16 v[124:125], v115 offset:0x1400
	ds_read_b64_tr_b16 v[126:127], v115 offset:0x1c00
	s_waitcnt lgkmcnt(6)
	v_mfma_f32_32x32x16_bf16 v[48:63], v[232:235], v[236:239], v[48:63]
	ds_read_b64_tr_b16 v[236:237], v115 offset:0x2400
	ds_read_b64_tr_b16 v[238:239], v115 offset:0x2c00
	s_waitcnt lgkmcnt(6)
	v_mfma_f32_32x32x16_bf16 v[48:63], v[116:119], v[240:243], v[48:63]
	ds_read_b64_tr_b16 v[240:241], v115 offset:0x3400
	ds_read_b64_tr_b16 v[242:243], v115 offset:0x3c00
	s_waitcnt lgkmcnt(6)
	v_mfma_f32_32x32x16_bf16 v[32:47], v[250:253], v[120:123], v[32:47]
	ds_read_b64_tr_b16 v[120:121], v115 offset:0x600
	ds_read_b64_tr_b16 v[122:123], v115 offset:0xe00
	s_waitcnt lgkmcnt(6)
	v_mfma_f32_32x32x16_bf16 v[32:47], v[228:231], v[124:127], v[32:47]
	ds_read_b64_tr_b16 v[124:125], v115 offset:0x1600
	ds_read_b64_tr_b16 v[126:127], v115 offset:0x1e00
	s_waitcnt lgkmcnt(6)
	v_mfma_f32_32x32x16_bf16 v[32:47], v[232:235], v[236:239], v[32:47]
	ds_read_b64_tr_b16 v[236:237], v115 offset:0x2600
	ds_read_b64_tr_b16 v[238:239], v115 offset:0x2e00
	s_waitcnt lgkmcnt(6)
	v_mfma_f32_32x32x16_bf16 v[32:47], v[116:119], v[240:243], v[32:47]
	ds_read_b64_tr_b16 v[240:241], v115 offset:0x3600
	ds_read_b64_tr_b16 v[242:243], v115 offset:0x3e00
	s_waitcnt lgkmcnt(0)
	v_mfma_f32_32x32x16_bf16 v[16:31], v[250:253], v[120:123], v[16:31]
	s_waitcnt vmcnt(3)
	v_add_u32_e32 v115, s10, v218
	s_mul_i32 s17, s58, 0x2400
	s_waitcnt vmcnt(2)
	ds_write_b128 v115, v[174:177]
	s_waitcnt vmcnt(1)
	ds_write_b128 v115, v[178:181] offset:8192
	v_add_u32_e32 v115, s17, v219
	v_cmp_gt_f32_e32 vcc, 1.0, v112
	s_waitcnt vmcnt(0)
	ds_write_b128 v115, v[182:185] offset:49152
	v_mfma_f32_32x32x16_bf16 v[16:31], v[228:231], v[124:127], v[16:31]
	v_mfma_f32_32x32x16_bf16 v[16:31], v[232:235], v[236:239], v[16:31]
	v_mfma_f32_32x32x16_bf16 v[16:31], v[116:119], v[240:243], v[16:31]
	s_cbranch_vccz .LBB0_1299
	s_and_saveexec_b64 s[10:11], s[6:7]
	ds_write_b32 v199, v112 offset:128
	s_or_b64 exec, exec, s[10:11]
	s_waitcnt lgkmcnt(0)
	v_add_u32_e32 v115, v191, v198
	ds_read_b128 v[116:119], v115 offset:224
	ds_read_b128 v[120:123], v115 offset:192
	ds_read_b128 v[124:127], v115 offset:160
	ds_read_b128 v[174:177], v115 offset:128
	s_waitcnt lgkmcnt(3)
	v_pk_mul_f32 v[12:13], v[12:13], v[116:117]
	s_waitcnt lgkmcnt(2)
	v_pk_mul_f32 v[8:9], v[8:9], v[120:121]
	s_waitcnt lgkmcnt(1)
	v_pk_mul_f32 v[4:5], v[4:5], v[124:125]
	v_pk_mul_f32 v[14:15], v[14:15], v[118:119]
	v_pk_mul_f32 v[10:11], v[10:11], v[122:123]
	v_pk_mul_f32 v[6:7], v[6:7], v[126:127]
	s_waitcnt lgkmcnt(0)
	v_pk_mul_f32 v[2:3], v[2:3], v[176:177]
	v_pk_mul_f32 v[0:1], v[0:1], v[174:175]
	v_pk_mul_f32 v[60:61], v[60:61], v[116:117]
	v_pk_mul_f32 v[56:57], v[56:57], v[120:121]
	v_pk_mul_f32 v[52:53], v[52:53], v[124:125]
	v_pk_mul_f32 v[62:63], v[62:63], v[118:119]
	v_pk_mul_f32 v[58:59], v[58:59], v[122:123]
	v_pk_mul_f32 v[54:55], v[54:55], v[126:127]
	v_pk_mul_f32 v[50:51], v[50:51], v[176:177]
	v_pk_mul_f32 v[48:49], v[48:49], v[174:175]
	v_pk_mul_f32 v[44:45], v[44:45], v[116:117]
	v_pk_mul_f32 v[40:41], v[40:41], v[120:121]
	v_pk_mul_f32 v[36:37], v[36:37], v[124:125]
	v_pk_mul_f32 v[46:47], v[46:47], v[118:119]
	v_pk_mul_f32 v[42:43], v[42:43], v[122:123]
	v_pk_mul_f32 v[38:39], v[38:39], v[126:127]
	v_pk_mul_f32 v[34:35], v[34:35], v[176:177]
	v_pk_mul_f32 v[32:33], v[32:33], v[174:175]
	v_pk_mul_f32 v[28:29], v[28:29], v[116:117]
	v_pk_mul_f32 v[24:25], v[24:25], v[120:121]
	v_pk_mul_f32 v[20:21], v[20:21], v[124:125]
	v_pk_mul_f32 v[30:31], v[30:31], v[118:119]
	v_pk_mul_f32 v[26:27], v[26:27], v[122:123]
	v_pk_mul_f32 v[22:23], v[22:23], v[126:127]
	v_pk_mul_f32 v[18:19], v[18:19], v[176:177]
	v_pk_mul_f32 v[16:17], v[16:17], v[174:175]

; #define SBAR() __builtin_amdgcn_sched_barrier(0)
; #define RESC(a) do { if (__any((a) < 1.f)) { if (hi == 0) al_l[r32] = (a); asm volatile("s_waitcnt lgkmcnt(0)" ::: "memory"); \
;     _Pragma("unroll") for (int d = 0; d < 4; ++d) _Pragma("unroll") for (int r = 0; r < 16; ++r) o[d][r] *= al_l[crow(r, hi)]; } } while (0)
; #define QKT(P0, P1, KS) do { if constexpr (MI) qkt_mi<NQK>(P0, P1, KS, qr, r32, hi, minit); else qkt<NQK>(P0, P1, KS, qr, r32, hi); } while (0)
; #define DECIDE(P0, P1, MN, AL) do { if constexpr (MI) decide_mi(P0, P1, minit, Mref, AL, thr2, false); else decideSM(P0, P1, m_reg, MN, AL, C, thr); } while (0)
; #define PVSM(VB, P0, P1, MN) do { if constexpr (MI) pv_mi(o, VB, pa0, pa1, pa2, pa3, P0); else pv_sm(o, VB, pa0, pa1, pa2, pa3, P0, P1, C, MN); } while (0)
; template <int D0> __device__ __forceinline__ void pv_one_mi(f32x16& od, int vb, bf16x8 pa0, bf16x8 pa1, bf16x8 pa2, bf16x8 pa3, f32x16& q0) {
;   const s16x4 l0 = tr_read<v_rd_off(D0, 0, 0)>(vb), h0 = tr_read<v_rd_off(D0, 0, 1)>(vb), l1 = tr_read<v_rd_off(D0, 1, 0)>(vb), h1 = tr_read<v_rd_off(D0, 1, 1)>(vb);
;   const s16x4 l2 = tr_read<v_rd_off(D0, 2, 0)>(vb), h2 = tr_read<v_rd_off(D0, 2, 1)>(vb), l3 = tr_read<v_rd_off(D0, 3, 0)>(vb), h3 = tr_read<v_rd_off(D0, 3, 1)>(vb);
;   asm volatile("s_waitcnt lgkmcnt(0)" ::: "memory"); SBAR();
;     ...
;   od = __builtin_amdgcn_mfma_f32_32x32x16_bf16(pa0, PK(l0, h0), od, 0, 0, 0);
;   od = __builtin_amdgcn_mfma_f32_32x32x16_bf16(pa1, PK(l1, h1), od, 0, 0, 0);
;   od = __builtin_amdgcn_mfma_f32_32x32x16_bf16(pa2, PK(l2, h2), od, 0, 0, 0);
;   od = __builtin_amdgcn_mfma_f32_32x32x16_bf16(pa3, PK(l3, h3), od, 0, 0, 0);
;     ...
; #pragma unroll
;   for (int r = 4 * D0; r < 4 * D0 + 4; ++r) q0[r] = __builtin_amdgcn_exp2f(q0[r]);
; }
; __device__ __forceinline__ void pv_mi(f32x16* o, int vb, bf16x8 pa0, bf16x8 pa1, bf16x8 pa2, bf16x8 pa3, f32x16& q0) {
;   pv_one_mi<0>(o[0], vb, pa0, pa1, pa2, pa3, q0); pv_one_mi<1>(o[1], vb, pa0, pa1, pa2, pa3, q0);
;   pv_one_mi<2>(o[2], vb, pa0, pa1, pa2, pa3, q0); pv_one_mi<3>(o[3], vb, pa0, pa1, pa2, pa3, q0);
; }
; template <int NQK, int SD, bool MI> ...
;     ...
;   SBAR(); QKT(pB0, pB1, K_lds + rc * KT);
;   finishSM(pA0, pA1, alA, l_reg, pa0, pa1, pa2, pa3); DECIDE(pB0, pB1, mnB, alB); SBAR();
;   PVSM(vb0 + rp * SHM_V, pB0, pB1, mnB);
;   RESC(alB);
.LBB0_1304:
	s_movk_i32 s58, 0x6000
	v_readlane_b32 s59, v255, 19
	v_cvt_pk_bf16_f32 v118, v175, v176
	v_cvt_pk_bf16_f32 v119, v177, v178
	v_cvt_pk_bf16_f32 v120, v179, v181
	v_cvt_pk_bf16_f32 v121, v183, v185
	v_cvt_pk_bf16_f32 v122, v180, v182
	v_cvt_pk_bf16_f32 v123, v184, v227
	v_cvt_pk_bf16_f32 v124, v228, v229
	v_cvt_pk_bf16_f32 v125, v230, v174
	v_cvt_pk_bf16_f32 v114, v113, v114
	v_cvt_pk_bf16_f32 v115, v115, v116
	v_cvt_pk_bf16_f32 v116, v117, v101
	v_cvt_pk_bf16_f32 v117, v102, v103
	v_cvt_pk_bf16_f32 v100, v99, v100
	v_cvt_pk_bf16_f32 v101, v104, v105
	v_cvt_pk_bf16_f32 v102, v106, v107
	v_cvt_pk_bf16_f32 v103, v108, v109
	v_add_u32_e32 v99, s16, v214
	ds_read_b64_tr_b16 v[104:105], v99 offset:0
	ds_read_b64_tr_b16 v[106:107], v99 offset:0x800
	ds_read_b64_tr_b16 v[108:109], v99 offset:0x1000
	ds_read_b64_tr_b16 v[110:111], v99 offset:0x1800
	ds_read_b64_tr_b16 v[126:127], v99 offset:0x2000
	ds_read_b64_tr_b16 v[128:129], v99 offset:0x2800
	ds_read_b64_tr_b16 v[130:131], v99 offset:0x3000
	ds_read_b64_tr_b16 v[132:133], v99 offset:0x3800
	s_waitcnt lgkmcnt(6)
	s_nop 0
	v_mfma_f32_32x32x16_bf16 v[0:15], v[118:121], v[104:107], v[0:15]
	ds_read_b64_tr_b16 v[104:105], v99 offset:0x200
	ds_read_b64_tr_b16 v[106:107], v99 offset:0xa00
	s_waitcnt lgkmcnt(6)
	v_mfma_f32_32x32x16_bf16 v[0:15], v[122:125], v[108:111], v[0:15]
	ds_read_b64_tr_b16 v[108:109], v99 offset:0x1200
	ds_read_b64_tr_b16 v[110:111], v99 offset:0x1a00
	s_waitcnt lgkmcnt(6)
	v_mfma_f32_32x32x16_bf16 v[0:15], v[114:117], v[126:129], v[0:15]
	ds_read_b64_tr_b16 v[126:127], v99 offset:0x2200
	ds_read_b64_tr_b16 v[128:129], v99 offset:0x2a00
	s_waitcnt lgkmcnt(6)
	v_mfma_f32_32x32x16_bf16 v[0:15], v[100:103], v[130:133], v[0:15]
	ds_read_b64_tr_b16 v[130:131], v99 offset:0x3200
	ds_read_b64_tr_b16 v[132:133], v99 offset:0x3a00
	s_waitcnt lgkmcnt(6)
	v_mfma_f32_32x32x16_bf16 v[48:63], v[118:121], v[104:107], v[48:63]
	ds_read_b64_tr_b16 v[104:105], v99 offset:0x400
	ds_read_b64_tr_b16 v[106:107], v99 offset:0xc00
	s_waitcnt lgkmcnt(6)
	v_mfma_f32_32x32x16_bf16 v[48:63], v[122:125], v[108:111], v[48:63]
	ds_read_b64_tr_b16 v[108:109], v99 offset:0x1400
	ds_read_b64_tr_b16 v[110:111], v99 offset:0x1c00
	s_waitcnt lgkmcnt(6)
	v_mfma_f32_32x32x16_bf16 v[48:63], v[114:117], v[126:129], v[48:63]
	ds_read_b64_tr_b16 v[126:127], v99 offset:0x2400
	ds_read_b64_tr_b16 v[128:129], v99 offset:0x2c00
	s_waitcnt lgkmcnt(6)
	v_mfma_f32_32x32x16_bf16 v[48:63], v[100:103], v[130:133], v[48:63]
	ds_read_b64_tr_b16 v[130:131], v99 offset:0x3400
	ds_read_b64_tr_b16 v[132:133], v99 offset:0x3c00
	s_waitcnt lgkmcnt(6)
	v_mfma_f32_32x32x16_bf16 v[32:47], v[118:121], v[104:107], v[32:47]
	ds_read_b64_tr_b16 v[104:105], v99 offset:0x600
	ds_read_b64_tr_b16 v[106:107], v99 offset:0xe00
	s_waitcnt lgkmcnt(6)
	v_mfma_f32_32x32x16_bf16 v[32:47], v[122:125], v[108:111], v[32:47]
	ds_read_b64_tr_b16 v[108:109], v99 offset:0x1600
	ds_read_b64_tr_b16 v[110:111], v99 offset:0x1e00
	s_waitcnt lgkmcnt(6)
	v_mfma_f32_32x32x16_bf16 v[32:47], v[114:117], v[126:129], v[32:47]
	ds_read_b64_tr_b16 v[126:127], v99 offset:0x2600
	ds_read_b64_tr_b16 v[128:129], v99 offset:0x2e00
	s_waitcnt lgkmcnt(6)
	v_mfma_f32_32x32x16_bf16 v[32:47], v[100:103], v[130:133], v[32:47]
	ds_read_b64_tr_b16 v[130:131], v99 offset:0x3600
	ds_read_b64_tr_b16 v[132:133], v99 offset:0x3e00
	s_waitcnt lgkmcnt(0)
	v_mfma_f32_32x32x16_bf16 v[16:31], v[118:121], v[104:107], v[16:31]
	v_cmp_gt_f32_e32 vcc, 1.0, v98
	v_mfma_f32_32x32x16_bf16 v[16:31], v[122:125], v[108:111], v[16:31]
	v_mfma_f32_32x32x16_bf16 v[16:31], v[114:117], v[126:129], v[16:31]
	v_mfma_f32_32x32x16_bf16 v[16:31], v[100:103], v[130:133], v[16:31]
	s_cbranch_vccz .LBB0_1308
	s_and_saveexec_b64 s[8:9], s[6:7]
	ds_write_b32 v199, v98 offset:128
	s_or_b64 exec, exec, s[8:9]
	s_waitcnt lgkmcnt(0)
	v_add_u32_e32 v99, v191, v198
	ds_read_b128 v[100:103], v99 offset:224
	ds_read_b128 v[104:107], v99 offset:192
	ds_read_b128 v[108:111], v99 offset:160
	ds_read_b128 v[114:117], v99 offset:128
	s_waitcnt lgkmcnt(3)
	v_pk_mul_f32 v[12:13], v[12:13], v[100:101]
	s_waitcnt lgkmcnt(2)
	v_pk_mul_f32 v[8:9], v[8:9], v[104:105]
	s_waitcnt lgkmcnt(1)
	v_pk_mul_f32 v[4:5], v[4:5], v[108:109]
	v_pk_mul_f32 v[14:15], v[14:15], v[102:103]
	v_pk_mul_f32 v[10:11], v[10:11], v[106:107]
	v_pk_mul_f32 v[6:7], v[6:7], v[110:111]
	s_waitcnt lgkmcnt(0)
	v_pk_mul_f32 v[2:3], v[2:3], v[116:117]
	v_pk_mul_f32 v[0:1], v[0:1], v[114:115]
	v_pk_mul_f32 v[60:61], v[60:61], v[100:101]
	v_pk_mul_f32 v[56:57], v[56:57], v[104:105]
	v_pk_mul_f32 v[52:53], v[52:53], v[108:109]
	v_pk_mul_f32 v[62:63], v[62:63], v[102:103]
	v_pk_mul_f32 v[58:59], v[58:59], v[106:107]
	v_pk_mul_f32 v[54:55], v[54:55], v[110:111]
	v_pk_mul_f32 v[50:51], v[50:51], v[116:117]
	v_pk_mul_f32 v[48:49], v[48:49], v[114:115]
	v_pk_mul_f32 v[44:45], v[44:45], v[100:101]
	v_pk_mul_f32 v[40:41], v[40:41], v[104:105]
	v_pk_mul_f32 v[36:37], v[36:37], v[108:109]
	v_pk_mul_f32 v[46:47], v[46:47], v[102:103]
	v_pk_mul_f32 v[42:43], v[42:43], v[106:107]
	v_pk_mul_f32 v[38:39], v[38:39], v[110:111]
	v_pk_mul_f32 v[34:35], v[34:35], v[116:117]
	v_pk_mul_f32 v[32:33], v[32:33], v[114:115]
	v_pk_mul_f32 v[28:29], v[28:29], v[100:101]
	v_pk_mul_f32 v[24:25], v[24:25], v[104:105]
	v_pk_mul_f32 v[20:21], v[20:21], v[108:109]
	v_pk_mul_f32 v[30:31], v[30:31], v[102:103]
	v_pk_mul_f32 v[26:27], v[26:27], v[106:107]
	v_pk_mul_f32 v[22:23], v[22:23], v[110:111]
	v_pk_mul_f32 v[18:19], v[18:19], v[116:117]
	v_pk_mul_f32 v[16:17], v[16:17], v[114:115]
; #define SBAR() __builtin_amdgcn_sched_barrier(0)
; #define PK4(P, BASE, OUT) do { u32x4 w = {cvtb(P[BASE + 0], P[BASE + 1]), cvtb(P[BASE + 2], P[BASE + 3]), \
;     cvtb(P[BASE + 4], P[BASE + 5]), cvtb(P[BASE + 6], P[BASE + 7])}; OUT = *reinterpret_cast<bf16x8*>(&w); } while (0)
; __device__ __forceinline__ void finishSM(f32x16& p0, f32x16& p1, float alpha, float& l_reg, bf16x8& pa0, bf16x8& pa1, bf16x8& pa2, bf16x8& pa3) {
; #pragma unroll
;   for (int r = 0; r < 16; ++r) p1[r] = __builtin_amdgcn_exp2f(p1[r]);
;   float ps = 0;
; #pragma unroll
;   for (int r = 0; r < 16; ++r) ps += p0[r];
; #pragma unroll
;   for (int r = 0; r < 16; ++r) ps += p1[r];
;   { auto rr = __builtin_amdgcn_permlane32_swap(__float_as_uint(ps), __float_as_uint(ps), false, false);
;     ps = __uint_as_float(rr[0]) + __uint_as_float(rr[1]); }
;   l_reg = l_reg * alpha + ps;
;     ...
;   PK4(p0, 0, pa0); PK4(p0, 8, pa1); PK4(p1, 0, pa2); PK4(p1, 8, pa3);
;     ...
; }
; template <int NQK, int SD, bool MI> ...
;     ...
;   finishSM(pB0, pB1, alB, l_reg, pa0, pa1, pa2, pa3); SBAR();
;   pv_d0(o, vb0 + rc * SHM_V, pa0, pa1, pa2, pa3);
;     ...
;   if (hi == 0) li_l[r32] = l_reg; asm volatile("s_waitcnt lgkmcnt(0)" ::: "memory");
.LBB0_1308:
	v_exp_f32_e32 v80, v80
	v_exp_f32_e32 v81, v81
	v_exp_f32_e32 v82, v82
	v_exp_f32_e32 v83, v83
	v_exp_f32_e32 v84, v84
	v_exp_f32_e32 v99, v64
	v_add_f32_e32 v64, 0, v80
	v_exp_f32_e32 v85, v85
	v_add_f32_e32 v64, v81, v64
	v_exp_f32_e32 v86, v86
	v_add_f32_e32 v64, v82, v64
	v_exp_f32_e32 v87, v87
	v_add_f32_e32 v64, v83, v64
	v_exp_f32_e32 v88, v88
	v_add_f32_e32 v64, v84, v64
	v_exp_f32_e32 v89, v89
	v_add_f32_e32 v64, v85, v64
	v_exp_f32_e32 v90, v90
	v_add_f32_e32 v64, v86, v64
	v_exp_f32_e32 v91, v91
	v_add_f32_e32 v64, v87, v64
	v_exp_f32_e32 v92, v92
	v_add_f32_e32 v64, v88, v64
	v_exp_f32_e32 v93, v93
	v_add_f32_e32 v64, v89, v64
	v_exp_f32_e32 v94, v94
	v_add_f32_e32 v64, v90, v64
	v_exp_f32_e32 v95, v95
	v_add_f32_e32 v64, v91, v64
	v_add_f32_e32 v64, v92, v64
	v_exp_f32_e32 v100, v65
	v_add_f32_e32 v64, v93, v64
	v_exp_f32_e32 v101, v66
	v_add_f32_e32 v64, v94, v64
	v_exp_f32_e32 v102, v67
	v_add_f32_e32 v64, v95, v64
	v_exp_f32_e32 v103, v68
	v_add_f32_e32 v64, v99, v64
	v_exp_f32_e32 v104, v69
	v_add_f32_e32 v64, v100, v64
	v_exp_f32_e32 v105, v70
	v_add_f32_e32 v64, v101, v64
	v_exp_f32_e32 v106, v71
	v_add_f32_e32 v64, v102, v64
	v_exp_f32_e32 v107, v72
	v_add_f32_e32 v64, v103, v64
	v_exp_f32_e32 v108, v73
	v_add_f32_e32 v64, v104, v64
	v_exp_f32_e32 v109, v74
	v_add_f32_e32 v64, v105, v64
	v_exp_f32_e32 v110, v75
	v_add_f32_e32 v64, v106, v64
	v_exp_f32_e32 v111, v76
	v_add_f32_e32 v64, v107, v64
	v_exp_f32_e32 v113, v77
	v_add_f32_e32 v64, v108, v64
	v_exp_f32_e32 v114, v78
	v_add_f32_e32 v64, v109, v64
	v_exp_f32_e32 v115, v79
	v_add_f32_e32 v64, v110, v64
	v_add_f32_e32 v64, v111, v64
	v_add_f32_e32 v64, v113, v64
	v_add_f32_e32 v64, v114, v64
	v_add_f32_e32 v64, v115, v64
	v_mov_b32_e32 v65, v64
	s_nop 1
	v_permlane32_swap_b32_e32 v64, v65
	v_cvt_pk_bf16_f32 v66, v80, v81
	v_cvt_pk_bf16_f32 v67, v82, v83
	v_cvt_pk_bf16_f32 v68, v84, v85
	v_cvt_pk_bf16_f32 v69, v86, v87
	v_cvt_pk_bf16_f32 v70, v88, v89
	v_cvt_pk_bf16_f32 v71, v90, v91
	v_cvt_pk_bf16_f32 v72, v92, v93
	v_cvt_pk_bf16_f32 v73, v94, v95
	v_cvt_pk_bf16_f32 v74, v99, v100
	v_cvt_pk_bf16_f32 v75, v101, v102
	v_cvt_pk_bf16_f32 v76, v103, v104
	v_cvt_pk_bf16_f32 v77, v105, v106
	v_cvt_pk_bf16_f32 v78, v107, v108
	v_cvt_pk_bf16_f32 v79, v109, v110
	v_cvt_pk_bf16_f32 v80, v111, v113
	v_cvt_pk_bf16_f32 v81, v114, v115
	ds_read_b64_tr_b16 v[82:83], v215 offset:0
	ds_read_b64_tr_b16 v[84:85], v215 offset:0x800
	ds_read_b64_tr_b16 v[86:87], v215 offset:0x1000
	ds_read_b64_tr_b16 v[88:89], v215 offset:0x1800
	ds_read_b64_tr_b16 v[90:91], v215 offset:0x2000
	ds_read_b64_tr_b16 v[92:93], v215 offset:0x2800
	ds_read_b64_tr_b16 v[100:101], v215 offset:0x3000
	ds_read_b64_tr_b16 v[102:103], v215 offset:0x3800
	s_waitcnt lgkmcnt(6)
	s_nop 0
	v_mfma_f32_32x32x16_bf16 v[0:15], v[66:69], v[82:85], v[0:15]
	ds_read_b64_tr_b16 v[82:83], v215 offset:0x200
	ds_read_b64_tr_b16 v[84:85], v215 offset:0xa00
	s_waitcnt lgkmcnt(6)
	v_mfma_f32_32x32x16_bf16 v[0:15], v[70:73], v[86:89], v[0:15]
	ds_read_b64_tr_b16 v[86:87], v215 offset:0x1200
	ds_read_b64_tr_b16 v[88:89], v215 offset:0x1a00
	s_waitcnt lgkmcnt(6)
	v_mfma_f32_32x32x16_bf16 v[0:15], v[74:77], v[90:93], v[0:15]
	ds_read_b64_tr_b16 v[90:91], v215 offset:0x2200
	ds_read_b64_tr_b16 v[92:93], v215 offset:0x2a00
	s_waitcnt lgkmcnt(6)
	v_mfma_f32_32x32x16_bf16 v[0:15], v[78:81], v[100:103], v[0:15]
	ds_read_b64_tr_b16 v[100:101], v215 offset:0x3200
	ds_read_b64_tr_b16 v[102:103], v215 offset:0x3a00
	s_waitcnt lgkmcnt(6)
	v_mfma_f32_32x32x16_bf16 v[48:63], v[66:69], v[82:85], v[48:63]
	ds_read_b64_tr_b16 v[82:83], v215 offset:0x400
	ds_read_b64_tr_b16 v[84:85], v215 offset:0xc00
	s_waitcnt lgkmcnt(6)
	v_mfma_f32_32x32x16_bf16 v[48:63], v[70:73], v[86:89], v[48:63]
	ds_read_b64_tr_b16 v[86:87], v215 offset:0x1400
	ds_read_b64_tr_b16 v[88:89], v215 offset:0x1c00
	s_waitcnt lgkmcnt(6)
	v_mfma_f32_32x32x16_bf16 v[48:63], v[74:77], v[90:93], v[48:63]
	ds_read_b64_tr_b16 v[90:91], v215 offset:0x2400
	ds_read_b64_tr_b16 v[92:93], v215 offset:0x2c00
	s_waitcnt lgkmcnt(6)
	v_mfma_f32_32x32x16_bf16 v[48:63], v[78:81], v[100:103], v[48:63]
	ds_read_b64_tr_b16 v[100:101], v215 offset:0x3400
	ds_read_b64_tr_b16 v[102:103], v215 offset:0x3c00
	s_waitcnt lgkmcnt(6)
	v_mfma_f32_32x32x16_bf16 v[32:47], v[66:69], v[82:85], v[32:47]
	ds_read_b64_tr_b16 v[82:83], v215 offset:0x600
	ds_read_b64_tr_b16 v[84:85], v215 offset:0xe00
	s_waitcnt lgkmcnt(6)
	v_mfma_f32_32x32x16_bf16 v[32:47], v[70:73], v[86:89], v[32:47]
	ds_read_b64_tr_b16 v[86:87], v215 offset:0x1600
	ds_read_b64_tr_b16 v[88:89], v215 offset:0x1e00
	s_waitcnt lgkmcnt(6)
	v_mfma_f32_32x32x16_bf16 v[32:47], v[74:77], v[90:93], v[32:47]
	ds_read_b64_tr_b16 v[90:91], v215 offset:0x2600
	ds_read_b64_tr_b16 v[92:93], v215 offset:0x2e00
	s_waitcnt lgkmcnt(6)
	v_mfma_f32_32x32x16_bf16 v[32:47], v[78:81], v[100:103], v[32:47]
	ds_read_b64_tr_b16 v[100:101], v215 offset:0x3600
	ds_read_b64_tr_b16 v[102:103], v215 offset:0x3e00
	s_waitcnt lgkmcnt(0)
	v_mfma_f32_32x32x16_bf16 v[16:31], v[66:69], v[82:85], v[16:31]
	v_mfma_f32_32x32x16_bf16 v[16:31], v[70:73], v[86:89], v[16:31]
	v_mfma_f32_32x32x16_bf16 v[16:31], v[74:77], v[90:93], v[16:31]
	v_mfma_f32_32x32x16_bf16 v[16:31], v[78:81], v[100:103], v[16:31]
	s_and_saveexec_b64 s[8:9], s[6:7]
	s_cbranch_execz .LBB0_1258
	v_add_f32_e32 v66, v96, v97
	v_fmac_f32_e32 v66, v201, v112
	v_add_f32_e32 v64, v64, v65
	v_fmac_f32_e32 v64, v66, v98
	ds_write_b32 v199, v64
	s_branch .LBB0_1258

; template <int NQK>
; __device__ __forceinline__ void qkt(f32x16& p0, f32x16& p1, const char* Ks, const bf16x8* qr, int r32, int hi) {
;   constexpr int KROW = NQK * 32 + 16;
;   p0 = f32x16{}; p1 = f32x16{};
; #pragma unroll
;   for (int d0 = 0; d0 < NQK; ++d0) { const int cb = (d0 * 16 + hi * 8) * 2;
;     bf16x8 b0 = *reinterpret_cast<const bf16x8*>(Ks + r32 * KROW + cb);
;     bf16x8 b1 = *reinterpret_cast<const bf16x8*>(Ks + (32 + r32) * KROW + cb);
;     p0 = __builtin_amdgcn_mfma_f32_32x32x16_bf16(b0, qr[d0], p0, 0, 0, 0);
;     p1 = __builtin_amdgcn_mfma_f32_32x32x16_bf16(b1, qr[d0], p1, 0, 0, 0); }
; }
; template <int D0> __device__ __forceinline__ void pv_one_sm(f32x16& od, int vb, bf16x8 pa0, bf16x8 pa1, bf16x8 pa2, bf16x8 pa3, f32x16& q0, f32x16& q1, const float C, const float mnC) {
;     ...
;   if (D0 < 2) {
; #pragma unroll
;     for (int r = 8 * D0; r < 8 * D0 + 8; ++r) q0[r] = __builtin_amdgcn_exp2f(fmaf(q0[r], C, mnC));
;   } else {
; #pragma unroll
;     for (int r = 8 * (D0 - 2); r < 8 * (D0 - 2) + 8; ++r) q1[r] = fmaf(q1[r], C, mnC);
;   }
.LBB0_2524:
	v_cndmask_b32_e64 v180, v158, v157, s[10:11]
	v_and_b32_e32 v164, 0xffffffe0, v154
	v_mul_f32_e32 v154, 0xbdd53b94, v180
	v_fmamk_f32 v80, v80, 0x3dd53b94, v154
	v_exp_f32_e32 v155, v80
	v_fmamk_f32 v80, v81, 0x3dd53b94, v154
	v_exp_f32_e32 v157, v80
	v_fmamk_f32 v80, v82, 0x3dd53b94, v154
	v_exp_f32_e32 v159, v80
	v_fmamk_f32 v80, v83, 0x3dd53b94, v154
	v_exp_f32_e32 v160, v80
	v_fmamk_f32 v80, v84, 0x3dd53b94, v154
	v_exp_f32_e32 v161, v80
	v_fmamk_f32 v80, v85, 0x3dd53b94, v154
	v_exp_f32_e32 v181, v80
	v_fmamk_f32 v80, v86, 0x3dd53b94, v154
	v_exp_f32_e32 v184, v80
	v_fmamk_f32 v80, v87, 0x3dd53b94, v154
	v_exp_f32_e32 v185, v80
	v_fmamk_f32 v80, v88, 0x3dd53b94, v154
	v_exp_f32_e32 v189, v80
	v_fmamk_f32 v80, v89, 0x3dd53b94, v154
	v_exp_f32_e32 v191, v80
	v_fmamk_f32 v80, v90, 0x3dd53b94, v154
	v_exp_f32_e32 v198, v80
	v_fmamk_f32 v80, v91, 0x3dd53b94, v154
	v_exp_f32_e32 v199, v80
	v_fmamk_f32 v80, v92, 0x3dd53b94, v154
	v_exp_f32_e32 v200, v80
	v_fmamk_f32 v80, v93, 0x3dd53b94, v154
	v_exp_f32_e32 v201, v80
	v_fmamk_f32 v80, v94, 0x3dd53b94, v154
	s_lshl_b32 s18, s18, 7
	v_exp_f32_e32 v214, v80
	v_fmamk_f32 v80, v95, 0x3dd53b94, v154
	v_fmamk_f32 v178, v66, 0x3dd53b94, v154
	v_fmamk_f32 v179, v68, 0x3dd53b94, v154
	v_or_b32_e32 v182, 0x80, v176
	v_or_b32_e32 v183, 0x100, v176
	v_exp_f32_e32 v215, v80
	v_fmamk_f32 v158, v64, 0x3dd53b94, v154
	v_fmamk_f32 v216, v70, 0x3dd53b94, v154
	v_fmamk_f32 v217, v65, 0x3dd53b94, v154
	v_fmamk_f32 v218, v67, 0x3dd53b94, v154
	v_fmamk_f32 v219, v69, 0x3dd53b94, v154
	v_fmamk_f32 v220, v71, 0x3dd53b94, v154
	v_fmamk_f32 v221, v72, 0x3dd53b94, v154
	v_fmamk_f32 v222, v73, 0x3dd53b94, v154
	v_fmamk_f32 v223, v74, 0x3dd53b94, v154
	v_fmamk_f32 v224, v75, 0x3dd53b94, v154
	v_fmamk_f32 v225, v76, 0x3dd53b94, v154
	v_fmamk_f32 v226, v77, 0x3dd53b94, v154
	v_fmamk_f32 v227, v78, 0x3dd53b94, v154
	v_fmac_f32_e32 v154, 0x3dd53b94, v79
	s_waitcnt lgkmcnt(0)
	s_barrier
	ds_read_b128 v[64:67], v156 offset:64000
	ds_read_b128 v[68:71], v156 offset:51200
	ds_read_b128 v[146:149], v156 offset:51232
	ds_read_b128 v[150:153], v156 offset:64032
	v_exp_f32_e32 v216, v216
	s_waitcnt lgkmcnt(2)
	v_mfma_f32_32x32x16_bf16 v[80:95], v[68:71], v[140:143], 0
	v_mfma_f32_32x32x16_bf16 v[64:79], v[64:67], v[140:143], 0
	s_waitcnt lgkmcnt(0)
	v_mfma_f32_32x32x16_bf16 v[64:79], v[150:153], v[136:139], v[64:79]
	v_mfma_f32_32x32x16_bf16 v[80:95], v[146:149], v[136:139], v[80:95]
	ds_read_b128 v[146:149], v156 offset:51264
	ds_read_b128 v[150:153], v156 offset:64064
	s_waitcnt lgkmcnt(0)
	v_mfma_f32_32x32x16_bf16 v[64:79], v[150:153], v[132:135], v[64:79]
	v_mfma_f32_32x32x16_bf16 v[80:95], v[146:149], v[132:135], v[80:95]
	ds_read_b128 v[146:149], v156 offset:51296
	ds_read_b128 v[150:153], v156 offset:64096
	s_waitcnt lgkmcnt(0)
	v_mfma_f32_32x32x16_bf16 v[64:79], v[150:153], v[128:131], v[64:79]
	v_mfma_f32_32x32x16_bf16 v[80:95], v[146:149], v[128:131], v[80:95]
	ds_read_b128 v[146:149], v156 offset:51328
	ds_read_b128 v[150:153], v156 offset:64128
	s_waitcnt lgkmcnt(0)
	v_mfma_f32_32x32x16_bf16 v[64:79], v[150:153], v[124:127], v[64:79]
	v_mfma_f32_32x32x16_bf16 v[80:95], v[146:149], v[124:127], v[80:95]
	ds_read_b128 v[146:149], v156 offset:51360
	ds_read_b128 v[150:153], v156 offset:64160
	s_waitcnt lgkmcnt(0)
	v_mfma_f32_32x32x16_bf16 v[64:79], v[150:153], v[120:123], v[64:79]
	v_mfma_f32_32x32x16_bf16 v[80:95], v[146:149], v[120:123], v[80:95]
	ds_read_b128 v[146:149], v156 offset:51392
	ds_read_b128 v[150:153], v156 offset:64192
	s_waitcnt lgkmcnt(0)
	v_mfma_f32_32x32x16_bf16 v[64:79], v[150:153], v[116:119], v[64:79]
	v_mfma_f32_32x32x16_bf16 v[80:95], v[146:149], v[116:119], v[80:95]
	ds_read_b128 v[146:149], v156 offset:51424
	ds_read_b128 v[150:153], v156 offset:64224
	s_waitcnt lgkmcnt(0)
	v_mfma_f32_32x32x16_bf16 v[64:79], v[150:153], v[112:115], v[64:79]
	v_mfma_f32_32x32x16_bf16 v[80:95], v[146:149], v[112:115], v[80:95]
	ds_read_b128 v[146:149], v156 offset:51456
	ds_read_b128 v[150:153], v156 offset:64256
	s_waitcnt lgkmcnt(0)
	v_mfma_f32_32x32x16_bf16 v[64:79], v[150:153], v[108:111], v[64:79]
	v_mfma_f32_32x32x16_bf16 v[80:95], v[146:149], v[108:111], v[80:95]
	ds_read_b128 v[146:149], v156 offset:51488
	ds_read_b128 v[150:153], v156 offset:64288
	s_waitcnt lgkmcnt(0)
	v_mfma_f32_32x32x16_bf16 v[64:79], v[150:153], v[104:107], v[64:79]
	v_mfma_f32_32x32x16_bf16 v[80:95], v[146:149], v[104:107], v[80:95]
	ds_read_b128 v[146:149], v156 offset:51520
	ds_read_b128 v[150:153], v156 offset:64320
	s_waitcnt lgkmcnt(0)
	v_mfma_f32_32x32x16_bf16 v[64:79], v[150:153], v[100:103], v[64:79]
	v_mfma_f32_32x32x16_bf16 v[80:95], v[146:149], v[100:103], v[80:95]
	ds_read_b128 v[146:149], v156 offset:51552
	ds_read_b128 v[150:153], v156 offset:64352
	v_cvt_pk_bf16_f32 v156, v200, v201
	s_waitcnt lgkmcnt(0)
; __device__ __forceinline__ void decideSM(const f32x16& p0, const f32x16& p1, float& m_reg, float& mn, float& alpha, const float C, const float thr) {
;   float pmax = p0[0];
; #pragma unroll
;   for (int r = 1; r < 16; ++r) pmax = fmaxf(pmax, p0[r]);
; #pragma unroll
;   for (int r = 0; r < 16; ++r) pmax = fmaxf(pmax, p1[r]);
;   { auto rr = __builtin_amdgcn_permlane32_swap(__float_as_uint(pmax), __float_as_uint(pmax), false, false);
;     pmax = fmaxf(__uint_as_float(rr[0]), __uint_as_float(rr[1])); }
;   if (__builtin_expect(__all(pmax - m_reg <= thr), 1)) { mn = m_reg; alpha = 1.f; }
;   else { mn = fmaxf(m_reg, pmax); alpha = __builtin_amdgcn_exp2f((m_reg - mn) * C); m_reg = mn; }
; }
; __device__ __forceinline__ void finishSM(f32x16& p0, f32x16& p1, float alpha, float& l_reg, bf16x8& pa0, bf16x8& pa1, bf16x8& pa2, bf16x8& pa3) {
; #pragma unroll
;   for (int r = 0; r < 16; ++r) p1[r] = __builtin_amdgcn_exp2f(p1[r]);
;   float ps = 0;
; #pragma unroll
;   for (int r = 0; r < 16; ++r) ps += p0[r];
; #pragma unroll
;   for (int r = 0; r < 16; ++r) ps += p1[r];
;   { auto rr = __builtin_amdgcn_permlane32_swap(__float_as_uint(ps), __float_as_uint(ps), false, false);
;     ps = __uint_as_float(rr[0]) + __uint_as_float(rr[1]); }
;   l_reg = l_reg * alpha + ps;
;     ...
;   PK4(p0, 0, pa0); PK4(p0, 8, pa1); PK4(p1, 0, pa2); PK4(p1, 8, pa3);
;     ...
; }
; template <int D0> __device__ __forceinline__ void pv_one_sm(f32x16& od, int vb, bf16x8 pa0, bf16x8 pa1, bf16x8 pa2, bf16x8 pa3, f32x16& q0, f32x16& q1, const float C, const float mnC) {
;   const s16x4 l0 = tr_read<v_rd_off(D0, 0, 0)>(vb), h0 = tr_read<v_rd_off(D0, 0, 1)>(vb), l1 = tr_read<v_rd_off(D0, 1, 0)>(vb), h1 = tr_read<v_rd_off(D0, 1, 1)>(vb);
;   const s16x4 l2 = tr_read<v_rd_off(D0, 2, 0)>(vb), h2 = tr_read<v_rd_off(D0, 2, 1)>(vb), l3 = tr_read<v_rd_off(D0, 3, 0)>(vb), h3 = tr_read<v_rd_off(D0, 3, 1)>(vb);
;   asm volatile("s_waitcnt lgkmcnt(0)" ::: "memory"); SBAR();
;     ...
;   od = __builtin_amdgcn_mfma_f32_32x32x16_bf16(pa0, PK(l0, h0), od, 0, 0, 0);
;   od = __builtin_amdgcn_mfma_f32_32x32x16_bf16(pa1, PK(l1, h1), od, 0, 0, 0);
;   od = __builtin_amdgcn_mfma_f32_32x32x16_bf16(pa2, PK(l2, h2), od, 0, 0, 0);
;   od = __builtin_amdgcn_mfma_f32_32x32x16_bf16(pa3, PK(l3, h3), od, 0, 0, 0);
;     ...
;   if (D0 < 2) {
; #pragma unroll
;     for (int r = 8 * D0; r < 8 * D0 + 8; ++r) q0[r] = __builtin_amdgcn_exp2f(fmaf(q0[r], C, mnC));
	v_mfma_f32_32x32x16_bf16 v[64:79], v[150:153], v[96:99], v[64:79]
	v_add_f32_e32 v150, 0, v155
	v_add_f32_e32 v150, v157, v150
	v_add_f32_e32 v150, v159, v150
	v_add_f32_e32 v150, v160, v150
	v_add_f32_e32 v150, v161, v150
	v_add_f32_e32 v150, v181, v150
	v_add_f32_e32 v150, v184, v150
	v_mfma_f32_32x32x16_bf16 v[80:95], v[146:149], v[96:99], v[80:95]
	v_add_f32_e32 v150, v185, v150
	v_add_f32_e32 v150, v189, v150
	v_add_f32_e32 v150, v191, v150
	v_cvt_pk_bf16_f32 v159, v159, v160
	v_cvt_pk_bf16_f32 v160, v161, v181
	v_cvt_pk_bf16_f32 v161, v184, v185
	v_add_f32_e32 v150, v198, v150
	s_nop 4
	v_max_f32_e32 v181, v81, v81
	v_max_f32_e32 v184, v80, v80
	v_max_f32_e32 v181, v184, v181
	v_add_f32_e32 v150, v199, v150
	v_max3_f32 v181, v181, v82, v83
	v_exp_f32_e32 v146, v158
	v_add_f32_e32 v150, v200, v150
	v_max3_f32 v181, v181, v84, v85
	v_exp_f32_e32 v147, v217
	v_add_f32_e32 v150, v201, v150
	v_max3_f32 v181, v181, v86, v87
	v_exp_f32_e32 v148, v178
	v_add_f32_e32 v150, v214, v150
	v_max3_f32 v181, v181, v88, v89
	v_exp_f32_e32 v149, v218
	v_add_f32_e32 v150, v215, v150
	v_max3_f32 v181, v181, v90, v91
	v_exp_f32_e32 v152, v179
	v_add_f32_e32 v150, v146, v150
	v_max3_f32 v181, v181, v92, v93
	v_exp_f32_e32 v153, v219
	v_add_f32_e32 v150, v147, v150
	v_max3_f32 v181, v181, v94, v95
	v_add_f32_e32 v150, v148, v150
	v_max3_f32 v181, v181, v64, v65
	v_exp_f32_e32 v217, v220
	v_add_f32_e32 v150, v149, v150
	v_max3_f32 v181, v181, v66, v67
	v_exp_f32_e32 v218, v221
	v_add_f32_e32 v150, v152, v150
	v_max3_f32 v181, v181, v68, v69
	v_exp_f32_e32 v219, v222
	v_add_f32_e32 v150, v153, v150
	v_max3_f32 v181, v181, v70, v71
	v_exp_f32_e32 v220, v223
	v_add_f32_e32 v150, v216, v150
	v_max3_f32 v181, v181, v72, v73
	v_exp_f32_e32 v221, v224
	v_add_f32_e32 v150, v217, v150
	v_max3_f32 v181, v181, v74, v75
	v_exp_f32_e32 v222, v225
	v_add_f32_e32 v150, v218, v150
	v_max3_f32 v181, v181, v76, v77
	v_exp_f32_e32 v223, v226
	v_add_f32_e32 v150, v219, v150
	v_max3_f32 v181, v181, v78, v79
	v_exp_f32_e32 v224, v227
	v_add_f32_e32 v150, v220, v150
	v_mov_b32_e32 v184, v181
	v_exp_f32_e32 v225, v154
	v_add_f32_e32 v150, v221, v150
	v_permlane32_swap_b32_e32 v181, v184
	v_add_f32_e32 v150, v222, v150
	v_max_f32_e32 v184, v184, v184
	v_max_f32_e32 v181, v181, v181
	v_add_f32_e32 v150, v223, v150
	v_max_f32_e32 v181, v181, v184
	v_add_f32_e32 v150, v224, v150
	v_sub_f32_e32 v184, v181, v180
	v_add_f32_e32 v178, v225, v150
	v_cmp_ge_f32_e32 vcc, s56, v184
	v_max_f32_e32 v184, v180, v180
	v_mov_b32_e32 v179, v178
	s_cmp_eq_u64 vcc, exec
	v_max_f32_e32 v181, v184, v181
	v_permlane32_swap_b32_e32 v178, v179
	v_cvt_pk_bf16_f32 v150, v146, v147
	s_cselect_b64 s[10:11], -1, 0
	v_sub_f32_e32 v184, v180, v181
	v_cvt_pk_bf16_f32 v158, v155, v157
	v_cvt_pk_bf16_f32 v154, v189, v191
	v_cvt_pk_bf16_f32 v155, v198, v199
	v_cvt_pk_bf16_f32 v157, v214, v215
	v_cvt_pk_bf16_f32 v151, v148, v149
	v_cvt_pk_bf16_f32 v152, v152, v153
	v_cvt_pk_bf16_f32 v153, v216, v217
	v_cvt_pk_bf16_f32 v146, v218, v219
	v_cvt_pk_bf16_f32 v147, v220, v221
	v_cvt_pk_bf16_f32 v148, v222, v223
	v_cvt_pk_bf16_f32 v149, v224, v225
	v_mul_f32_e32 v189, 0x3dd53b94, v184
	s_mov_b32 s14, s30
	s_mov_b32 s15, s31
	buffer_load_dwordx4 v[198:201], v174, s[12:15], s88 offen
	buffer_load_dwordx4 v[214:217], v174, s[12:15], s77 offen
	buffer_load_dwordx4 v[218:221], v176, s[28:31], s80 offen
	buffer_load_dwordx4 v[222:225], v182, s[28:31], s80 offen
	s_nop 0
	buffer_load_dwordx4 v[182:185], v183, s[28:31], s80 offen
	v_exp_f32_e32 v174, v189
	s_cmp_lg_u32 16, -1
	s_cselect_b32 s12, 16, 0
	s_addk_i32 s12, 0x4000
	v_add_u32_e32 v176, s12, v167
	ds_read_b64_tr_b16 v[226:227], v176 offset:0
	ds_read_b64_tr_b16 v[228:229], v176 offset:0x800
	ds_read_b64_tr_b16 v[230:231], v176 offset:0x1000
	ds_read_b64_tr_b16 v[232:233], v176 offset:0x1800
	ds_read_b64_tr_b16 v[234:235], v176 offset:0x2000
	ds_read_b64_tr_b16 v[236:237], v176 offset:0x2800
	ds_read_b64_tr_b16 v[238:239], v176 offset:0x3000
	ds_read_b64_tr_b16 v[240:241], v176 offset:0x3800
	s_waitcnt lgkmcnt(6)
	s_nop 0
	v_mfma_f32_32x32x16_bf16 v[0:15], v[158:161], v[226:229], v[0:15]
	ds_read_b64_tr_b16 v[226:227], v176 offset:0x200
	ds_read_b64_tr_b16 v[228:229], v176 offset:0xa00
	s_waitcnt lgkmcnt(6)
	v_mfma_f32_32x32x16_bf16 v[0:15], v[154:157], v[230:233], v[0:15]
	ds_read_b64_tr_b16 v[230:231], v176 offset:0x1200
	ds_read_b64_tr_b16 v[232:233], v176 offset:0x1a00
	s_waitcnt lgkmcnt(6)
	v_mfma_f32_32x32x16_bf16 v[0:15], v[150:153], v[234:237], v[0:15]
	ds_read_b64_tr_b16 v[234:235], v176 offset:0x2200
	ds_read_b64_tr_b16 v[236:237], v176 offset:0x2a00
	s_waitcnt lgkmcnt(6)
	v_mfma_f32_32x32x16_bf16 v[0:15], v[146:149], v[238:241], v[0:15]
	ds_read_b64_tr_b16 v[238:239], v176 offset:0x3200
	ds_read_b64_tr_b16 v[240:241], v176 offset:0x3a00
	s_waitcnt lgkmcnt(6)
	v_mfma_f32_32x32x16_bf16 v[16:31], v[158:161], v[226:229], v[16:31]
	ds_read_b64_tr_b16 v[226:227], v176 offset:0x400
	ds_read_b64_tr_b16 v[228:229], v176 offset:0xc00
	s_waitcnt lgkmcnt(6)
	v_mfma_f32_32x32x16_bf16 v[16:31], v[154:157], v[230:233], v[16:31]
	ds_read_b64_tr_b16 v[230:231], v176 offset:0x1400
	ds_read_b64_tr_b16 v[232:233], v176 offset:0x1c00
	s_waitcnt lgkmcnt(6)
	v_mfma_f32_32x32x16_bf16 v[16:31], v[150:153], v[234:237], v[16:31]
	ds_read_b64_tr_b16 v[234:235], v176 offset:0x2400
	ds_read_b64_tr_b16 v[236:237], v176 offset:0x2c00
	s_waitcnt lgkmcnt(6)
	v_mfma_f32_32x32x16_bf16 v[16:31], v[146:149], v[238:241], v[16:31]
	ds_read_b64_tr_b16 v[238:239], v176 offset:0x3400
	ds_read_b64_tr_b16 v[240:241], v176 offset:0x3c00
	s_waitcnt lgkmcnt(6)
; #define SBAR() __builtin_amdgcn_sched_barrier(0)
; template <int D0> __device__ __forceinline__ void pv_one_sm(f32x16& od, int vb, bf16x8 pa0, bf16x8 pa1, bf16x8 pa2, bf16x8 pa3, f32x16& q0, f32x16& q1, const float C, const float mnC) {
;   const s16x4 l0 = tr_read<v_rd_off(D0, 0, 0)>(vb), h0 = tr_read<v_rd_off(D0, 0, 1)>(vb), l1 = tr_read<v_rd_off(D0, 1, 0)>(vb), h1 = tr_read<v_rd_off(D0, 1, 1)>(vb);
;   const s16x4 l2 = tr_read<v_rd_off(D0, 2, 0)>(vb), h2 = tr_read<v_rd_off(D0, 2, 1)>(vb), l3 = tr_read<v_rd_off(D0, 3, 0)>(vb), h3 = tr_read<v_rd_off(D0, 3, 1)>(vb);
;   asm volatile("s_waitcnt lgkmcnt(0)" ::: "memory"); SBAR();
;     ...
;   od = __builtin_amdgcn_mfma_f32_32x32x16_bf16(pa0, PK(l0, h0), od, 0, 0, 0);
;   od = __builtin_amdgcn_mfma_f32_32x32x16_bf16(pa1, PK(l1, h1), od, 0, 0, 0);
;   od = __builtin_amdgcn_mfma_f32_32x32x16_bf16(pa2, PK(l2, h2), od, 0, 0, 0);
;   od = __builtin_amdgcn_mfma_f32_32x32x16_bf16(pa3, PK(l3, h3), od, 0, 0, 0);
;     ...
;   if (D0 < 2) {
; #pragma unroll
;     for (int r = 8 * D0; r < 8 * D0 + 8; ++r) q0[r] = __builtin_amdgcn_exp2f(fmaf(q0[r], C, mnC));
;   } else {
; #pragma unroll
;     for (int r = 8 * (D0 - 2); r < 8 * (D0 - 2) + 8; ++r) q1[r] = fmaf(q1[r], C, mnC);
;   }
; }
	v_mfma_f32_32x32x16_bf16 v[32:47], v[158:161], v[226:229], v[32:47]
	ds_read_b64_tr_b16 v[226:227], v176 offset:0x600
	ds_read_b64_tr_b16 v[228:229], v176 offset:0xe00
	s_waitcnt lgkmcnt(6)
	v_mfma_f32_32x32x16_bf16 v[32:47], v[154:157], v[230:233], v[32:47]
	ds_read_b64_tr_b16 v[230:231], v176 offset:0x1600
	ds_read_b64_tr_b16 v[232:233], v176 offset:0x1e00
	s_waitcnt lgkmcnt(6)
	v_mfma_f32_32x32x16_bf16 v[32:47], v[150:153], v[234:237], v[32:47]
	ds_read_b64_tr_b16 v[234:235], v176 offset:0x2600
	ds_read_b64_tr_b16 v[236:237], v176 offset:0x2e00
	s_waitcnt lgkmcnt(6)
	v_mfma_f32_32x32x16_bf16 v[32:47], v[146:149], v[238:241], v[32:47]
	ds_read_b64_tr_b16 v[238:239], v176 offset:0x3600
	ds_read_b64_tr_b16 v[240:241], v176 offset:0x3e00
	s_waitcnt lgkmcnt(0)
	v_mfma_f32_32x32x16_bf16 v[48:63], v[158:161], v[226:229], v[48:63]
	s_waitcnt vmcnt(0)
	s_waitcnt vmcnt(4)
	ds_write_b128 v173, v[198:201]
	s_waitcnt vmcnt(3)
	ds_write_b128 v173, v[214:217] offset:8192
	s_waitcnt vmcnt(2)
	ds_write_b128 v172, v[218:221] offset:49152
	s_waitcnt vmcnt(1)
	ds_write_b128 v172, v[222:225] offset:49280
	s_waitcnt vmcnt(0)
	ds_write_b128 v172, v[182:185] offset:49408
	v_mfma_f32_32x32x16_bf16 v[48:63], v[154:157], v[230:233], v[48:63]
	v_mfma_f32_32x32x16_bf16 v[48:63], v[150:153], v[234:237], v[48:63]
	v_cndmask_b32_e64 v150, v174, 1.0, s[10:11]
	v_cmp_gt_f32_e32 vcc, 1.0, v150
	v_mfma_f32_32x32x16_bf16 v[48:63], v[146:149], v[238:241], v[48:63]
	s_cbranch_vccz .LBB0_2528
	s_and_saveexec_b64 s[12:13], s[8:9]
	ds_write_b32 v168, v150 offset:128
	s_or_b64 exec, exec, s[12:13]
	s_waitcnt lgkmcnt(0)
	v_add_u32_e32 v151, v165, v162
	ds_read_b128 v[146:149], v151 offset:224
	ds_read_b128 v[152:155], v151 offset:192
	ds_read_b128 v[156:159], v151 offset:160
	ds_read_b128 v[182:185], v151 offset:128
	s_waitcnt lgkmcnt(3)
	v_pk_mul_f32 v[12:13], v[12:13], v[146:147]
	s_waitcnt lgkmcnt(2)
	v_pk_mul_f32 v[8:9], v[8:9], v[152:153]
	s_waitcnt lgkmcnt(1)
	v_pk_mul_f32 v[4:5], v[4:5], v[156:157]
	v_pk_mul_f32 v[14:15], v[14:15], v[148:149]
	v_pk_mul_f32 v[10:11], v[10:11], v[154:155]
	v_pk_mul_f32 v[6:7], v[6:7], v[158:159]
	s_waitcnt lgkmcnt(0)
	v_pk_mul_f32 v[2:3], v[2:3], v[184:185]
	v_pk_mul_f32 v[0:1], v[0:1], v[182:183]
	v_pk_mul_f32 v[28:29], v[28:29], v[146:147]
	v_pk_mul_f32 v[24:25], v[24:25], v[152:153]
	v_pk_mul_f32 v[20:21], v[20:21], v[156:157]
	v_pk_mul_f32 v[30:31], v[30:31], v[148:149]
	v_pk_mul_f32 v[26:27], v[26:27], v[154:155]
	v_pk_mul_f32 v[22:23], v[22:23], v[158:159]
	v_pk_mul_f32 v[18:19], v[18:19], v[184:185]
	v_pk_mul_f32 v[16:17], v[16:17], v[182:183]
	v_pk_mul_f32 v[44:45], v[44:45], v[146:147]
	v_pk_mul_f32 v[40:41], v[40:41], v[152:153]
	v_pk_mul_f32 v[36:37], v[36:37], v[156:157]
	v_pk_mul_f32 v[46:47], v[46:47], v[148:149]
	v_pk_mul_f32 v[42:43], v[42:43], v[154:155]
	v_pk_mul_f32 v[38:39], v[38:39], v[158:159]
	v_pk_mul_f32 v[34:35], v[34:35], v[184:185]
	v_pk_mul_f32 v[32:33], v[32:33], v[182:183]
	v_pk_mul_f32 v[60:61], v[60:61], v[146:147]
	v_pk_mul_f32 v[56:57], v[56:57], v[152:153]
	v_pk_mul_f32 v[52:53], v[52:53], v[156:157]
	v_pk_mul_f32 v[62:63], v[62:63], v[148:149]
	v_pk_mul_f32 v[58:59], v[58:59], v[154:155]
	v_pk_mul_f32 v[54:55], v[54:55], v[158:159]
	v_pk_mul_f32 v[50:51], v[50:51], v[184:185]
	v_pk_mul_f32 v[48:49], v[48:49], v[182:183]
.LBB0_2528:
	v_cndmask_b32_e64 v147, v181, v180, s[10:11]
	v_mul_f32_e32 v148, 0xbdd53b94, v147
	v_fmamk_f32 v80, v80, 0x3dd53b94, v148
	v_exp_f32_e32 v149, v80
	v_fmamk_f32 v80, v81, 0x3dd53b94, v148
	v_exp_f32_e32 v151, v80
	v_fmamk_f32 v80, v82, 0x3dd53b94, v148
	v_exp_f32_e32 v156, v80
	v_fmamk_f32 v80, v83, 0x3dd53b94, v148
	v_exp_f32_e32 v157, v80
	v_fmamk_f32 v80, v84, 0x3dd53b94, v148
	v_exp_f32_e32 v158, v80
	v_fmamk_f32 v80, v85, 0x3dd53b94, v148
	v_exp_f32_e32 v159, v80
	v_fmamk_f32 v80, v86, 0x3dd53b94, v148
	v_exp_f32_e32 v160, v80
	v_fmamk_f32 v80, v87, 0x3dd53b94, v148
	v_exp_f32_e32 v161, v80
	v_fmamk_f32 v80, v88, 0x3dd53b94, v148
	v_exp_f32_e32 v172, v80
	v_fmamk_f32 v80, v89, 0x3dd53b94, v148
	v_sub_f32_e32 v146, 0xf149f2ca, v177
	v_exp_f32_e32 v173, v80
	v_fmamk_f32 v80, v90, 0x3dd53b94, v148
	v_mul_f32_e32 v146, 0x3dd53b94, v146
	v_exp_f32_e32 v174, v80
	v_fmamk_f32 v80, v91, 0x3dd53b94, v148
	v_exp_f32_e32 v146, v146
	v_exp_f32_e32 v176, v80
	v_fmamk_f32 v80, v92, 0x3dd53b94, v148
	v_exp_f32_e32 v177, v80
	v_fmamk_f32 v80, v93, 0x3dd53b94, v148
	v_exp_f32_e32 v180, v80
	v_fmamk_f32 v80, v94, 0x3dd53b94, v148
	v_exp_f32_e32 v181, v80
	v_fmamk_f32 v80, v95, 0x3dd53b94, v148
	v_exp_f32_e32 v182, v80
	v_fmamk_f32 v183, v64, 0x3dd53b94, v148
	v_fmamk_f32 v184, v65, 0x3dd53b94, v148
	v_fmamk_f32 v185, v66, 0x3dd53b94, v148
	v_fmamk_f32 v189, v67, 0x3dd53b94, v148
	v_fmamk_f32 v191, v68, 0x3dd53b94, v148
	v_fmamk_f32 v198, v69, 0x3dd53b94, v148
	v_fmamk_f32 v199, v70, 0x3dd53b94, v148
	v_fmamk_f32 v200, v71, 0x3dd53b94, v148
	v_fmamk_f32 v201, v72, 0x3dd53b94, v148
	v_fmamk_f32 v214, v73, 0x3dd53b94, v148
	v_fmamk_f32 v215, v74, 0x3dd53b94, v148
	v_fmamk_f32 v216, v75, 0x3dd53b94, v148
	v_fmamk_f32 v217, v76, 0x3dd53b94, v148
	v_fmamk_f32 v218, v77, 0x3dd53b94, v148
	v_fmamk_f32 v219, v78, 0x3dd53b94, v148
	v_fmac_f32_e32 v148, 0x3dd53b94, v79
	s_waitcnt lgkmcnt(0)
	s_barrier
; #define PK4(P, BASE, OUT) do { u32x4 w = {cvtb(P[BASE + 0], P[BASE + 1]), cvtb(P[BASE + 2], P[BASE + 3]), \
;     cvtb(P[BASE + 4], P[BASE + 5]), cvtb(P[BASE + 6], P[BASE + 7])}; OUT = *reinterpret_cast<bf16x8*>(&w); } while (0)
; __device__ __forceinline__ void decideSM(const f32x16& p0, const f32x16& p1, float& m_reg, float& mn, float& alpha, const float C, const float thr) {
;   float pmax = p0[0];
; #pragma unroll
;   for (int r = 1; r < 16; ++r) pmax = fmaxf(pmax, p0[r]);
; #pragma unroll
;   for (int r = 0; r < 16; ++r) pmax = fmaxf(pmax, p1[r]);
;   { auto rr = __builtin_amdgcn_permlane32_swap(__float_as_uint(pmax), __float_as_uint(pmax), false, false);
;     pmax = fmaxf(__uint_as_float(rr[0]), __uint_as_float(rr[1])); }
;   if (__builtin_expect(__all(pmax - m_reg <= thr), 1)) { mn = m_reg; alpha = 1.f; }
;   else { mn = fmaxf(m_reg, pmax); alpha = __builtin_amdgcn_exp2f((m_reg - mn) * C); m_reg = mn; }
; }
; __device__ __forceinline__ void finishSM(f32x16& p0, f32x16& p1, float alpha, float& l_reg, bf16x8& pa0, bf16x8& pa1, bf16x8& pa2, bf16x8& pa3) {
; #pragma unroll
;   for (int r = 0; r < 16; ++r) p1[r] = __builtin_amdgcn_exp2f(p1[r]);
;   float ps = 0;
; #pragma unroll
;   for (int r = 0; r < 16; ++r) ps += p0[r];
; #pragma unroll
;   for (int r = 0; r < 16; ++r) ps += p1[r];
;   { auto rr = __builtin_amdgcn_permlane32_swap(__float_as_uint(ps), __float_as_uint(ps), false, false);
;     ps = __uint_as_float(rr[0]) + __uint_as_float(rr[1]); }
;   l_reg = l_reg * alpha + ps;
;     ...
;   PK4(p0, 0, pa0); PK4(p0, 8, pa1); PK4(p1, 0, pa2); PK4(p1, 8, pa3);
;     ...
; }
; template <int NQK>
; __device__ __forceinline__ void qkt(f32x16& p0, f32x16& p1, const char* Ks, const bf16x8* qr, int r32, int hi) {
;   constexpr int KROW = NQK * 32 + 16;
;   p0 = f32x16{}; p1 = f32x16{};
; #pragma unroll
;   for (int d0 = 0; d0 < NQK; ++d0) { const int cb = (d0 * 16 + hi * 8) * 2;
;     bf16x8 b0 = *reinterpret_cast<const bf16x8*>(Ks + r32 * KROW + cb);
;     bf16x8 b1 = *reinterpret_cast<const bf16x8*>(Ks + (32 + r32) * KROW + cb);
;     p0 = __builtin_amdgcn_mfma_f32_32x32x16_bf16(b0, qr[d0], p0, 0, 0, 0);
;     p1 = __builtin_amdgcn_mfma_f32_32x32x16_bf16(b1, qr[d0], p1, 0, 0, 0); }
; }
	ds_read_b128 v[64:67], v169 offset:61952
	ds_read_b128 v[68:71], v169 offset:49152
	ds_read_b128 v[152:155], v169 offset:49184
	s_waitcnt lgkmcnt(1)
	v_mfma_f32_32x32x16_bf16 v[80:95], v[68:71], v[140:143], 0
	v_mfma_f32_32x32x16_bf16 v[64:79], v[64:67], v[140:143], 0
	ds_read_b128 v[140:143], v169 offset:61984
	s_waitcnt lgkmcnt(1)
	v_mfma_f32_32x32x16_bf16 v[80:95], v[152:155], v[136:139], v[80:95]
	s_waitcnt lgkmcnt(0)
	v_mfma_f32_32x32x16_bf16 v[64:79], v[140:143], v[136:139], v[64:79]
	ds_read_b128 v[136:139], v169 offset:49216
	ds_read_b128 v[140:143], v169 offset:62016
	s_waitcnt lgkmcnt(1)
	v_mfma_f32_32x32x16_bf16 v[80:95], v[136:139], v[132:135], v[80:95]
	s_waitcnt lgkmcnt(0)
	v_mfma_f32_32x32x16_bf16 v[64:79], v[140:143], v[132:135], v[64:79]
	ds_read_b128 v[132:135], v169 offset:49248
	ds_read_b128 v[136:139], v169 offset:62048
	s_waitcnt lgkmcnt(1)
	v_mfma_f32_32x32x16_bf16 v[80:95], v[132:135], v[128:131], v[80:95]
	s_waitcnt lgkmcnt(0)
	v_mfma_f32_32x32x16_bf16 v[64:79], v[136:139], v[128:131], v[64:79]
	ds_read_b128 v[128:131], v169 offset:49280
	ds_read_b128 v[132:135], v169 offset:62080
	s_waitcnt lgkmcnt(1)
	v_mfma_f32_32x32x16_bf16 v[80:95], v[128:131], v[124:127], v[80:95]
	s_waitcnt lgkmcnt(0)
	v_mfma_f32_32x32x16_bf16 v[64:79], v[132:135], v[124:127], v[64:79]
	ds_read_b128 v[124:127], v169 offset:49312
	ds_read_b128 v[128:131], v169 offset:62112
	s_waitcnt lgkmcnt(1)
	v_mfma_f32_32x32x16_bf16 v[80:95], v[124:127], v[120:123], v[80:95]
	s_waitcnt lgkmcnt(0)
	v_mfma_f32_32x32x16_bf16 v[64:79], v[128:131], v[120:123], v[64:79]
	ds_read_b128 v[120:123], v169 offset:49344
	ds_read_b128 v[124:127], v169 offset:62144
	s_waitcnt lgkmcnt(1)
	v_mfma_f32_32x32x16_bf16 v[80:95], v[120:123], v[116:119], v[80:95]
	s_waitcnt lgkmcnt(0)
	v_mfma_f32_32x32x16_bf16 v[64:79], v[124:127], v[116:119], v[64:79]
	ds_read_b128 v[116:119], v169 offset:49376
	ds_read_b128 v[120:123], v169 offset:62176
	s_waitcnt lgkmcnt(1)
	v_mfma_f32_32x32x16_bf16 v[80:95], v[116:119], v[112:115], v[80:95]
	s_waitcnt lgkmcnt(0)
	v_mfma_f32_32x32x16_bf16 v[64:79], v[120:123], v[112:115], v[64:79]
	ds_read_b128 v[112:115], v169 offset:49408
	ds_read_b128 v[116:119], v169 offset:62208
	v_exp_f32_e32 v120, v219
	v_exp_f32_e32 v121, v148
	s_waitcnt lgkmcnt(1)
	v_mfma_f32_32x32x16_bf16 v[80:95], v[112:115], v[108:111], v[80:95]
	s_waitcnt lgkmcnt(0)
	v_mfma_f32_32x32x16_bf16 v[64:79], v[116:119], v[108:111], v[64:79]
	ds_read_b128 v[108:111], v169 offset:49440
	ds_read_b128 v[112:115], v169 offset:62240
	v_exp_f32_e32 v116, v215
	v_exp_f32_e32 v117, v216
	v_exp_f32_e32 v118, v217
	v_exp_f32_e32 v119, v218
	s_waitcnt lgkmcnt(1)
	v_mfma_f32_32x32x16_bf16 v[80:95], v[108:111], v[104:107], v[80:95]
	s_waitcnt lgkmcnt(0)
	v_mfma_f32_32x32x16_bf16 v[64:79], v[112:115], v[104:107], v[64:79]
	ds_read_b128 v[104:107], v169 offset:49472
	ds_read_b128 v[108:111], v169 offset:62272
	v_exp_f32_e32 v114, v201
	v_exp_f32_e32 v115, v214
	s_waitcnt lgkmcnt(1)
	v_mfma_f32_32x32x16_bf16 v[80:95], v[104:107], v[100:103], v[80:95]
	s_waitcnt lgkmcnt(0)
	v_mfma_f32_32x32x16_bf16 v[64:79], v[108:111], v[100:103], v[64:79]
	ds_read_b128 v[100:103], v169 offset:49504
	ds_read_b128 v[104:107], v169 offset:62304
	v_exp_f32_e32 v108, v191
	v_exp_f32_e32 v109, v198
	v_exp_f32_e32 v110, v199
	v_exp_f32_e32 v111, v200
	s_waitcnt lgkmcnt(1)
	v_mfma_f32_32x32x16_bf16 v[80:95], v[100:103], v[96:99], v[80:95]
	v_cvt_pk_bf16_f32 v100, v172, v173
	v_cvt_pk_bf16_f32 v101, v174, v176
	v_cvt_pk_bf16_f32 v102, v177, v180
	v_cvt_pk_bf16_f32 v103, v181, v182
	s_waitcnt lgkmcnt(0)
	v_mfma_f32_32x32x16_bf16 v[64:79], v[104:107], v[96:99], v[64:79]
	v_add_f32_e32 v96, 0, v149
	v_add_f32_e32 v96, v151, v96
	v_add_f32_e32 v96, v156, v96
	v_add_f32_e32 v96, v157, v96
	v_add_f32_e32 v96, v158, v96
	v_add_f32_e32 v96, v159, v96
	v_add_f32_e32 v96, v160, v96
	v_add_f32_e32 v96, v161, v96
	v_add_f32_e32 v96, v172, v96
	v_add_f32_e32 v96, v173, v96
	v_add_f32_e32 v96, v174, v96
	v_add_f32_e32 v96, v176, v96
	v_exp_f32_e32 v104, v183
	v_add_f32_e32 v96, v177, v96
	v_exp_f32_e32 v105, v184
	v_add_f32_e32 v96, v180, v96
	v_exp_f32_e32 v106, v185
	v_add_f32_e32 v96, v181, v96
	v_exp_f32_e32 v107, v189
	v_add_f32_e32 v96, v182, v96
	v_add_f32_e32 v96, v104, v96
	v_add_f32_e32 v96, v105, v96
	v_add_f32_e32 v96, v106, v96
	v_add_f32_e32 v96, v107, v96
	v_add_f32_e32 v96, v108, v96
	v_add_f32_e32 v96, v109, v96
	v_add_f32_e32 v96, v110, v96
	v_add_f32_e32 v96, v111, v96
	v_add_f32_e32 v96, v114, v96
	v_add_f32_e32 v96, v115, v96
	v_cvt_pk_bf16_f32 v104, v104, v105
	v_cvt_pk_bf16_f32 v105, v106, v107
	v_cvt_pk_bf16_f32 v106, v108, v109
	v_cvt_pk_bf16_f32 v108, v114, v115
	v_max_f32_e32 v114, v81, v81
	v_max_f32_e32 v115, v80, v80
	v_max_f32_e32 v114, v115, v114
	v_max3_f32 v114, v114, v82, v83
	v_max3_f32 v114, v114, v84, v85
	v_max3_f32 v114, v114, v86, v87
	v_max3_f32 v114, v114, v88, v89
	v_max3_f32 v114, v114, v90, v91
	v_max3_f32 v114, v114, v92, v93
	v_max3_f32 v114, v114, v94, v95
	v_max3_f32 v114, v114, v64, v65
	v_max3_f32 v114, v114, v66, v67
	v_max3_f32 v114, v114, v68, v69
	v_max3_f32 v114, v114, v70, v71
	v_max3_f32 v114, v114, v72, v73
	v_max3_f32 v114, v114, v74, v75
	v_max3_f32 v114, v114, v76, v77
	v_max3_f32 v114, v114, v78, v79
	v_mov_b32_e32 v115, v114
	s_nop 1
	v_permlane32_swap_b32_e32 v114, v115
	v_max_f32_e32 v115, v115, v115
	v_max_f32_e32 v114, v114, v114
	v_max_f32_e32 v114, v114, v115
	v_sub_f32_e32 v115, v114, v147
	v_cmp_ge_f32_e32 vcc, s56, v115
	v_max_f32_e32 v115, v147, v147
	v_add_f32_e32 v96, v116, v96
	v_max_f32_e32 v115, v115, v114
	v_add_f32_e32 v96, v117, v96
	v_sub_f32_e32 v114, v147, v115
	v_add_f32_e32 v96, v118, v96
	v_mul_f32_e32 v114, 0x3dd53b94, v114
	v_add_f32_e32 v96, v119, v96
	v_exp_f32_e32 v114, v114
	v_add_f32_e32 v96, v120, v96
	v_add_f32_e32 v112, v121, v96
	s_cmp_eq_u64 vcc, exec
	v_mov_b32_e32 v113, v112
	s_cselect_b64 s[10:11], -1, 0
	s_nop 0
	v_permlane32_swap_b32_e32 v112, v113
	v_cndmask_b32_e64 v114, v114, 1.0, s[10:11]
	v_cvt_pk_bf16_f32 v96, v149, v151
	v_cvt_pk_bf16_f32 v97, v156, v157
	v_cvt_pk_bf16_f32 v98, v158, v159
	v_cvt_pk_bf16_f32 v99, v160, v161
	v_cvt_pk_bf16_f32 v107, v110, v111
	v_cvt_pk_bf16_f32 v109, v116, v117
	v_cvt_pk_bf16_f32 v110, v118, v119
	v_cvt_pk_bf16_f32 v111, v120, v121
	s_cmp_lg_u32 16, -1
	s_cselect_b32 s12, 16, 0
	s_add_i32 s12, s12, 0x8000
	v_add_u32_e32 v132, s12, v167
	ds_read_b64_tr_b16 v[116:117], v132 offset:0
	ds_read_b64_tr_b16 v[118:119], v132 offset:0x800
	ds_read_b64_tr_b16 v[120:121], v132 offset:0x1000
	ds_read_b64_tr_b16 v[122:123], v132 offset:0x1800
	ds_read_b64_tr_b16 v[124:125], v132 offset:0x2000
	ds_read_b64_tr_b16 v[126:127], v132 offset:0x2800
	ds_read_b64_tr_b16 v[128:129], v132 offset:0x3000
	ds_read_b64_tr_b16 v[130:131], v132 offset:0x3800
	s_waitcnt lgkmcnt(6)
; #define SBAR() __builtin_amdgcn_sched_barrier(0)
; #define RESC(a) do { if (__any((a) < 1.f)) { if (hi == 0) al_l[r32] = (a); asm volatile("s_waitcnt lgkmcnt(0)" ::: "memory"); \
;     _Pragma("unroll") for (int d = 0; d < 4; ++d) _Pragma("unroll") for (int r = 0; r < 16; ++r) o[d][r] *= al_l[crow(r, hi)]; } } while (0)
; #define QKT(P0, P1, KS) do { if constexpr (MI) qkt_mi<NQK>(P0, P1, KS, qr, r32, hi, minit); else qkt<NQK>(P0, P1, KS, qr, r32, hi); } while (0)
; #define DECIDE(P0, P1, MN, AL) do { if constexpr (MI) decide_mi(P0, P1, minit, Mref, AL, thr2, false); else decideSM(P0, P1, m_reg, MN, AL, C, thr); } while (0)
; #define PVSM(VB, P0, P1, MN) do { if constexpr (MI) pv_mi(o, VB, pa0, pa1, pa2, pa3, P0); else pv_sm(o, VB, pa0, pa1, pa2, pa3, P0, P1, C, MN); } while (0)
; template <int D0> __device__ __forceinline__ void pv_one_sm(f32x16& od, int vb, bf16x8 pa0, bf16x8 pa1, bf16x8 pa2, bf16x8 pa3, f32x16& q0, f32x16& q1, const float C, const float mnC) {
;   const s16x4 l0 = tr_read<v_rd_off(D0, 0, 0)>(vb), h0 = tr_read<v_rd_off(D0, 0, 1)>(vb), l1 = tr_read<v_rd_off(D0, 1, 0)>(vb), h1 = tr_read<v_rd_off(D0, 1, 1)>(vb);
;   const s16x4 l2 = tr_read<v_rd_off(D0, 2, 0)>(vb), h2 = tr_read<v_rd_off(D0, 2, 1)>(vb), l3 = tr_read<v_rd_off(D0, 3, 0)>(vb), h3 = tr_read<v_rd_off(D0, 3, 1)>(vb);
;   asm volatile("s_waitcnt lgkmcnt(0)" ::: "memory"); SBAR();
;     ...
;   od = __builtin_amdgcn_mfma_f32_32x32x16_bf16(pa0, PK(l0, h0), od, 0, 0, 0);
;   od = __builtin_amdgcn_mfma_f32_32x32x16_bf16(pa1, PK(l1, h1), od, 0, 0, 0);
;   od = __builtin_amdgcn_mfma_f32_32x32x16_bf16(pa2, PK(l2, h2), od, 0, 0, 0);
;   od = __builtin_amdgcn_mfma_f32_32x32x16_bf16(pa3, PK(l3, h3), od, 0, 0, 0);
;     ...
;   if (D0 < 2) {
; #pragma unroll
;     for (int r = 8 * D0; r < 8 * D0 + 8; ++r) q0[r] = __builtin_amdgcn_exp2f(fmaf(q0[r], C, mnC));
;   } else {
; #pragma unroll
;     for (int r = 8 * (D0 - 2); r < 8 * (D0 - 2) + 8; ++r) q1[r] = fmaf(q1[r], C, mnC);
;   }
; }
; template <int NQK, int SD, bool MI> ...
;     ...
;   SBAR(); QKT(pB0, pB1, K_lds + rc * KT);
;   finishSM(pA0, pA1, alA, l_reg, pa0, pa1, pa2, pa3); DECIDE(pB0, pB1, mnB, alB); SBAR();
;   PVSM(vb0 + rp * SHM_V, pB0, pB1, mnB);
;   RESC(alB);
	s_nop 0
	v_mfma_f32_32x32x16_bf16 v[0:15], v[96:99], v[116:119], v[0:15]
	ds_read_b64_tr_b16 v[116:117], v132 offset:0x200
	ds_read_b64_tr_b16 v[118:119], v132 offset:0xa00
	s_waitcnt lgkmcnt(6)
	v_mfma_f32_32x32x16_bf16 v[0:15], v[100:103], v[120:123], v[0:15]
	ds_read_b64_tr_b16 v[120:121], v132 offset:0x1200
	ds_read_b64_tr_b16 v[122:123], v132 offset:0x1a00
	s_waitcnt lgkmcnt(6)
	v_mfma_f32_32x32x16_bf16 v[0:15], v[104:107], v[124:127], v[0:15]
	ds_read_b64_tr_b16 v[124:125], v132 offset:0x2200
	ds_read_b64_tr_b16 v[126:127], v132 offset:0x2a00
	s_waitcnt lgkmcnt(6)
	v_mfma_f32_32x32x16_bf16 v[0:15], v[108:111], v[128:131], v[0:15]
	ds_read_b64_tr_b16 v[128:129], v132 offset:0x3200
	ds_read_b64_tr_b16 v[130:131], v132 offset:0x3a00
	s_waitcnt lgkmcnt(6)
	v_mfma_f32_32x32x16_bf16 v[16:31], v[96:99], v[116:119], v[16:31]
	ds_read_b64_tr_b16 v[116:117], v132 offset:0x400
	ds_read_b64_tr_b16 v[118:119], v132 offset:0xc00
	s_waitcnt lgkmcnt(6)
	v_mfma_f32_32x32x16_bf16 v[16:31], v[100:103], v[120:123], v[16:31]
	ds_read_b64_tr_b16 v[120:121], v132 offset:0x1400
	ds_read_b64_tr_b16 v[122:123], v132 offset:0x1c00
	s_waitcnt lgkmcnt(6)
	v_mfma_f32_32x32x16_bf16 v[16:31], v[104:107], v[124:127], v[16:31]
	ds_read_b64_tr_b16 v[124:125], v132 offset:0x2400
	ds_read_b64_tr_b16 v[126:127], v132 offset:0x2c00
	s_waitcnt lgkmcnt(6)
	v_mfma_f32_32x32x16_bf16 v[16:31], v[108:111], v[128:131], v[16:31]
	ds_read_b64_tr_b16 v[128:129], v132 offset:0x3400
	ds_read_b64_tr_b16 v[130:131], v132 offset:0x3c00
	s_waitcnt lgkmcnt(6)
	v_mfma_f32_32x32x16_bf16 v[32:47], v[96:99], v[116:119], v[32:47]
	ds_read_b64_tr_b16 v[116:117], v132 offset:0x600
	ds_read_b64_tr_b16 v[118:119], v132 offset:0xe00
	s_waitcnt lgkmcnt(6)
	v_mfma_f32_32x32x16_bf16 v[32:47], v[100:103], v[120:123], v[32:47]
	ds_read_b64_tr_b16 v[120:121], v132 offset:0x1600
	ds_read_b64_tr_b16 v[122:123], v132 offset:0x1e00
	s_waitcnt lgkmcnt(6)
	v_mfma_f32_32x32x16_bf16 v[32:47], v[104:107], v[124:127], v[32:47]
	ds_read_b64_tr_b16 v[124:125], v132 offset:0x2600
	ds_read_b64_tr_b16 v[126:127], v132 offset:0x2e00
	s_waitcnt lgkmcnt(6)
	v_mfma_f32_32x32x16_bf16 v[32:47], v[108:111], v[128:131], v[32:47]
	ds_read_b64_tr_b16 v[128:129], v132 offset:0x3600
	ds_read_b64_tr_b16 v[130:131], v132 offset:0x3e00
	s_waitcnt lgkmcnt(0)
	v_mfma_f32_32x32x16_bf16 v[48:63], v[96:99], v[116:119], v[48:63]
	v_cmp_gt_f32_e32 vcc, 1.0, v114
	v_mfma_f32_32x32x16_bf16 v[48:63], v[100:103], v[120:123], v[48:63]
	v_mfma_f32_32x32x16_bf16 v[48:63], v[104:107], v[124:127], v[48:63]
	v_mfma_f32_32x32x16_bf16 v[48:63], v[108:111], v[128:131], v[48:63]
	s_cbranch_vccz .LBB0_2532
	s_and_saveexec_b64 s[12:13], s[8:9]
	ds_write_b32 v168, v114 offset:128
	s_or_b64 exec, exec, s[12:13]
	s_waitcnt lgkmcnt(0)
	v_add_u32_e32 v108, v165, v162
	ds_read_b128 v[96:99], v108 offset:224
	ds_read_b128 v[100:103], v108 offset:192
	ds_read_b128 v[104:107], v108 offset:160
	ds_read_b128 v[108:111], v108 offset:128
	s_waitcnt lgkmcnt(3)
	v_pk_mul_f32 v[12:13], v[12:13], v[96:97]
	s_waitcnt lgkmcnt(2)
	v_pk_mul_f32 v[8:9], v[8:9], v[100:101]
	s_waitcnt lgkmcnt(1)
	v_pk_mul_f32 v[4:5], v[4:5], v[104:105]
	v_pk_mul_f32 v[14:15], v[14:15], v[98:99]
	v_pk_mul_f32 v[10:11], v[10:11], v[102:103]
	v_pk_mul_f32 v[6:7], v[6:7], v[106:107]
	s_waitcnt lgkmcnt(0)
	v_pk_mul_f32 v[2:3], v[2:3], v[110:111]
	v_pk_mul_f32 v[0:1], v[0:1], v[108:109]
	v_pk_mul_f32 v[28:29], v[28:29], v[96:97]
	v_pk_mul_f32 v[24:25], v[24:25], v[100:101]
	v_pk_mul_f32 v[20:21], v[20:21], v[104:105]
	v_pk_mul_f32 v[30:31], v[30:31], v[98:99]
	v_pk_mul_f32 v[26:27], v[26:27], v[102:103]
	v_pk_mul_f32 v[22:23], v[22:23], v[106:107]
	v_pk_mul_f32 v[18:19], v[18:19], v[110:111]
	v_pk_mul_f32 v[16:17], v[16:17], v[108:109]
	v_pk_mul_f32 v[44:45], v[44:45], v[96:97]
	v_pk_mul_f32 v[40:41], v[40:41], v[100:101]
	v_pk_mul_f32 v[36:37], v[36:37], v[104:105]
	v_pk_mul_f32 v[46:47], v[46:47], v[98:99]
	v_pk_mul_f32 v[42:43], v[42:43], v[102:103]
	v_pk_mul_f32 v[38:39], v[38:39], v[106:107]
	v_pk_mul_f32 v[34:35], v[34:35], v[110:111]
	v_pk_mul_f32 v[32:33], v[32:33], v[108:109]
	v_pk_mul_f32 v[60:61], v[60:61], v[96:97]
	v_pk_mul_f32 v[56:57], v[56:57], v[100:101]
	v_pk_mul_f32 v[52:53], v[52:53], v[104:105]
	v_pk_mul_f32 v[62:63], v[62:63], v[98:99]
	v_pk_mul_f32 v[58:59], v[58:59], v[102:103]
	v_pk_mul_f32 v[54:55], v[54:55], v[106:107]
	v_pk_mul_f32 v[50:51], v[50:51], v[110:111]
	v_pk_mul_f32 v[48:49], v[48:49], v[108:109]
; #define SBAR() __builtin_amdgcn_sched_barrier(0)
; #define PK4(P, BASE, OUT) do { u32x4 w = {cvtb(P[BASE + 0], P[BASE + 1]), cvtb(P[BASE + 2], P[BASE + 3]), \
;     cvtb(P[BASE + 4], P[BASE + 5]), cvtb(P[BASE + 6], P[BASE + 7])}; OUT = *reinterpret_cast<bf16x8*>(&w); } while (0)
; __device__ __forceinline__ void finishSM(f32x16& p0, f32x16& p1, float alpha, float& l_reg, bf16x8& pa0, bf16x8& pa1, bf16x8& pa2, bf16x8& pa3) {
; #pragma unroll
;   for (int r = 0; r < 16; ++r) p1[r] = __builtin_amdgcn_exp2f(p1[r]);
;   float ps = 0;
; #pragma unroll
;   for (int r = 0; r < 16; ++r) ps += p0[r];
; #pragma unroll
;   for (int r = 0; r < 16; ++r) ps += p1[r];
;   { auto rr = __builtin_amdgcn_permlane32_swap(__float_as_uint(ps), __float_as_uint(ps), false, false);
;     ps = __uint_as_float(rr[0]) + __uint_as_float(rr[1]); }
;   l_reg = l_reg * alpha + ps;
;     ...
;   PK4(p0, 0, pa0); PK4(p0, 8, pa1); PK4(p1, 0, pa2); PK4(p1, 8, pa3);
;     ...
; }
; template <int NQK, int SD, bool MI> ...
;     ...
;   finishSM(pB0, pB1, alB, l_reg, pa0, pa1, pa2, pa3); SBAR();
;   pv_d0(o, vb0 + rc * SHM_V, pa0, pa1, pa2, pa3);
;     ...
;   if (hi == 0) li_l[r32] = l_reg; asm volatile("s_waitcnt lgkmcnt(0)" ::: "memory");
.LBB0_2532:
	v_cndmask_b32_e64 v96, v115, v147, s[10:11]
	v_mul_f32_e32 v96, 0xbdd53b94, v96
	v_fmamk_f32 v80, v80, 0x3dd53b94, v96
	v_exp_f32_e32 v80, v80
	v_fmamk_f32 v81, v81, 0x3dd53b94, v96
	v_exp_f32_e32 v81, v81
	v_fmamk_f32 v82, v82, 0x3dd53b94, v96
	v_exp_f32_e32 v82, v82
	v_fmamk_f32 v83, v83, 0x3dd53b94, v96
	v_exp_f32_e32 v83, v83
	v_fmamk_f32 v84, v84, 0x3dd53b94, v96
	v_fmamk_f32 v64, v64, 0x3dd53b94, v96
	v_exp_f32_e32 v84, v84
	v_fmamk_f32 v85, v85, 0x3dd53b94, v96
	v_fmamk_f32 v86, v86, 0x3dd53b94, v96
	v_fmamk_f32 v87, v87, 0x3dd53b94, v96
	v_fmamk_f32 v88, v88, 0x3dd53b94, v96
	v_fmamk_f32 v89, v89, 0x3dd53b94, v96
	v_fmamk_f32 v90, v90, 0x3dd53b94, v96
	v_fmamk_f32 v91, v91, 0x3dd53b94, v96
	v_fmamk_f32 v92, v92, 0x3dd53b94, v96
	v_fmamk_f32 v93, v93, 0x3dd53b94, v96
	v_fmamk_f32 v94, v94, 0x3dd53b94, v96
	v_fmamk_f32 v95, v95, 0x3dd53b94, v96
	v_fmamk_f32 v65, v65, 0x3dd53b94, v96
	v_fmamk_f32 v66, v66, 0x3dd53b94, v96
	v_fmamk_f32 v67, v67, 0x3dd53b94, v96
	v_fmamk_f32 v68, v68, 0x3dd53b94, v96
	v_fmamk_f32 v69, v69, 0x3dd53b94, v96
	v_fmamk_f32 v70, v70, 0x3dd53b94, v96
	v_fmamk_f32 v71, v71, 0x3dd53b94, v96
	v_fmamk_f32 v72, v72, 0x3dd53b94, v96
	v_fmamk_f32 v73, v73, 0x3dd53b94, v96
	v_fmamk_f32 v74, v74, 0x3dd53b94, v96
	v_fmamk_f32 v75, v75, 0x3dd53b94, v96
	v_fmamk_f32 v76, v76, 0x3dd53b94, v96
	v_fmamk_f32 v77, v77, 0x3dd53b94, v96
	v_fmamk_f32 v78, v78, 0x3dd53b94, v96
	v_fmac_f32_e32 v96, 0x3dd53b94, v79
	v_exp_f32_e32 v79, v64
	v_add_f32_e32 v64, 0, v80
	v_exp_f32_e32 v85, v85
	v_add_f32_e32 v64, v81, v64
	v_exp_f32_e32 v86, v86
	v_add_f32_e32 v64, v82, v64
	v_exp_f32_e32 v87, v87
	v_add_f32_e32 v64, v83, v64
	v_exp_f32_e32 v88, v88
	v_add_f32_e32 v64, v84, v64
	v_exp_f32_e32 v89, v89
	v_add_f32_e32 v64, v85, v64
	v_exp_f32_e32 v90, v90
	v_add_f32_e32 v64, v86, v64
	v_exp_f32_e32 v91, v91
	v_add_f32_e32 v64, v87, v64
	v_exp_f32_e32 v92, v92
	v_add_f32_e32 v64, v88, v64
	v_exp_f32_e32 v93, v93
	v_add_f32_e32 v64, v89, v64
	v_exp_f32_e32 v94, v94
	v_add_f32_e32 v64, v90, v64
	v_exp_f32_e32 v95, v95
	v_add_f32_e32 v64, v91, v64
	v_add_f32_e32 v64, v92, v64
	v_exp_f32_e32 v97, v65
	v_add_f32_e32 v64, v93, v64
	v_exp_f32_e32 v98, v66
	v_add_f32_e32 v64, v94, v64
	v_exp_f32_e32 v99, v67
	v_add_f32_e32 v64, v95, v64
	v_exp_f32_e32 v100, v68
	v_add_f32_e32 v64, v79, v64
	v_exp_f32_e32 v101, v69
	v_add_f32_e32 v64, v97, v64
	v_exp_f32_e32 v102, v70
	v_add_f32_e32 v64, v98, v64
	v_exp_f32_e32 v103, v71
	v_add_f32_e32 v64, v99, v64
	v_exp_f32_e32 v104, v72
	v_add_f32_e32 v64, v100, v64
	v_exp_f32_e32 v105, v73
	v_add_f32_e32 v64, v101, v64
	v_exp_f32_e32 v106, v74
	v_add_f32_e32 v64, v102, v64
	v_exp_f32_e32 v107, v75
	v_add_f32_e32 v64, v103, v64
	v_exp_f32_e32 v108, v76
	v_add_f32_e32 v64, v104, v64
	v_exp_f32_e32 v109, v77
	v_add_f32_e32 v64, v105, v64
	v_exp_f32_e32 v110, v78
	v_add_f32_e32 v64, v106, v64
	v_exp_f32_e32 v96, v96
	v_add_f32_e32 v64, v107, v64
	v_add_f32_e32 v64, v108, v64
	v_add_f32_e32 v64, v109, v64
	v_add_f32_e32 v64, v110, v64
	v_add_f32_e32 v64, v96, v64
	v_mov_b32_e32 v65, v64
	s_nop 1
	v_permlane32_swap_b32_e32 v64, v65
	v_cvt_pk_bf16_f32 v66, v80, v81
	v_cvt_pk_bf16_f32 v67, v82, v83
	v_cvt_pk_bf16_f32 v68, v84, v85
	v_cvt_pk_bf16_f32 v69, v86, v87
	v_cvt_pk_bf16_f32 v70, v88, v89
	v_cvt_pk_bf16_f32 v71, v90, v91
	v_cvt_pk_bf16_f32 v72, v92, v93
	v_cvt_pk_bf16_f32 v73, v94, v95
	v_cvt_pk_bf16_f32 v74, v79, v97
	v_cvt_pk_bf16_f32 v75, v98, v99
	v_cvt_pk_bf16_f32 v76, v100, v101
	v_cvt_pk_bf16_f32 v77, v102, v103
	v_cvt_pk_bf16_f32 v78, v104, v105
	v_cvt_pk_bf16_f32 v79, v106, v107
	v_cvt_pk_bf16_f32 v80, v108, v109
	v_cvt_pk_bf16_f32 v81, v110, v96
	ds_read_b64_tr_b16 v[82:83], v166 offset:0
	ds_read_b64_tr_b16 v[84:85], v166 offset:0x800
	ds_read_b64_tr_b16 v[86:87], v166 offset:0x1000
	ds_read_b64_tr_b16 v[88:89], v166 offset:0x1800
	ds_read_b64_tr_b16 v[90:91], v166 offset:0x2000
	ds_read_b64_tr_b16 v[92:93], v166 offset:0x2800
	ds_read_b64_tr_b16 v[94:95], v166 offset:0x3000
	ds_read_b64_tr_b16 v[96:97], v166 offset:0x3800
	s_waitcnt lgkmcnt(6)
	s_nop 0
	v_mfma_f32_32x32x16_bf16 v[0:15], v[66:69], v[82:85], v[0:15]
	ds_read_b64_tr_b16 v[82:83], v166 offset:0x200
	ds_read_b64_tr_b16 v[84:85], v166 offset:0xa00
	s_waitcnt lgkmcnt(6)
	v_mfma_f32_32x32x16_bf16 v[0:15], v[70:73], v[86:89], v[0:15]
	ds_read_b64_tr_b16 v[86:87], v166 offset:0x1200
	ds_read_b64_tr_b16 v[88:89], v166 offset:0x1a00
	s_waitcnt lgkmcnt(6)
	v_mfma_f32_32x32x16_bf16 v[0:15], v[74:77], v[90:93], v[0:15]
	ds_read_b64_tr_b16 v[90:91], v166 offset:0x2200
	ds_read_b64_tr_b16 v[92:93], v166 offset:0x2a00
	s_waitcnt lgkmcnt(6)
	v_mfma_f32_32x32x16_bf16 v[0:15], v[78:81], v[94:97], v[0:15]
	ds_read_b64_tr_b16 v[94:95], v166 offset:0x3200
	ds_read_b64_tr_b16 v[96:97], v166 offset:0x3a00
	s_waitcnt lgkmcnt(6)
	v_mfma_f32_32x32x16_bf16 v[16:31], v[66:69], v[82:85], v[16:31]
	ds_read_b64_tr_b16 v[82:83], v166 offset:0x400
	ds_read_b64_tr_b16 v[84:85], v166 offset:0xc00
	s_waitcnt lgkmcnt(6)
	v_mfma_f32_32x32x16_bf16 v[16:31], v[70:73], v[86:89], v[16:31]
	ds_read_b64_tr_b16 v[86:87], v166 offset:0x1400
	ds_read_b64_tr_b16 v[88:89], v166 offset:0x1c00
	s_waitcnt lgkmcnt(6)
	v_mfma_f32_32x32x16_bf16 v[16:31], v[74:77], v[90:93], v[16:31]
	ds_read_b64_tr_b16 v[90:91], v166 offset:0x2400
	ds_read_b64_tr_b16 v[92:93], v166 offset:0x2c00
	s_waitcnt lgkmcnt(6)
	v_mfma_f32_32x32x16_bf16 v[16:31], v[78:81], v[94:97], v[16:31]
	ds_read_b64_tr_b16 v[94:95], v166 offset:0x3400
	ds_read_b64_tr_b16 v[96:97], v166 offset:0x3c00
	s_waitcnt lgkmcnt(6)
	v_mfma_f32_32x32x16_bf16 v[32:47], v[66:69], v[82:85], v[32:47]
	ds_read_b64_tr_b16 v[82:83], v166 offset:0x600
	ds_read_b64_tr_b16 v[84:85], v166 offset:0xe00
	s_waitcnt lgkmcnt(6)
	v_mfma_f32_32x32x16_bf16 v[32:47], v[70:73], v[86:89], v[32:47]
	ds_read_b64_tr_b16 v[86:87], v166 offset:0x1600
	ds_read_b64_tr_b16 v[88:89], v166 offset:0x1e00
	s_waitcnt lgkmcnt(6)
	v_mfma_f32_32x32x16_bf16 v[32:47], v[74:77], v[90:93], v[32:47]
	ds_read_b64_tr_b16 v[90:91], v166 offset:0x2600
	ds_read_b64_tr_b16 v[92:93], v166 offset:0x2e00
	s_waitcnt lgkmcnt(6)
	v_mfma_f32_32x32x16_bf16 v[32:47], v[78:81], v[94:97], v[32:47]
	ds_read_b64_tr_b16 v[94:95], v166 offset:0x3600
	ds_read_b64_tr_b16 v[96:97], v166 offset:0x3e00
	s_waitcnt lgkmcnt(0)
	v_mfma_f32_32x32x16_bf16 v[48:63], v[66:69], v[82:85], v[48:63]
	v_mfma_f32_32x32x16_bf16 v[48:63], v[70:73], v[86:89], v[48:63]
	v_mfma_f32_32x32x16_bf16 v[48:63], v[74:77], v[90:93], v[48:63]
	v_mfma_f32_32x32x16_bf16 v[48:63], v[78:81], v[94:97], v[48:63]
	s_and_saveexec_b64 s[10:11], s[8:9]
	s_cbranch_execz .LBB0_2534
	v_mul_f32_e32 v66, 0, v146
	v_cndmask_b32_e64 v66, v66, 0, s[6:7]
	v_add_f32_e32 v67, v170, v171
	v_add_f32_e32 v66, v66, v67
	v_add_f32_e32 v67, v178, v179
	v_fmac_f32_e32 v67, v66, v175
	v_add_f32_e32 v66, v112, v113
	v_fmac_f32_e32 v66, v67, v150
	v_add_f32_e32 v64, v64, v65
	v_fmac_f32_e32 v64, v66, v114
	ds_write_b32 v168, v64

; #define PK4(P, BASE, OUT) do { u32x4 w = {cvtb(P[BASE + 0], P[BASE + 1]), cvtb(P[BASE + 2], P[BASE + 3]), \
;     cvtb(P[BASE + 4], P[BASE + 5]), cvtb(P[BASE + 6], P[BASE + 7])}; OUT = *reinterpret_cast<bf16x8*>(&w); } while (0)
; __device__ __forceinline__ void finishSM(f32x16& p0, f32x16& p1, float alpha, float& l_reg, bf16x8& pa0, bf16x8& pa1, bf16x8& pa2, bf16x8& pa3) {
; #pragma unroll
;   for (int r = 0; r < 16; ++r) p1[r] = __builtin_amdgcn_exp2f(p1[r]);
;   float ps = 0;
; #pragma unroll
;   for (int r = 0; r < 16; ++r) ps += p0[r];
; #pragma unroll
;   for (int r = 0; r < 16; ++r) ps += p1[r];
;   { auto rr = __builtin_amdgcn_permlane32_swap(__float_as_uint(ps), __float_as_uint(ps), false, false);
;     ps = __uint_as_float(rr[0]) + __uint_as_float(rr[1]); }
;   l_reg = l_reg * alpha + ps;
;     ...
;   PK4(p0, 0, pa0); PK4(p0, 8, pa1); PK4(p1, 0, pa2); PK4(p1, 8, pa3);
;     ...
; }
; template <int NQK>
; __device__ __forceinline__ void qkt(f32x16& p0, f32x16& p1, const char* Ks, const bf16x8* qr, int r32, int hi) {
;   constexpr int KROW = NQK * 32 + 16;
;   p0 = f32x16{}; p1 = f32x16{};
; #pragma unroll
;   for (int d0 = 0; d0 < NQK; ++d0) { const int cb = (d0 * 16 + hi * 8) * 2;
;     bf16x8 b0 = *reinterpret_cast<const bf16x8*>(Ks + r32 * KROW + cb);
;     bf16x8 b1 = *reinterpret_cast<const bf16x8*>(Ks + (32 + r32) * KROW + cb);
;     p0 = __builtin_amdgcn_mfma_f32_32x32x16_bf16(b0, qr[d0], p0, 0, 0, 0);
;     p1 = __builtin_amdgcn_mfma_f32_32x32x16_bf16(b1, qr[d0], p1, 0, 0, 0); }
; }
.LBB0_2539:
	s_mov_b32 s14, s44
	s_mov_b32 s44, s8
	s_mul_i32 s8, s14, 0x6400
	v_add_u32_e32 v169, s8, v174
	ds_read_b128 v[64:67], v169 offset:61952
	ds_read_b128 v[68:71], v169 offset:49152
	ds_read_b128 v[180:183], v169 offset:49184
	ds_read_b128 v[222:225], v169 offset:61984
	v_exp_f32_e32 v231, v146
	v_add_f32_e32 v146, 0, v184
	s_waitcnt lgkmcnt(2)
	v_mfma_f32_32x32x16_bf16 v[80:95], v[68:71], v[140:143], 0
	v_add_f32_e32 v146, v185, v146
	v_add_f32_e32 v146, v189, v146
	v_add_f32_e32 v146, v191, v146
	v_add_f32_e32 v146, v198, v146
	v_add_f32_e32 v146, v200, v146
	v_add_f32_e32 v146, v214, v146
	v_add_f32_e32 v146, v217, v146
	v_mfma_f32_32x32x16_bf16 v[64:79], v[64:67], v[140:143], 0
	v_add_f32_e32 v146, v215, v146
	v_add_f32_e32 v146, v218, v146
	v_add_f32_e32 v146, v199, v146
	v_add_f32_e32 v146, v201, v146
	v_add_f32_e32 v146, v216, v146
	v_add_f32_e32 v146, v219, v146
	v_add_f32_e32 v146, v220, v146
	s_waitcnt lgkmcnt(1)
	v_mfma_f32_32x32x16_bf16 v[80:95], v[180:183], v[136:139], v[80:95]
	v_add_f32_e32 v146, v221, v146
	v_exp_f32_e32 v229, v150
	v_exp_f32_e32 v226, v155
	v_exp_f32_e32 v227, v152
	v_exp_f32_e32 v228, v153
	v_exp_f32_e32 v230, v151
	v_exp_f32_e32 v148, v148
	s_waitcnt lgkmcnt(0)
	v_mfma_f32_32x32x16_bf16 v[64:79], v[222:225], v[136:139], v[64:79]
	ds_read_b128 v[180:183], v169 offset:49216
	ds_read_b128 v[222:225], v169 offset:62016
	v_exp_f32_e32 v149, v149
	v_exp_f32_e32 v232, v147
	v_cvt_pk_bf16_f32 v155, v199, v201
	v_cvt_pk_bf16_f32 v147, v229, v230
	s_waitcnt lgkmcnt(1)
	v_mfma_f32_32x32x16_bf16 v[80:95], v[180:183], v[132:135], v[80:95]
	s_waitcnt lgkmcnt(0)
	v_mfma_f32_32x32x16_bf16 v[64:79], v[222:225], v[132:135], v[64:79]
	ds_read_b128 v[180:183], v169 offset:49248
	ds_read_b128 v[222:225], v169 offset:62048
	s_waitcnt lgkmcnt(1)
	v_mfma_f32_32x32x16_bf16 v[80:95], v[180:183], v[128:131], v[80:95]
	s_waitcnt lgkmcnt(0)
	v_mfma_f32_32x32x16_bf16 v[64:79], v[222:225], v[128:131], v[64:79]
	ds_read_b128 v[180:183], v169 offset:49280
	ds_read_b128 v[222:225], v169 offset:62080
	s_waitcnt lgkmcnt(1)
	v_mfma_f32_32x32x16_bf16 v[80:95], v[180:183], v[124:127], v[80:95]
	s_waitcnt lgkmcnt(0)
	v_mfma_f32_32x32x16_bf16 v[64:79], v[222:225], v[124:127], v[64:79]
	ds_read_b128 v[180:183], v169 offset:49312
	ds_read_b128 v[222:225], v169 offset:62112
	s_waitcnt lgkmcnt(1)
	v_mfma_f32_32x32x16_bf16 v[80:95], v[180:183], v[120:123], v[80:95]
	s_waitcnt lgkmcnt(0)
	v_mfma_f32_32x32x16_bf16 v[64:79], v[222:225], v[120:123], v[64:79]
	ds_read_b128 v[180:183], v169 offset:49344
	ds_read_b128 v[222:225], v169 offset:62144
	s_waitcnt lgkmcnt(1)
	v_mfma_f32_32x32x16_bf16 v[80:95], v[180:183], v[116:119], v[80:95]
	s_waitcnt lgkmcnt(0)
	v_mfma_f32_32x32x16_bf16 v[64:79], v[222:225], v[116:119], v[64:79]
	ds_read_b128 v[180:183], v169 offset:49376
	ds_read_b128 v[222:225], v169 offset:62176
	s_waitcnt lgkmcnt(1)
	v_mfma_f32_32x32x16_bf16 v[80:95], v[180:183], v[112:115], v[80:95]
	s_waitcnt lgkmcnt(0)
	v_mfma_f32_32x32x16_bf16 v[64:79], v[222:225], v[112:115], v[64:79]
	ds_read_b128 v[180:183], v169 offset:49408
	ds_read_b128 v[222:225], v169 offset:62208
	s_waitcnt lgkmcnt(1)
	v_mfma_f32_32x32x16_bf16 v[80:95], v[180:183], v[108:111], v[80:95]
	s_waitcnt lgkmcnt(0)
	v_mfma_f32_32x32x16_bf16 v[64:79], v[222:225], v[108:111], v[64:79]
	ds_read_b128 v[180:183], v169 offset:49440
	ds_read_b128 v[222:225], v169 offset:62240
	s_waitcnt lgkmcnt(1)
	v_mfma_f32_32x32x16_bf16 v[80:95], v[180:183], v[104:107], v[80:95]
	s_waitcnt lgkmcnt(0)
	v_mfma_f32_32x32x16_bf16 v[64:79], v[222:225], v[104:107], v[64:79]
	ds_read_b128 v[180:183], v169 offset:49472
	ds_read_b128 v[222:225], v169 offset:62272
	s_waitcnt lgkmcnt(1)
	v_mfma_f32_32x32x16_bf16 v[80:95], v[180:183], v[100:103], v[80:95]
	s_waitcnt lgkmcnt(0)
	v_mfma_f32_32x32x16_bf16 v[64:79], v[222:225], v[100:103], v[64:79]
	ds_read_b128 v[180:183], v169 offset:49504
	ds_read_b128 v[222:225], v169 offset:62304
	v_exp_f32_e32 v169, v160
	v_cvt_pk_bf16_f32 v160, v198, v200
	v_add_f32_e32 v146, v169, v146
	s_waitcnt lgkmcnt(1)
	v_mfma_f32_32x32x16_bf16 v[80:95], v[180:183], v[96:99], v[80:95]
	v_exp_f32_e32 v180, v161
	v_exp_f32_e32 v183, v158
	v_cvt_pk_bf16_f32 v158, v184, v185
	v_cvt_pk_bf16_f32 v161, v214, v217
	v_add_f32_e32 v146, v180, v146
	v_cvt_pk_bf16_f32 v150, v169, v180
	v_add_f32_e32 v146, v183, v146
	s_nop 4
	v_max_f32_e32 v169, v81, v81
	v_max_f32_e32 v180, v80, v80
	s_waitcnt lgkmcnt(0)
; #define SBAR() __builtin_amdgcn_sched_barrier(0)
; #define SWRITE(b, i) do { STG_T() const int _sv = VSTV(), _sk = LDSK(); *(u32x4*)(V_lds + (b) * SHM_V + _sv) = sr_[i].vs0; *(u32x4*)(V_lds + (b) * SHM_V + _sv + 8192) = sr_[i].vs1; \
;     _Pragma("unroll") for (int _p = 0; _p < NP; ++_p) *(u32x4*)(K_lds + (b) * KT + _sk + _p * 128) = sr_[i].ks[_p]; } while (0)
; #define SWAIT() do { if constexpr (SD == 2) { if constexpr (NP == 1) asm volatile("s_waitcnt vmcnt(3)" ::: "memory"); else asm volatile("s_waitcnt vmcnt(5)" ::: "memory"); } else asm volatile("s_waitcnt vmcnt(0)" ::: "memory"); } while (0)
; #define QKT(P0, P1, KS) do { if constexpr (MI) qkt_mi<NQK>(P0, P1, KS, qr, r32, hi, minit); else qkt<NQK>(P0, P1, KS, qr, r32, hi); } while (0)
; #define ROT() do { const int _r = rp; rp = rc; rc = rn; rn = _r; } while (0)
; template <int D0> __device__ __forceinline__ void pv_one_sm(f32x16& od, int vb, bf16x8 pa0, bf16x8 pa1, bf16x8 pa2, bf16x8 pa3, f32x16& q0, f32x16& q1, const float C, const float mnC) {
;   const s16x4 l0 = tr_read<v_rd_off(D0, 0, 0)>(vb), h0 = tr_read<v_rd_off(D0, 0, 1)>(vb), l1 = tr_read<v_rd_off(D0, 1, 0)>(vb), h1 = tr_read<v_rd_off(D0, 1, 1)>(vb);
;   const s16x4 l2 = tr_read<v_rd_off(D0, 2, 0)>(vb), h2 = tr_read<v_rd_off(D0, 2, 1)>(vb), l3 = tr_read<v_rd_off(D0, 3, 0)>(vb), h3 = tr_read<v_rd_off(D0, 3, 1)>(vb);
;   asm volatile("s_waitcnt lgkmcnt(0)" ::: "memory"); SBAR();
;     ...
;   od = __builtin_amdgcn_mfma_f32_32x32x16_bf16(pa0, PK(l0, h0), od, 0, 0, 0);
;   od = __builtin_amdgcn_mfma_f32_32x32x16_bf16(pa1, PK(l1, h1), od, 0, 0, 0);
;   od = __builtin_amdgcn_mfma_f32_32x32x16_bf16(pa2, PK(l2, h2), od, 0, 0, 0);
;   od = __builtin_amdgcn_mfma_f32_32x32x16_bf16(pa3, PK(l3, h3), od, 0, 0, 0);
;     ...
;   if (D0 < 2) {
; #pragma unroll
;     for (int r = 8 * D0; r < 8 * D0 + 8; ++r) q0[r] = __builtin_amdgcn_exp2f(fmaf(q0[r], C, mnC));
;   } else {
; #pragma unroll
;     for (int r = 8 * (D0 - 2); r < 8 * (D0 - 2) + 8; ++r) q1[r] = fmaf(q1[r], C, mnC);
;   }
; }
; template <int NQK, int SD, bool MI> ...
;     ...
;   for (int j = 1; j + 1 < NT; j += 2) {
;     SBAR(); QKT(pB0, pB1, K_lds + rc * KT);
;     finishSM(pA0, pA1, alA, l_reg, pa0, pa1, pa2, pa3); DECIDE(pB0, pB1, mnB, alB); SBAR();
;     SLOAD(SO, (j + SD) * 64); SBAR();
;     PVSM(vb0 + rp * SHM_V, pB0, pB1, mnB);
;     SWAIT(); SWRITE(rn, SE);
;     RESC(alB); __syncthreads(); ROT();
	v_mfma_f32_32x32x16_bf16 v[64:79], v[222:225], v[96:99], v[64:79]
	v_max_f32_e32 v169, v180, v169
	v_max3_f32 v169, v169, v82, v83
	v_max3_f32 v169, v169, v84, v85
	v_max3_f32 v169, v169, v86, v87
	v_max3_f32 v169, v169, v88, v89
	v_max3_f32 v169, v169, v90, v91
	v_exp_f32_e32 v222, v159
	v_max3_f32 v169, v169, v92, v93
	v_exp_f32_e32 v223, v156
	v_max3_f32 v169, v169, v94, v95
	v_exp_f32_e32 v224, v157
	s_nop 0
	v_max3_f32 v169, v169, v64, v65
	v_exp_f32_e32 v225, v154
	v_max3_f32 v169, v169, v66, v67
	v_add_f32_e32 v146, v222, v146
	v_max3_f32 v169, v169, v68, v69
	v_add_f32_e32 v146, v223, v146
	v_max3_f32 v169, v169, v70, v71
	v_add_f32_e32 v146, v224, v146
	v_max3_f32 v169, v169, v72, v73
	v_add_f32_e32 v146, v225, v146
	v_max3_f32 v169, v169, v74, v75
	v_add_f32_e32 v146, v226, v146
	v_max3_f32 v169, v169, v76, v77
	v_add_f32_e32 v146, v227, v146
	v_max3_f32 v169, v169, v78, v79
	v_add_f32_e32 v146, v228, v146
	v_mov_b32_e32 v180, v169
	v_add_f32_e32 v146, v229, v146
	s_nop 0
	v_permlane32_swap_b32_e32 v169, v180
	v_add_f32_e32 v146, v230, v146
	v_max_f32_e32 v180, v180, v180
	v_max_f32_e32 v169, v169, v169
	v_add_f32_e32 v146, v148, v146
	v_max_f32_e32 v169, v169, v180
	v_add_f32_e32 v146, v149, v146
	v_sub_f32_e32 v180, v169, v178
	v_add_f32_e32 v146, v231, v146
	v_cmp_ge_f32_e32 vcc, s56, v180
	v_max_f32_e32 v180, v178, v178
	v_add_f32_e32 v181, v232, v146
	v_max_f32_e32 v180, v180, v169
	v_mov_b32_e32 v182, v181
	s_cmp_eq_u64 vcc, exec
	v_sub_f32_e32 v169, v178, v180
	v_permlane32_swap_b32_e32 v181, v182
	s_cselect_b64 s[8:9], -1, 0
	v_mul_f32_e32 v169, 0x3dd53b94, v169
	v_cvt_pk_bf16_f32 v159, v189, v191
	v_cvt_pk_bf16_f32 v154, v215, v218
	v_cvt_pk_bf16_f32 v156, v216, v219
	v_cvt_pk_bf16_f32 v157, v220, v221
	v_cvt_pk_bf16_f32 v151, v183, v222
	v_cvt_pk_bf16_f32 v152, v223, v224
	v_cvt_pk_bf16_f32 v153, v225, v226
	v_cvt_pk_bf16_f32 v146, v227, v228
	v_cvt_pk_bf16_f32 v148, v148, v149
	v_cvt_pk_bf16_f32 v149, v231, v232
	s_add_i32 s10, s13, 0xfffe8000
	s_mov_b32 s38, s30
	s_mov_b32 s39, s31
	s_add_i32 s11, s13, 0xffff0000
	buffer_load_dwordx4 v[198:201], v170, s[28:31], s10 offen
	buffer_load_dwordx4 v[214:217], v170, s[28:31], s11 offen
	buffer_load_dwordx4 v[218:221], v171, s[36:39], s12 offen
	buffer_load_dwordx4 v[222:225], v176, s[36:39], s12 offen
	buffer_load_dwordx4 v[226:229], v177, s[36:39], s12 offen
	v_exp_f32_e32 v183, v169
	s_lshl_b32 s16, s44, 14
	v_add_u32_e32 v169, s16, v168
	ds_read_b64_tr_b16 v[230:231], v169 offset:0
	ds_read_b64_tr_b16 v[232:233], v169 offset:0x800
	ds_read_b64_tr_b16 v[234:235], v169 offset:0x1000
	ds_read_b64_tr_b16 v[236:237], v169 offset:0x1800
	ds_read_b64_tr_b16 v[238:239], v169 offset:0x2000
	ds_read_b64_tr_b16 v[240:241], v169 offset:0x2800
	ds_read_b64_tr_b16 v[242:243], v169 offset:0x3000
	ds_read_b64_tr_b16 v[244:245], v169 offset:0x3800
	s_waitcnt lgkmcnt(6)
	s_nop 0
	v_mfma_f32_32x32x16_bf16 v[0:15], v[158:161], v[230:233], v[0:15]
	ds_read_b64_tr_b16 v[230:231], v169 offset:0x200
	ds_read_b64_tr_b16 v[232:233], v169 offset:0xa00
	s_waitcnt lgkmcnt(6)
	v_mfma_f32_32x32x16_bf16 v[0:15], v[154:157], v[234:237], v[0:15]
	ds_read_b64_tr_b16 v[234:235], v169 offset:0x1200
	ds_read_b64_tr_b16 v[236:237], v169 offset:0x1a00
	s_waitcnt lgkmcnt(6)
	v_mfma_f32_32x32x16_bf16 v[0:15], v[150:153], v[238:241], v[0:15]
	ds_read_b64_tr_b16 v[238:239], v169 offset:0x2200
	ds_read_b64_tr_b16 v[240:241], v169 offset:0x2a00
	s_waitcnt lgkmcnt(6)
	v_mfma_f32_32x32x16_bf16 v[0:15], v[146:149], v[242:245], v[0:15]
	ds_read_b64_tr_b16 v[242:243], v169 offset:0x3200
	ds_read_b64_tr_b16 v[244:245], v169 offset:0x3a00
	s_waitcnt lgkmcnt(6)
	v_mfma_f32_32x32x16_bf16 v[48:63], v[158:161], v[230:233], v[48:63]
	ds_read_b64_tr_b16 v[230:231], v169 offset:0x400
	ds_read_b64_tr_b16 v[232:233], v169 offset:0xc00
	s_waitcnt lgkmcnt(6)
	v_mfma_f32_32x32x16_bf16 v[48:63], v[154:157], v[234:237], v[48:63]
	ds_read_b64_tr_b16 v[234:235], v169 offset:0x1400
	ds_read_b64_tr_b16 v[236:237], v169 offset:0x1c00
	s_waitcnt lgkmcnt(6)
	v_mfma_f32_32x32x16_bf16 v[48:63], v[150:153], v[238:241], v[48:63]
	ds_read_b64_tr_b16 v[238:239], v169 offset:0x2400
	ds_read_b64_tr_b16 v[240:241], v169 offset:0x2c00
	s_waitcnt lgkmcnt(6)
	v_mfma_f32_32x32x16_bf16 v[48:63], v[146:149], v[242:245], v[48:63]
	ds_read_b64_tr_b16 v[242:243], v169 offset:0x3400
	ds_read_b64_tr_b16 v[244:245], v169 offset:0x3c00
	s_waitcnt lgkmcnt(6)
	v_mfma_f32_32x32x16_bf16 v[32:47], v[158:161], v[230:233], v[32:47]
	ds_read_b64_tr_b16 v[230:231], v169 offset:0x600
	ds_read_b64_tr_b16 v[232:233], v169 offset:0xe00
	s_waitcnt lgkmcnt(6)
	v_mfma_f32_32x32x16_bf16 v[32:47], v[154:157], v[234:237], v[32:47]
	ds_read_b64_tr_b16 v[234:235], v169 offset:0x1600
	ds_read_b64_tr_b16 v[236:237], v169 offset:0x1e00
	s_waitcnt lgkmcnt(6)
	v_mfma_f32_32x32x16_bf16 v[32:47], v[150:153], v[238:241], v[32:47]
	ds_read_b64_tr_b16 v[238:239], v169 offset:0x2600
	ds_read_b64_tr_b16 v[240:241], v169 offset:0x2e00
	s_waitcnt lgkmcnt(6)
	v_mfma_f32_32x32x16_bf16 v[32:47], v[146:149], v[242:245], v[32:47]
	ds_read_b64_tr_b16 v[242:243], v169 offset:0x3600
	ds_read_b64_tr_b16 v[244:245], v169 offset:0x3e00
	s_waitcnt lgkmcnt(0)
	v_mfma_f32_32x32x16_bf16 v[16:31], v[158:161], v[230:233], v[16:31]
	s_waitcnt vmcnt(0)
	s_lshl_b32 s15, s51, 14
	s_mul_i32 s17, s51, 0x6400
	v_cndmask_b32_e64 v183, v183, 1.0, s[8:9]
	v_cmp_gt_f32_e32 vcc, 1.0, v183
	v_mfma_f32_32x32x16_bf16 v[16:31], v[154:157], v[234:237], v[16:31]
	v_add_u32_e32 v154, s15, v175
	s_waitcnt vmcnt(4)
	ds_write_b128 v154, v[198:201]
	s_waitcnt vmcnt(3)
	ds_write_b128 v154, v[214:217] offset:8192
	v_mfma_f32_32x32x16_bf16 v[16:31], v[150:153], v[238:241], v[16:31]
	v_add_u32_e32 v150, s17, v173
	s_waitcnt vmcnt(2)
	ds_write_b128 v150, v[218:221] offset:49152
	s_waitcnt vmcnt(1)
	ds_write_b128 v150, v[222:225] offset:49280
	s_waitcnt vmcnt(0)
	ds_write_b128 v150, v[226:229] offset:49408
	v_mfma_f32_32x32x16_bf16 v[16:31], v[146:149], v[242:245], v[16:31]
	s_cbranch_vccz .LBB0_2543
; template <int NQK>
; __device__ __forceinline__ void qkt(f32x16& p0, f32x16& p1, const char* Ks, const bf16x8* qr, int r32, int hi) {
;   constexpr int KROW = NQK * 32 + 16;
;   p0 = f32x16{}; p1 = f32x16{};
; #pragma unroll
;   for (int d0 = 0; d0 < NQK; ++d0) { const int cb = (d0 * 16 + hi * 8) * 2;
;     bf16x8 b0 = *reinterpret_cast<const bf16x8*>(Ks + r32 * KROW + cb);
;     bf16x8 b1 = *reinterpret_cast<const bf16x8*>(Ks + (32 + r32) * KROW + cb);
;     p0 = __builtin_amdgcn_mfma_f32_32x32x16_bf16(b0, qr[d0], p0, 0, 0, 0);
;     p1 = __builtin_amdgcn_mfma_f32_32x32x16_bf16(b1, qr[d0], p1, 0, 0, 0); }
; }
; template <int D0> __device__ __forceinline__ void pv_one_sm(f32x16& od, int vb, bf16x8 pa0, bf16x8 pa1, bf16x8 pa2, bf16x8 pa3, f32x16& q0, f32x16& q1, const float C, const float mnC) {
;     ...
;   if (D0 < 2) {
; #pragma unroll
;     for (int r = 8 * D0; r < 8 * D0 + 8; ++r) q0[r] = __builtin_amdgcn_exp2f(fmaf(q0[r], C, mnC));
;   } else {
; #pragma unroll
;     for (int r = 8 * (D0 - 2); r < 8 * (D0 - 2) + 8; ++r) q1[r] = fmaf(q1[r], C, mnC);
;   }
; }
	s_and_saveexec_b64 s[10:11], s[6:7]
	ds_write_b32 v166, v183 offset:128
	s_or_b64 exec, exec, s[10:11]
	s_waitcnt lgkmcnt(0)
	v_add_u32_e32 v158, v165, v162
	ds_read_b128 v[146:149], v158 offset:224
	ds_read_b128 v[150:153], v158 offset:192
	ds_read_b128 v[154:157], v158 offset:160
	ds_read_b128 v[158:161], v158 offset:128
	s_waitcnt lgkmcnt(3)
	v_pk_mul_f32 v[12:13], v[12:13], v[146:147]
	s_waitcnt lgkmcnt(2)
	v_pk_mul_f32 v[8:9], v[8:9], v[150:151]
	s_waitcnt lgkmcnt(1)
	v_pk_mul_f32 v[4:5], v[4:5], v[154:155]
	v_pk_mul_f32 v[14:15], v[14:15], v[148:149]
	v_pk_mul_f32 v[10:11], v[10:11], v[152:153]
	v_pk_mul_f32 v[6:7], v[6:7], v[156:157]
	s_waitcnt lgkmcnt(0)
	v_pk_mul_f32 v[2:3], v[2:3], v[160:161]
	v_pk_mul_f32 v[0:1], v[0:1], v[158:159]
	v_pk_mul_f32 v[60:61], v[60:61], v[146:147]
	v_pk_mul_f32 v[56:57], v[56:57], v[150:151]
	v_pk_mul_f32 v[52:53], v[52:53], v[154:155]
	v_pk_mul_f32 v[62:63], v[62:63], v[148:149]
	v_pk_mul_f32 v[58:59], v[58:59], v[152:153]
	v_pk_mul_f32 v[54:55], v[54:55], v[156:157]
	v_pk_mul_f32 v[50:51], v[50:51], v[160:161]
	v_pk_mul_f32 v[48:49], v[48:49], v[158:159]
	v_pk_mul_f32 v[44:45], v[44:45], v[146:147]
	v_pk_mul_f32 v[40:41], v[40:41], v[150:151]
	v_pk_mul_f32 v[36:37], v[36:37], v[154:155]
	v_pk_mul_f32 v[46:47], v[46:47], v[148:149]
	v_pk_mul_f32 v[42:43], v[42:43], v[152:153]
	v_pk_mul_f32 v[38:39], v[38:39], v[156:157]
	v_pk_mul_f32 v[34:35], v[34:35], v[160:161]
	v_pk_mul_f32 v[32:33], v[32:33], v[158:159]
	v_pk_mul_f32 v[28:29], v[28:29], v[146:147]
	v_pk_mul_f32 v[24:25], v[24:25], v[150:151]
	v_pk_mul_f32 v[20:21], v[20:21], v[154:155]
	v_pk_mul_f32 v[30:31], v[30:31], v[148:149]
	v_pk_mul_f32 v[26:27], v[26:27], v[152:153]
	v_pk_mul_f32 v[22:23], v[22:23], v[156:157]
	v_pk_mul_f32 v[18:19], v[18:19], v[160:161]
	v_pk_mul_f32 v[16:17], v[16:17], v[158:159]
.LBB0_2543:
	v_cndmask_b32_e64 v178, v180, v178, s[8:9]
	v_mul_f32_e32 v154, 0xbdd53b94, v178
	v_fmamk_f32 v80, v80, 0x3dd53b94, v154
	v_exp_f32_e32 v155, v80
	v_fmamk_f32 v80, v81, 0x3dd53b94, v154
	v_exp_f32_e32 v156, v80
	v_fmamk_f32 v80, v82, 0x3dd53b94, v154
	v_exp_f32_e32 v157, v80
	v_fmamk_f32 v80, v83, 0x3dd53b94, v154
	v_exp_f32_e32 v159, v80
	v_fmamk_f32 v80, v84, 0x3dd53b94, v154
	v_exp_f32_e32 v160, v80
	v_fmamk_f32 v80, v85, 0x3dd53b94, v154
	v_exp_f32_e32 v161, v80
	v_fmamk_f32 v80, v86, 0x3dd53b94, v154
	v_exp_f32_e32 v180, v80
	v_fmamk_f32 v80, v87, 0x3dd53b94, v154
	v_exp_f32_e32 v189, v80
	v_fmamk_f32 v80, v88, 0x3dd53b94, v154
	v_exp_f32_e32 v191, v80
	v_fmamk_f32 v80, v89, 0x3dd53b94, v154
	v_exp_f32_e32 v198, v80
	v_fmamk_f32 v80, v90, 0x3dd53b94, v154
	v_exp_f32_e32 v199, v80
	v_fmamk_f32 v80, v91, 0x3dd53b94, v154
	v_exp_f32_e32 v200, v80
	v_fmamk_f32 v80, v92, 0x3dd53b94, v154
	v_exp_f32_e32 v201, v80
	v_fmamk_f32 v80, v93, 0x3dd53b94, v154
	v_exp_f32_e32 v214, v80
	v_fmamk_f32 v80, v94, 0x3dd53b94, v154
	v_exp_f32_e32 v215, v80
	v_fmamk_f32 v80, v95, 0x3dd53b94, v154
	v_fmamk_f32 v184, v66, 0x3dd53b94, v154
	v_fmamk_f32 v185, v68, 0x3dd53b94, v154
	v_exp_f32_e32 v216, v80
	v_fmamk_f32 v158, v64, 0x3dd53b94, v154
	v_fmamk_f32 v217, v70, 0x3dd53b94, v154
	v_fmamk_f32 v218, v65, 0x3dd53b94, v154
	v_fmamk_f32 v219, v67, 0x3dd53b94, v154
	v_fmamk_f32 v220, v69, 0x3dd53b94, v154
	v_fmamk_f32 v221, v71, 0x3dd53b94, v154
	v_fmamk_f32 v222, v72, 0x3dd53b94, v154
	v_fmamk_f32 v223, v73, 0x3dd53b94, v154
	v_fmamk_f32 v224, v74, 0x3dd53b94, v154
	v_fmamk_f32 v225, v75, 0x3dd53b94, v154
	v_fmamk_f32 v226, v76, 0x3dd53b94, v154
	v_fmamk_f32 v227, v77, 0x3dd53b94, v154
	v_fmamk_f32 v228, v78, 0x3dd53b94, v154
	v_fmac_f32_e32 v154, 0x3dd53b94, v79
	s_waitcnt lgkmcnt(0)
	s_barrier
	v_add_u32_e32 v229, s17, v174
	ds_read_b128 v[64:67], v229 offset:61952
	ds_read_b128 v[68:71], v229 offset:49152
	ds_read_b128 v[146:149], v229 offset:49184
	ds_read_b128 v[150:153], v229 offset:61984
	v_exp_f32_e32 v217, v217
	s_waitcnt lgkmcnt(2)
	v_mfma_f32_32x32x16_bf16 v[80:95], v[68:71], v[140:143], 0
	v_mfma_f32_32x32x16_bf16 v[64:79], v[64:67], v[140:143], 0
	s_waitcnt lgkmcnt(1)
	v_mfma_f32_32x32x16_bf16 v[80:95], v[146:149], v[136:139], v[80:95]
	s_waitcnt lgkmcnt(0)
	v_mfma_f32_32x32x16_bf16 v[64:79], v[150:153], v[136:139], v[64:79]
	ds_read_b128 v[146:149], v229 offset:49216
	ds_read_b128 v[150:153], v229 offset:62016
	s_waitcnt lgkmcnt(1)
	v_mfma_f32_32x32x16_bf16 v[80:95], v[146:149], v[132:135], v[80:95]
	s_waitcnt lgkmcnt(0)
	v_mfma_f32_32x32x16_bf16 v[64:79], v[150:153], v[132:135], v[64:79]
	ds_read_b128 v[146:149], v229 offset:49248
	ds_read_b128 v[150:153], v229 offset:62048
	s_waitcnt lgkmcnt(1)
	v_mfma_f32_32x32x16_bf16 v[80:95], v[146:149], v[128:131], v[80:95]
	s_waitcnt lgkmcnt(0)
	v_mfma_f32_32x32x16_bf16 v[64:79], v[150:153], v[128:131], v[64:79]
	ds_read_b128 v[146:149], v229 offset:49280
	ds_read_b128 v[150:153], v229 offset:62080
	s_waitcnt lgkmcnt(1)
	v_mfma_f32_32x32x16_bf16 v[80:95], v[146:149], v[124:127], v[80:95]
	s_waitcnt lgkmcnt(0)
	v_mfma_f32_32x32x16_bf16 v[64:79], v[150:153], v[124:127], v[64:79]
	ds_read_b128 v[146:149], v229 offset:49312
	ds_read_b128 v[150:153], v229 offset:62112
	s_waitcnt lgkmcnt(1)
	v_mfma_f32_32x32x16_bf16 v[80:95], v[146:149], v[120:123], v[80:95]
	s_waitcnt lgkmcnt(0)
	v_mfma_f32_32x32x16_bf16 v[64:79], v[150:153], v[120:123], v[64:79]
	ds_read_b128 v[146:149], v229 offset:49344
	ds_read_b128 v[150:153], v229 offset:62144
	s_waitcnt lgkmcnt(1)
	v_mfma_f32_32x32x16_bf16 v[80:95], v[146:149], v[116:119], v[80:95]
	s_waitcnt lgkmcnt(0)
	v_mfma_f32_32x32x16_bf16 v[64:79], v[150:153], v[116:119], v[64:79]
	ds_read_b128 v[146:149], v229 offset:49376
	ds_read_b128 v[150:153], v229 offset:62176
	s_waitcnt lgkmcnt(1)
; #define SBAR() __builtin_amdgcn_sched_barrier(0)
; #define PK4(P, BASE, OUT) do { u32x4 w = {cvtb(P[BASE + 0], P[BASE + 1]), cvtb(P[BASE + 2], P[BASE + 3]), \
;     cvtb(P[BASE + 4], P[BASE + 5]), cvtb(P[BASE + 6], P[BASE + 7])}; OUT = *reinterpret_cast<bf16x8*>(&w); } while (0)
; #define QKT(P0, P1, KS) do { if constexpr (MI) qkt_mi<NQK>(P0, P1, KS, qr, r32, hi, minit); else qkt<NQK>(P0, P1, KS, qr, r32, hi); } while (0)
; #define DECIDE(P0, P1, MN, AL) do { if constexpr (MI) decide_mi(P0, P1, minit, Mref, AL, thr2, false); else decideSM(P0, P1, m_reg, MN, AL, C, thr); } while (0)
; __device__ __forceinline__ void decideSM(const f32x16& p0, const f32x16& p1, float& m_reg, float& mn, float& alpha, const float C, const float thr) {
;   float pmax = p0[0];
; #pragma unroll
;   for (int r = 1; r < 16; ++r) pmax = fmaxf(pmax, p0[r]);
; #pragma unroll
;   for (int r = 0; r < 16; ++r) pmax = fmaxf(pmax, p1[r]);
;   { auto rr = __builtin_amdgcn_permlane32_swap(__float_as_uint(pmax), __float_as_uint(pmax), false, false);
;     pmax = fmaxf(__uint_as_float(rr[0]), __uint_as_float(rr[1])); }
;   if (__builtin_expect(__all(pmax - m_reg <= thr), 1)) { mn = m_reg; alpha = 1.f; }
;   else { mn = fmaxf(m_reg, pmax); alpha = __builtin_amdgcn_exp2f((m_reg - mn) * C); m_reg = mn; }
; }
; __device__ __forceinline__ void finishSM(f32x16& p0, f32x16& p1, float alpha, float& l_reg, bf16x8& pa0, bf16x8& pa1, bf16x8& pa2, bf16x8& pa3) {
; #pragma unroll
;   for (int r = 0; r < 16; ++r) p1[r] = __builtin_amdgcn_exp2f(p1[r]);
;   float ps = 0;
; #pragma unroll
;   for (int r = 0; r < 16; ++r) ps += p0[r];
; #pragma unroll
;   for (int r = 0; r < 16; ++r) ps += p1[r];
;   { auto rr = __builtin_amdgcn_permlane32_swap(__float_as_uint(ps), __float_as_uint(ps), false, false);
;     ps = __uint_as_float(rr[0]) + __uint_as_float(rr[1]); }
;   l_reg = l_reg * alpha + ps;
;     ...
;   PK4(p0, 0, pa0); PK4(p0, 8, pa1); PK4(p1, 0, pa2); PK4(p1, 8, pa3);
;     ...
; }
; template <int NQK, int SD, bool MI> ...
;     ...
;     SBAR(); QKT(pA0, pA1, K_lds + rc * KT);
;     finishSM(pB0, pB1, alB, l_reg, pa0, pa1, pa2, pa3); DECIDE(pA0, pA1, mnA, alA); SBAR();
;     if (SD == 1 || j + 3 < NT) SLOAD(SE, (j + 1 + SD) * 64); SBAR();
;     PVSM(vb0 + rp * SHM_V, pA0, pA1, mnA);
	v_mfma_f32_32x32x16_bf16 v[80:95], v[146:149], v[112:115], v[80:95]
	s_waitcnt lgkmcnt(0)
	v_mfma_f32_32x32x16_bf16 v[64:79], v[150:153], v[112:115], v[64:79]
	ds_read_b128 v[146:149], v229 offset:49408
	ds_read_b128 v[150:153], v229 offset:62208
	s_waitcnt lgkmcnt(1)
	v_mfma_f32_32x32x16_bf16 v[80:95], v[146:149], v[108:111], v[80:95]
	s_waitcnt lgkmcnt(0)
	v_mfma_f32_32x32x16_bf16 v[64:79], v[150:153], v[108:111], v[64:79]
	ds_read_b128 v[146:149], v229 offset:49440
	ds_read_b128 v[150:153], v229 offset:62240
	s_waitcnt lgkmcnt(1)
	v_mfma_f32_32x32x16_bf16 v[80:95], v[146:149], v[104:107], v[80:95]
	s_waitcnt lgkmcnt(0)
	v_mfma_f32_32x32x16_bf16 v[64:79], v[150:153], v[104:107], v[64:79]
	ds_read_b128 v[146:149], v229 offset:49472
	ds_read_b128 v[150:153], v229 offset:62272
	s_waitcnt lgkmcnt(1)
	v_mfma_f32_32x32x16_bf16 v[80:95], v[146:149], v[100:103], v[80:95]
	s_waitcnt lgkmcnt(0)
	v_mfma_f32_32x32x16_bf16 v[64:79], v[150:153], v[100:103], v[64:79]
	ds_read_b128 v[146:149], v229 offset:49504
	ds_read_b128 v[150:153], v229 offset:62304
	s_waitcnt lgkmcnt(1)
	v_mfma_f32_32x32x16_bf16 v[80:95], v[146:149], v[96:99], v[80:95]
	v_exp_f32_e32 v146, v158
	v_exp_f32_e32 v147, v218
	v_exp_f32_e32 v148, v184
	v_exp_f32_e32 v149, v219
	v_exp_f32_e32 v218, v221
	v_exp_f32_e32 v219, v222
	v_exp_f32_e32 v221, v224
	s_waitcnt lgkmcnt(0)
	v_mfma_f32_32x32x16_bf16 v[64:79], v[150:153], v[96:99], v[64:79]
	v_add_f32_e32 v150, 0, v155
	v_add_f32_e32 v150, v156, v150
	v_add_f32_e32 v150, v157, v150
	v_add_f32_e32 v150, v159, v150
	v_add_f32_e32 v150, v160, v150
	v_add_f32_e32 v150, v161, v150
	v_add_f32_e32 v150, v180, v150
	v_add_f32_e32 v150, v189, v150
	v_add_f32_e32 v150, v191, v150
	v_cvt_pk_bf16_f32 v160, v160, v161
	v_cvt_pk_bf16_f32 v161, v180, v189
	v_max_f32_e32 v180, v81, v81
	v_max_f32_e32 v189, v80, v80
	v_add_f32_e32 v150, v198, v150
	v_max_f32_e32 v180, v189, v180
	v_add_f32_e32 v150, v199, v150
	v_max3_f32 v180, v180, v82, v83
	v_add_f32_e32 v150, v200, v150
	v_max3_f32 v180, v180, v84, v85
	v_add_f32_e32 v150, v201, v150
	v_max3_f32 v180, v180, v86, v87
	v_add_f32_e32 v150, v214, v150
	v_max3_f32 v180, v180, v88, v89
	v_add_f32_e32 v150, v215, v150
	v_max3_f32 v180, v180, v90, v91
	v_add_f32_e32 v150, v216, v150
	v_max3_f32 v180, v180, v92, v93
	v_exp_f32_e32 v152, v185
	v_add_f32_e32 v150, v146, v150
	v_max3_f32 v180, v180, v94, v95
	v_exp_f32_e32 v153, v220
	v_add_f32_e32 v150, v147, v150
	v_max3_f32 v180, v180, v64, v65
	v_add_f32_e32 v150, v148, v150
	v_max3_f32 v180, v180, v66, v67
	v_add_f32_e32 v150, v149, v150
	v_max3_f32 v180, v180, v68, v69
	v_add_f32_e32 v150, v152, v150
	v_max3_f32 v180, v180, v70, v71
	v_exp_f32_e32 v220, v223
	v_add_f32_e32 v150, v153, v150
	v_max3_f32 v180, v180, v72, v73
	v_add_f32_e32 v150, v217, v150
	v_max3_f32 v180, v180, v74, v75
	v_exp_f32_e32 v222, v225
	v_add_f32_e32 v150, v218, v150
	v_max3_f32 v180, v180, v76, v77
	v_exp_f32_e32 v223, v226
	v_add_f32_e32 v150, v219, v150
	v_max3_f32 v180, v180, v78, v79
	v_exp_f32_e32 v224, v227
	v_add_f32_e32 v150, v220, v150
	v_mov_b32_e32 v189, v180
	v_exp_f32_e32 v225, v228
	v_add_f32_e32 v150, v221, v150
	v_permlane32_swap_b32_e32 v180, v189
	v_exp_f32_e32 v226, v154
	v_add_f32_e32 v150, v222, v150
	v_max_f32_e32 v189, v189, v189
	v_max_f32_e32 v180, v180, v180
	v_add_f32_e32 v150, v223, v150
	v_max_f32_e32 v180, v180, v189
	v_add_f32_e32 v150, v224, v150
	v_sub_f32_e32 v189, v180, v178
	v_add_f32_e32 v150, v225, v150
	v_cmp_ge_f32_e32 vcc, s56, v189
	v_max_f32_e32 v189, v178, v178
	v_add_f32_e32 v184, v226, v150
	v_max_f32_e32 v189, v189, v180
	v_mov_b32_e32 v185, v184
	s_cmp_eq_u64 vcc, exec
	v_sub_f32_e32 v180, v178, v189
	v_permlane32_swap_b32_e32 v184, v185
	s_cselect_b64 s[8:9], -1, 0
	v_mul_f32_e32 v180, 0x3dd53b94, v180
	v_cvt_pk_bf16_f32 v158, v155, v156
	v_cvt_pk_bf16_f32 v159, v157, v159
	v_cvt_pk_bf16_f32 v154, v191, v198
	v_cvt_pk_bf16_f32 v155, v199, v200
	v_cvt_pk_bf16_f32 v156, v201, v214
	v_cvt_pk_bf16_f32 v157, v215, v216
	v_cvt_pk_bf16_f32 v150, v146, v147
	v_cvt_pk_bf16_f32 v151, v148, v149
	v_cvt_pk_bf16_f32 v152, v152, v153
	v_cvt_pk_bf16_f32 v153, v217, v218
	v_cvt_pk_bf16_f32 v146, v219, v220
	v_cvt_pk_bf16_f32 v147, v221, v222
	v_cvt_pk_bf16_f32 v148, v223, v224
	v_cvt_pk_bf16_f32 v149, v225, v226
	s_add_i32 s10, s13, 0xffff8000
	s_add_i32 s11, s12, 0x18000
	s_mov_b32 s38, s30
	s_mov_b32 s39, s31
	buffer_load_dwordx4 v[198:201], v170, s[28:31], s10 offen
	buffer_load_dwordx4 v[214:217], v170, s[28:31], s13 offen
	buffer_load_dwordx4 v[218:221], v171, s[36:39], s11 offen
	buffer_load_dwordx4 v[222:225], v176, s[36:39], s11 offen
	buffer_load_dwordx4 v[226:229], v177, s[36:39], s11 offen
	v_exp_f32_e32 v180, v180
	v_lshl_add_u32 v191, s14, 14, v168
	ds_read_b64_tr_b16 v[230:231], v191 offset:0
	ds_read_b64_tr_b16 v[232:233], v191 offset:0x800
	ds_read_b64_tr_b16 v[234:235], v191 offset:0x1000
	ds_read_b64_tr_b16 v[236:237], v191 offset:0x1800
	ds_read_b64_tr_b16 v[238:239], v191 offset:0x2000
	ds_read_b64_tr_b16 v[240:241], v191 offset:0x2800
	ds_read_b64_tr_b16 v[242:243], v191 offset:0x3000
	ds_read_b64_tr_b16 v[244:245], v191 offset:0x3800
	s_waitcnt lgkmcnt(6)
; #define SBAR() __builtin_amdgcn_sched_barrier(0)
; #define SWRITE(b, i) do { STG_T() const int _sv = VSTV(), _sk = LDSK(); *(u32x4*)(V_lds + (b) * SHM_V + _sv) = sr_[i].vs0; *(u32x4*)(V_lds + (b) * SHM_V + _sv + 8192) = sr_[i].vs1; \
;     _Pragma("unroll") for (int _p = 0; _p < NP; ++_p) *(u32x4*)(K_lds + (b) * KT + _sk + _p * 128) = sr_[i].ks[_p]; } while (0)
; #define SWAIT() do { if constexpr (SD == 2) { if constexpr (NP == 1) asm volatile("s_waitcnt vmcnt(3)" ::: "memory"); else asm volatile("s_waitcnt vmcnt(5)" ::: "memory"); } else asm volatile("s_waitcnt vmcnt(0)" ::: "memory"); } while (0)
; #define RESC(a) do { if (__any((a) < 1.f)) { if (hi == 0) al_l[r32] = (a); asm volatile("s_waitcnt lgkmcnt(0)" ::: "memory"); \
;     _Pragma("unroll") for (int d = 0; d < 4; ++d) _Pragma("unroll") for (int r = 0; r < 16; ++r) o[d][r] *= al_l[crow(r, hi)]; } } while (0)
; #define PVSM(VB, P0, P1, MN) do { if constexpr (MI) pv_mi(o, VB, pa0, pa1, pa2, pa3, P0); else pv_sm(o, VB, pa0, pa1, pa2, pa3, P0, P1, C, MN); } while (0)
; template <int D0> __device__ __forceinline__ void pv_one_sm(f32x16& od, int vb, bf16x8 pa0, bf16x8 pa1, bf16x8 pa2, bf16x8 pa3, f32x16& q0, f32x16& q1, const float C, const float mnC) {
;   const s16x4 l0 = tr_read<v_rd_off(D0, 0, 0)>(vb), h0 = tr_read<v_rd_off(D0, 0, 1)>(vb), l1 = tr_read<v_rd_off(D0, 1, 0)>(vb), h1 = tr_read<v_rd_off(D0, 1, 1)>(vb);
;   const s16x4 l2 = tr_read<v_rd_off(D0, 2, 0)>(vb), h2 = tr_read<v_rd_off(D0, 2, 1)>(vb), l3 = tr_read<v_rd_off(D0, 3, 0)>(vb), h3 = tr_read<v_rd_off(D0, 3, 1)>(vb);
;   asm volatile("s_waitcnt lgkmcnt(0)" ::: "memory"); SBAR();
;     ...
;   od = __builtin_amdgcn_mfma_f32_32x32x16_bf16(pa0, PK(l0, h0), od, 0, 0, 0);
;   od = __builtin_amdgcn_mfma_f32_32x32x16_bf16(pa1, PK(l1, h1), od, 0, 0, 0);
;   od = __builtin_amdgcn_mfma_f32_32x32x16_bf16(pa2, PK(l2, h2), od, 0, 0, 0);
;   od = __builtin_amdgcn_mfma_f32_32x32x16_bf16(pa3, PK(l3, h3), od, 0, 0, 0);
;     ...
;   if (D0 < 2) {
; #pragma unroll
;     for (int r = 8 * D0; r < 8 * D0 + 8; ++r) q0[r] = __builtin_amdgcn_exp2f(fmaf(q0[r], C, mnC));
;   } else {
; #pragma unroll
;     for (int r = 8 * (D0 - 2); r < 8 * (D0 - 2) + 8; ++r) q1[r] = fmaf(q1[r], C, mnC);
;   }
; }
; template <int NQK, int SD, bool MI> ...
;     ...
;     PVSM(vb0 + rp * SHM_V, pA0, pA1, mnA);
;     SWAIT(); SWRITE(rn, SO);
;     RESC(alA); __syncthreads(); ROT();
	s_nop 0
	v_mfma_f32_32x32x16_bf16 v[0:15], v[158:161], v[230:233], v[0:15]
	ds_read_b64_tr_b16 v[230:231], v191 offset:0x200
	ds_read_b64_tr_b16 v[232:233], v191 offset:0xa00
	s_waitcnt lgkmcnt(6)
	v_mfma_f32_32x32x16_bf16 v[0:15], v[154:157], v[234:237], v[0:15]
	ds_read_b64_tr_b16 v[234:235], v191 offset:0x1200
	ds_read_b64_tr_b16 v[236:237], v191 offset:0x1a00
	s_waitcnt lgkmcnt(6)
	v_mfma_f32_32x32x16_bf16 v[0:15], v[150:153], v[238:241], v[0:15]
	ds_read_b64_tr_b16 v[238:239], v191 offset:0x2200
	ds_read_b64_tr_b16 v[240:241], v191 offset:0x2a00
	s_waitcnt lgkmcnt(6)
	v_mfma_f32_32x32x16_bf16 v[0:15], v[146:149], v[242:245], v[0:15]
	ds_read_b64_tr_b16 v[242:243], v191 offset:0x3200
	ds_read_b64_tr_b16 v[244:245], v191 offset:0x3a00
	s_waitcnt lgkmcnt(6)
	v_mfma_f32_32x32x16_bf16 v[48:63], v[158:161], v[230:233], v[48:63]
	ds_read_b64_tr_b16 v[230:231], v191 offset:0x400
	ds_read_b64_tr_b16 v[232:233], v191 offset:0xc00
	s_waitcnt lgkmcnt(6)
	v_mfma_f32_32x32x16_bf16 v[48:63], v[154:157], v[234:237], v[48:63]
	ds_read_b64_tr_b16 v[234:235], v191 offset:0x1400
	ds_read_b64_tr_b16 v[236:237], v191 offset:0x1c00
	s_waitcnt lgkmcnt(6)
	v_mfma_f32_32x32x16_bf16 v[48:63], v[150:153], v[238:241], v[48:63]
	ds_read_b64_tr_b16 v[238:239], v191 offset:0x2400
	ds_read_b64_tr_b16 v[240:241], v191 offset:0x2c00
	s_waitcnt lgkmcnt(6)
	v_mfma_f32_32x32x16_bf16 v[48:63], v[146:149], v[242:245], v[48:63]
	ds_read_b64_tr_b16 v[242:243], v191 offset:0x3400
	ds_read_b64_tr_b16 v[244:245], v191 offset:0x3c00
	s_waitcnt lgkmcnt(6)
	v_mfma_f32_32x32x16_bf16 v[32:47], v[158:161], v[230:233], v[32:47]
	ds_read_b64_tr_b16 v[230:231], v191 offset:0x600
	ds_read_b64_tr_b16 v[232:233], v191 offset:0xe00
	s_waitcnt lgkmcnt(6)
	v_mfma_f32_32x32x16_bf16 v[32:47], v[154:157], v[234:237], v[32:47]
	ds_read_b64_tr_b16 v[234:235], v191 offset:0x1600
	ds_read_b64_tr_b16 v[236:237], v191 offset:0x1e00
	s_waitcnt lgkmcnt(6)
	v_mfma_f32_32x32x16_bf16 v[32:47], v[150:153], v[238:241], v[32:47]
	ds_read_b64_tr_b16 v[238:239], v191 offset:0x2600
	ds_read_b64_tr_b16 v[240:241], v191 offset:0x2e00
	s_waitcnt lgkmcnt(6)
	v_mfma_f32_32x32x16_bf16 v[32:47], v[146:149], v[242:245], v[32:47]
	ds_read_b64_tr_b16 v[242:243], v191 offset:0x3600
	ds_read_b64_tr_b16 v[244:245], v191 offset:0x3e00
	s_waitcnt lgkmcnt(0)
	v_mfma_f32_32x32x16_bf16 v[16:31], v[158:161], v[230:233], v[16:31]
	s_waitcnt vmcnt(0)
	v_cndmask_b32_e64 v180, v180, 1.0, s[8:9]
	v_cmp_gt_f32_e32 vcc, 1.0, v180
	v_mfma_f32_32x32x16_bf16 v[16:31], v[154:157], v[234:237], v[16:31]
	v_add_u32_e32 v154, s16, v175
	s_mul_i32 s16, s44, 0x6400
	s_waitcnt vmcnt(4)
	ds_write_b128 v154, v[198:201]
	s_waitcnt vmcnt(3)
	ds_write_b128 v154, v[214:217] offset:8192
	v_mfma_f32_32x32x16_bf16 v[16:31], v[150:153], v[238:241], v[16:31]
	v_add_u32_e32 v150, s16, v173
	s_waitcnt vmcnt(2)
	ds_write_b128 v150, v[218:221] offset:49152
	s_waitcnt vmcnt(1)
	ds_write_b128 v150, v[222:225] offset:49280
	s_waitcnt vmcnt(0)
	ds_write_b128 v150, v[226:229] offset:49408
	v_mfma_f32_32x32x16_bf16 v[16:31], v[146:149], v[242:245], v[16:31]
	s_cbranch_vccz .LBB0_2547
	s_and_saveexec_b64 s[10:11], s[6:7]
	ds_write_b32 v166, v180 offset:128
	s_or_b64 exec, exec, s[10:11]
	s_waitcnt lgkmcnt(0)
	v_add_u32_e32 v158, v165, v162
	ds_read_b128 v[146:149], v158 offset:224
	ds_read_b128 v[150:153], v158 offset:192
	ds_read_b128 v[154:157], v158 offset:160
	ds_read_b128 v[158:161], v158 offset:128
	s_waitcnt lgkmcnt(3)
	v_pk_mul_f32 v[12:13], v[12:13], v[146:147]
	s_waitcnt lgkmcnt(2)
	v_pk_mul_f32 v[8:9], v[8:9], v[150:151]
	s_waitcnt lgkmcnt(1)
	v_pk_mul_f32 v[4:5], v[4:5], v[154:155]
	v_pk_mul_f32 v[14:15], v[14:15], v[148:149]
	v_pk_mul_f32 v[10:11], v[10:11], v[152:153]
	v_pk_mul_f32 v[6:7], v[6:7], v[156:157]
	s_waitcnt lgkmcnt(0)
	v_pk_mul_f32 v[2:3], v[2:3], v[160:161]
	v_pk_mul_f32 v[0:1], v[0:1], v[158:159]
	v_pk_mul_f32 v[60:61], v[60:61], v[146:147]
	v_pk_mul_f32 v[56:57], v[56:57], v[150:151]
	v_pk_mul_f32 v[52:53], v[52:53], v[154:155]
	v_pk_mul_f32 v[62:63], v[62:63], v[148:149]
	v_pk_mul_f32 v[58:59], v[58:59], v[152:153]
	v_pk_mul_f32 v[54:55], v[54:55], v[156:157]
	v_pk_mul_f32 v[50:51], v[50:51], v[160:161]
	v_pk_mul_f32 v[48:49], v[48:49], v[158:159]
	v_pk_mul_f32 v[44:45], v[44:45], v[146:147]
	v_pk_mul_f32 v[40:41], v[40:41], v[150:151]
	v_pk_mul_f32 v[36:37], v[36:37], v[154:155]
	v_pk_mul_f32 v[46:47], v[46:47], v[148:149]
	v_pk_mul_f32 v[42:43], v[42:43], v[152:153]
	v_pk_mul_f32 v[38:39], v[38:39], v[156:157]
	v_pk_mul_f32 v[34:35], v[34:35], v[160:161]
	v_pk_mul_f32 v[32:33], v[32:33], v[158:159]
	v_pk_mul_f32 v[28:29], v[28:29], v[146:147]
	v_pk_mul_f32 v[24:25], v[24:25], v[150:151]
	v_pk_mul_f32 v[20:21], v[20:21], v[154:155]
	v_pk_mul_f32 v[30:31], v[30:31], v[148:149]
	v_pk_mul_f32 v[26:27], v[26:27], v[152:153]
	v_pk_mul_f32 v[22:23], v[22:23], v[156:157]
	v_pk_mul_f32 v[18:19], v[18:19], v[160:161]
	v_pk_mul_f32 v[16:17], v[16:17], v[158:159]

; #define PK4(P, BASE, OUT) do { u32x4 w = {cvtb(P[BASE + 0], P[BASE + 1]), cvtb(P[BASE + 2], P[BASE + 3]), \
;     cvtb(P[BASE + 4], P[BASE + 5]), cvtb(P[BASE + 6], P[BASE + 7])}; OUT = *reinterpret_cast<bf16x8*>(&w); } while (0)
; __device__ __forceinline__ void decideSM(const f32x16& p0, const f32x16& p1, float& m_reg, float& mn, float& alpha, const float C, const float thr) {
;   float pmax = p0[0];
; #pragma unroll
;   for (int r = 1; r < 16; ++r) pmax = fmaxf(pmax, p0[r]);
; #pragma unroll
;   for (int r = 0; r < 16; ++r) pmax = fmaxf(pmax, p1[r]);
;   { auto rr = __builtin_amdgcn_permlane32_swap(__float_as_uint(pmax), __float_as_uint(pmax), false, false);
;     pmax = fmaxf(__uint_as_float(rr[0]), __uint_as_float(rr[1])); }
;   if (__builtin_expect(__all(pmax - m_reg <= thr), 1)) { mn = m_reg; alpha = 1.f; }
;   else { mn = fmaxf(m_reg, pmax); alpha = __builtin_amdgcn_exp2f((m_reg - mn) * C); m_reg = mn; }
; }
; __device__ __forceinline__ void finishSM(f32x16& p0, f32x16& p1, float alpha, float& l_reg, bf16x8& pa0, bf16x8& pa1, bf16x8& pa2, bf16x8& pa3) {
; #pragma unroll
;   for (int r = 0; r < 16; ++r) p1[r] = __builtin_amdgcn_exp2f(p1[r]);
;   float ps = 0;
; #pragma unroll
;   for (int r = 0; r < 16; ++r) ps += p0[r];
; #pragma unroll
;   for (int r = 0; r < 16; ++r) ps += p1[r];
;   { auto rr = __builtin_amdgcn_permlane32_swap(__float_as_uint(ps), __float_as_uint(ps), false, false);
;     ps = __uint_as_float(rr[0]) + __uint_as_float(rr[1]); }
;   l_reg = l_reg * alpha + ps;
;     ...
;   PK4(p0, 0, pa0); PK4(p0, 8, pa1); PK4(p1, 0, pa2); PK4(p1, 8, pa3);
;     ...
; }
; template <int NQK>
; __device__ __forceinline__ void qkt(f32x16& p0, f32x16& p1, const char* Ks, const bf16x8* qr, int r32, int hi) {
;   constexpr int KROW = NQK * 32 + 16;
;   p0 = f32x16{}; p1 = f32x16{};
; #pragma unroll
;   for (int d0 = 0; d0 < NQK; ++d0) { const int cb = (d0 * 16 + hi * 8) * 2;
;     bf16x8 b0 = *reinterpret_cast<const bf16x8*>(Ks + r32 * KROW + cb);
;     bf16x8 b1 = *reinterpret_cast<const bf16x8*>(Ks + (32 + r32) * KROW + cb);
;     p0 = __builtin_amdgcn_mfma_f32_32x32x16_bf16(b0, qr[d0], p0, 0, 0, 0);
;     p1 = __builtin_amdgcn_mfma_f32_32x32x16_bf16(b1, qr[d0], p1, 0, 0, 0); }
; }
.LBB0_2549:
	s_add_i32 s8, s16, 16
	v_add3_u32 v174, s8, v172, v162
	ds_read_b128 v[64:67], v174 offset:61952
	ds_read_b128 v[68:71], v174 offset:49152
	ds_read_b128 v[170:173], v174 offset:49184
	s_waitcnt lgkmcnt(1)
	v_mfma_f32_32x32x16_bf16 v[80:95], v[68:71], v[140:143], 0
	v_mfma_f32_32x32x16_bf16 v[64:79], v[64:67], v[140:143], 0
	ds_read_b128 v[140:143], v174 offset:61984
	s_waitcnt lgkmcnt(1)
	v_mfma_f32_32x32x16_bf16 v[80:95], v[170:173], v[136:139], v[80:95]
	s_waitcnt lgkmcnt(0)
	v_mfma_f32_32x32x16_bf16 v[64:79], v[140:143], v[136:139], v[64:79]
	ds_read_b128 v[136:139], v174 offset:49216
	ds_read_b128 v[140:143], v174 offset:62016
	s_waitcnt lgkmcnt(1)
	v_mfma_f32_32x32x16_bf16 v[80:95], v[136:139], v[132:135], v[80:95]
	s_waitcnt lgkmcnt(0)
	v_mfma_f32_32x32x16_bf16 v[64:79], v[140:143], v[132:135], v[64:79]
	ds_read_b128 v[132:135], v174 offset:49248
	ds_read_b128 v[136:139], v174 offset:62048
	s_waitcnt lgkmcnt(1)
	v_mfma_f32_32x32x16_bf16 v[80:95], v[132:135], v[128:131], v[80:95]
	s_waitcnt lgkmcnt(0)
	v_mfma_f32_32x32x16_bf16 v[64:79], v[136:139], v[128:131], v[64:79]
	ds_read_b128 v[128:131], v174 offset:49280
	ds_read_b128 v[132:135], v174 offset:62080
	s_waitcnt lgkmcnt(1)
	v_mfma_f32_32x32x16_bf16 v[80:95], v[128:131], v[124:127], v[80:95]
	s_waitcnt lgkmcnt(0)
	v_mfma_f32_32x32x16_bf16 v[64:79], v[132:135], v[124:127], v[64:79]
	ds_read_b128 v[124:127], v174 offset:49312
	ds_read_b128 v[128:131], v174 offset:62112
	s_waitcnt lgkmcnt(1)
	v_mfma_f32_32x32x16_bf16 v[80:95], v[124:127], v[120:123], v[80:95]
	s_waitcnt lgkmcnt(0)
	v_mfma_f32_32x32x16_bf16 v[64:79], v[128:131], v[120:123], v[64:79]
	ds_read_b128 v[120:123], v174 offset:49344
	ds_read_b128 v[124:127], v174 offset:62144
	s_waitcnt lgkmcnt(1)
	v_mfma_f32_32x32x16_bf16 v[80:95], v[120:123], v[116:119], v[80:95]
	s_waitcnt lgkmcnt(0)
	v_mfma_f32_32x32x16_bf16 v[64:79], v[124:127], v[116:119], v[64:79]
	ds_read_b128 v[116:119], v174 offset:49376
	ds_read_b128 v[120:123], v174 offset:62176
	s_waitcnt lgkmcnt(1)
	v_mfma_f32_32x32x16_bf16 v[80:95], v[116:119], v[112:115], v[80:95]
	s_waitcnt lgkmcnt(0)
	v_mfma_f32_32x32x16_bf16 v[64:79], v[120:123], v[112:115], v[64:79]
	ds_read_b128 v[112:115], v174 offset:49408
	ds_read_b128 v[116:119], v174 offset:62208
	v_exp_f32_e32 v120, v146
	v_exp_f32_e32 v121, v147
	s_waitcnt lgkmcnt(1)
	v_mfma_f32_32x32x16_bf16 v[80:95], v[112:115], v[108:111], v[80:95]
	s_waitcnt lgkmcnt(0)
	v_mfma_f32_32x32x16_bf16 v[64:79], v[116:119], v[108:111], v[64:79]
	ds_read_b128 v[108:111], v174 offset:49440
	ds_read_b128 v[112:115], v174 offset:62240
	v_exp_f32_e32 v116, v150
	v_exp_f32_e32 v117, v151
	v_exp_f32_e32 v118, v148
	v_exp_f32_e32 v119, v149
	s_waitcnt lgkmcnt(1)
	v_mfma_f32_32x32x16_bf16 v[80:95], v[108:111], v[104:107], v[80:95]
	s_waitcnt lgkmcnt(0)
	v_mfma_f32_32x32x16_bf16 v[64:79], v[112:115], v[104:107], v[64:79]
	ds_read_b128 v[104:107], v174 offset:49472
	ds_read_b128 v[108:111], v174 offset:62272
	v_exp_f32_e32 v114, v152
	v_exp_f32_e32 v115, v153
	s_waitcnt lgkmcnt(1)
	v_mfma_f32_32x32x16_bf16 v[80:95], v[104:107], v[100:103], v[80:95]
	s_waitcnt lgkmcnt(0)
	v_mfma_f32_32x32x16_bf16 v[64:79], v[108:111], v[100:103], v[64:79]
	ds_read_b128 v[100:103], v174 offset:49504
	ds_read_b128 v[104:107], v174 offset:62304
	v_exp_f32_e32 v108, v156
	v_exp_f32_e32 v109, v157
	v_exp_f32_e32 v110, v154
	v_exp_f32_e32 v111, v155
	s_waitcnt lgkmcnt(1)
	v_mfma_f32_32x32x16_bf16 v[80:95], v[100:103], v[96:99], v[80:95]
	v_cvt_pk_bf16_f32 v100, v215, v218
	v_cvt_pk_bf16_f32 v101, v199, v201
	v_cvt_pk_bf16_f32 v102, v216, v219
	v_cvt_pk_bf16_f32 v103, v220, v221
	s_waitcnt lgkmcnt(0)
	v_mfma_f32_32x32x16_bf16 v[64:79], v[104:107], v[96:99], v[64:79]
	v_add_f32_e32 v96, 0, v184
	v_add_f32_e32 v96, v185, v96
	v_add_f32_e32 v96, v189, v96
	v_add_f32_e32 v96, v191, v96
	v_add_f32_e32 v96, v198, v96
	v_add_f32_e32 v96, v200, v96
	v_add_f32_e32 v96, v214, v96
	v_add_f32_e32 v96, v217, v96
	v_add_f32_e32 v96, v215, v96
	v_add_f32_e32 v96, v218, v96
	v_add_f32_e32 v96, v199, v96
	v_add_f32_e32 v96, v201, v96
	v_exp_f32_e32 v104, v160
	v_add_f32_e32 v96, v216, v96
	v_exp_f32_e32 v105, v161
	v_add_f32_e32 v96, v219, v96
	v_exp_f32_e32 v106, v158
	v_add_f32_e32 v96, v220, v96
	v_exp_f32_e32 v107, v159
	v_add_f32_e32 v96, v221, v96
	v_add_f32_e32 v96, v104, v96
	v_add_f32_e32 v96, v105, v96
	v_add_f32_e32 v96, v106, v96
	v_add_f32_e32 v96, v107, v96
	v_add_f32_e32 v96, v108, v96
	v_add_f32_e32 v96, v109, v96
	v_add_f32_e32 v96, v110, v96
	v_add_f32_e32 v96, v111, v96
	v_add_f32_e32 v96, v114, v96
	v_add_f32_e32 v96, v115, v96
	v_cvt_pk_bf16_f32 v104, v104, v105
	v_cvt_pk_bf16_f32 v105, v106, v107
	v_cvt_pk_bf16_f32 v106, v108, v109
	v_cvt_pk_bf16_f32 v108, v114, v115
	v_max_f32_e32 v114, v81, v81
	v_max_f32_e32 v115, v80, v80
	v_max_f32_e32 v114, v115, v114
	v_max3_f32 v114, v114, v82, v83
	v_max3_f32 v114, v114, v84, v85
	v_max3_f32 v114, v114, v86, v87
	v_max3_f32 v114, v114, v88, v89
	v_max3_f32 v114, v114, v90, v91
	v_max3_f32 v114, v114, v92, v93
	v_max3_f32 v114, v114, v94, v95
	v_max3_f32 v114, v114, v64, v65
	v_max3_f32 v114, v114, v66, v67
	v_max3_f32 v114, v114, v68, v69
	v_max3_f32 v114, v114, v70, v71
	v_max3_f32 v114, v114, v72, v73
	v_max3_f32 v114, v114, v74, v75
	v_max3_f32 v114, v114, v76, v77
	v_max3_f32 v114, v114, v78, v79
	v_mov_b32_e32 v115, v114
	s_nop 1
	v_permlane32_swap_b32_e32 v114, v115
	v_max_f32_e32 v115, v115, v115
	v_max_f32_e32 v114, v114, v114
	v_max_f32_e32 v114, v114, v115
	v_sub_f32_e32 v115, v114, v178
	v_cmp_ge_f32_e32 vcc, s56, v115
	v_max_f32_e32 v115, v178, v178
	v_add_f32_e32 v96, v116, v96
	v_max_f32_e32 v115, v115, v114
	v_add_f32_e32 v96, v117, v96
	v_sub_f32_e32 v114, v178, v115
	v_add_f32_e32 v96, v118, v96
	v_mul_f32_e32 v114, 0x3dd53b94, v114
	v_add_f32_e32 v96, v119, v96
	v_exp_f32_e32 v114, v114
	v_add_f32_e32 v96, v120, v96
	v_add_f32_e32 v112, v121, v96
	s_cmp_eq_u64 vcc, exec
	v_mov_b32_e32 v113, v112
	s_cselect_b64 s[8:9], -1, 0
	s_nop 0
	v_permlane32_swap_b32_e32 v112, v113
	v_cndmask_b32_e64 v114, v114, 1.0, s[8:9]
	v_cvt_pk_bf16_f32 v96, v184, v185
	v_cvt_pk_bf16_f32 v97, v189, v191
	v_cvt_pk_bf16_f32 v98, v198, v200
	v_cvt_pk_bf16_f32 v99, v214, v217
	v_cvt_pk_bf16_f32 v107, v110, v111
	v_cvt_pk_bf16_f32 v109, v116, v117
	v_cvt_pk_bf16_f32 v110, v118, v119
	v_cvt_pk_bf16_f32 v111, v120, v121
	v_add_u32_e32 v132, s15, v168
	ds_read_b64_tr_b16 v[116:117], v132 offset:0
	ds_read_b64_tr_b16 v[118:119], v132 offset:0x800
	ds_read_b64_tr_b16 v[120:121], v132 offset:0x1000
	ds_read_b64_tr_b16 v[122:123], v132 offset:0x1800
	ds_read_b64_tr_b16 v[124:125], v132 offset:0x2000
	ds_read_b64_tr_b16 v[126:127], v132 offset:0x2800
	ds_read_b64_tr_b16 v[128:129], v132 offset:0x3000
	ds_read_b64_tr_b16 v[130:131], v132 offset:0x3800
	s_waitcnt lgkmcnt(6)
; #define SBAR() __builtin_amdgcn_sched_barrier(0)
; #define RESC(a) do { if (__any((a) < 1.f)) { if (hi == 0) al_l[r32] = (a); asm volatile("s_waitcnt lgkmcnt(0)" ::: "memory"); \
;     _Pragma("unroll") for (int d = 0; d < 4; ++d) _Pragma("unroll") for (int r = 0; r < 16; ++r) o[d][r] *= al_l[crow(r, hi)]; } } while (0)
; #define PVSM(VB, P0, P1, MN) do { if constexpr (MI) pv_mi(o, VB, pa0, pa1, pa2, pa3, P0); else pv_sm(o, VB, pa0, pa1, pa2, pa3, P0, P1, C, MN); } while (0)
; template <int D0> __device__ __forceinline__ void pv_one_sm(f32x16& od, int vb, bf16x8 pa0, bf16x8 pa1, bf16x8 pa2, bf16x8 pa3, f32x16& q0, f32x16& q1, const float C, const float mnC) {
;   const s16x4 l0 = tr_read<v_rd_off(D0, 0, 0)>(vb), h0 = tr_read<v_rd_off(D0, 0, 1)>(vb), l1 = tr_read<v_rd_off(D0, 1, 0)>(vb), h1 = tr_read<v_rd_off(D0, 1, 1)>(vb);
;   const s16x4 l2 = tr_read<v_rd_off(D0, 2, 0)>(vb), h2 = tr_read<v_rd_off(D0, 2, 1)>(vb), l3 = tr_read<v_rd_off(D0, 3, 0)>(vb), h3 = tr_read<v_rd_off(D0, 3, 1)>(vb);
;   asm volatile("s_waitcnt lgkmcnt(0)" ::: "memory"); SBAR();
;     ...
;   od = __builtin_amdgcn_mfma_f32_32x32x16_bf16(pa0, PK(l0, h0), od, 0, 0, 0);
;   od = __builtin_amdgcn_mfma_f32_32x32x16_bf16(pa1, PK(l1, h1), od, 0, 0, 0);
;   od = __builtin_amdgcn_mfma_f32_32x32x16_bf16(pa2, PK(l2, h2), od, 0, 0, 0);
;   od = __builtin_amdgcn_mfma_f32_32x32x16_bf16(pa3, PK(l3, h3), od, 0, 0, 0);
;     ...
;   if (D0 < 2) {
; #pragma unroll
;     for (int r = 8 * D0; r < 8 * D0 + 8; ++r) q0[r] = __builtin_amdgcn_exp2f(fmaf(q0[r], C, mnC));
;   } else {
; #pragma unroll
;     for (int r = 8 * (D0 - 2); r < 8 * (D0 - 2) + 8; ++r) q1[r] = fmaf(q1[r], C, mnC);
;   }
; }
; template <int NQK, int SD, bool MI> ...
;     ...
;   PVSM(vb0 + rp * SHM_V, pB0, pB1, mnB);
;   RESC(alB);
	s_nop 0
	v_mfma_f32_32x32x16_bf16 v[0:15], v[96:99], v[116:119], v[0:15]
	ds_read_b64_tr_b16 v[116:117], v132 offset:0x200
	ds_read_b64_tr_b16 v[118:119], v132 offset:0xa00
	s_waitcnt lgkmcnt(6)
	v_mfma_f32_32x32x16_bf16 v[0:15], v[100:103], v[120:123], v[0:15]
	ds_read_b64_tr_b16 v[120:121], v132 offset:0x1200
	ds_read_b64_tr_b16 v[122:123], v132 offset:0x1a00
	s_waitcnt lgkmcnt(6)
	v_mfma_f32_32x32x16_bf16 v[0:15], v[104:107], v[124:127], v[0:15]
	ds_read_b64_tr_b16 v[124:125], v132 offset:0x2200
	ds_read_b64_tr_b16 v[126:127], v132 offset:0x2a00
	s_waitcnt lgkmcnt(6)
	v_mfma_f32_32x32x16_bf16 v[0:15], v[108:111], v[128:131], v[0:15]
	ds_read_b64_tr_b16 v[128:129], v132 offset:0x3200
	ds_read_b64_tr_b16 v[130:131], v132 offset:0x3a00
	s_waitcnt lgkmcnt(6)
	v_mfma_f32_32x32x16_bf16 v[48:63], v[96:99], v[116:119], v[48:63]
	ds_read_b64_tr_b16 v[116:117], v132 offset:0x400
	ds_read_b64_tr_b16 v[118:119], v132 offset:0xc00
	s_waitcnt lgkmcnt(6)
	v_mfma_f32_32x32x16_bf16 v[48:63], v[100:103], v[120:123], v[48:63]
	ds_read_b64_tr_b16 v[120:121], v132 offset:0x1400
	ds_read_b64_tr_b16 v[122:123], v132 offset:0x1c00
	s_waitcnt lgkmcnt(6)
	v_mfma_f32_32x32x16_bf16 v[48:63], v[104:107], v[124:127], v[48:63]
	ds_read_b64_tr_b16 v[124:125], v132 offset:0x2400
	ds_read_b64_tr_b16 v[126:127], v132 offset:0x2c00
	s_waitcnt lgkmcnt(6)
	v_mfma_f32_32x32x16_bf16 v[48:63], v[108:111], v[128:131], v[48:63]
	ds_read_b64_tr_b16 v[128:129], v132 offset:0x3400
	ds_read_b64_tr_b16 v[130:131], v132 offset:0x3c00
	s_waitcnt lgkmcnt(6)
	v_mfma_f32_32x32x16_bf16 v[32:47], v[96:99], v[116:119], v[32:47]
	ds_read_b64_tr_b16 v[116:117], v132 offset:0x600
	ds_read_b64_tr_b16 v[118:119], v132 offset:0xe00
	s_waitcnt lgkmcnt(6)
	v_mfma_f32_32x32x16_bf16 v[32:47], v[100:103], v[120:123], v[32:47]
	ds_read_b64_tr_b16 v[120:121], v132 offset:0x1600
	ds_read_b64_tr_b16 v[122:123], v132 offset:0x1e00
	s_waitcnt lgkmcnt(6)
	v_mfma_f32_32x32x16_bf16 v[32:47], v[104:107], v[124:127], v[32:47]
	ds_read_b64_tr_b16 v[124:125], v132 offset:0x2600
	ds_read_b64_tr_b16 v[126:127], v132 offset:0x2e00
	s_waitcnt lgkmcnt(6)
	v_mfma_f32_32x32x16_bf16 v[32:47], v[108:111], v[128:131], v[32:47]
	ds_read_b64_tr_b16 v[128:129], v132 offset:0x3600
	ds_read_b64_tr_b16 v[130:131], v132 offset:0x3e00
	s_waitcnt lgkmcnt(0)
	v_mfma_f32_32x32x16_bf16 v[16:31], v[96:99], v[116:119], v[16:31]
	v_cmp_gt_f32_e32 vcc, 1.0, v114
	v_mfma_f32_32x32x16_bf16 v[16:31], v[100:103], v[120:123], v[16:31]
	v_mfma_f32_32x32x16_bf16 v[16:31], v[104:107], v[124:127], v[16:31]
	v_mfma_f32_32x32x16_bf16 v[16:31], v[108:111], v[128:131], v[16:31]
	s_cbranch_vccz .LBB0_2553
	s_and_saveexec_b64 s[10:11], s[6:7]
	s_movk_i32 s51, 0x4000
	v_readlane_b32 s44, v255, 32
	v_readlane_b32 s45, v255, 33
	ds_write_b32 v166, v114 offset:128
	s_or_b64 exec, exec, s[10:11]
	s_waitcnt lgkmcnt(0)
	v_add_u32_e32 v108, v165, v162
	ds_read_b128 v[96:99], v108 offset:224
	ds_read_b128 v[100:103], v108 offset:192
	ds_read_b128 v[104:107], v108 offset:160
	ds_read_b128 v[108:111], v108 offset:128
	s_waitcnt lgkmcnt(3)
	v_pk_mul_f32 v[12:13], v[12:13], v[96:97]
	s_waitcnt lgkmcnt(2)
	v_pk_mul_f32 v[8:9], v[8:9], v[100:101]
	s_waitcnt lgkmcnt(1)
	v_pk_mul_f32 v[4:5], v[4:5], v[104:105]
	v_pk_mul_f32 v[14:15], v[14:15], v[98:99]
	v_pk_mul_f32 v[10:11], v[10:11], v[102:103]
	v_pk_mul_f32 v[6:7], v[6:7], v[106:107]
	s_waitcnt lgkmcnt(0)
	v_pk_mul_f32 v[2:3], v[2:3], v[110:111]
	v_pk_mul_f32 v[0:1], v[0:1], v[108:109]
	v_pk_mul_f32 v[60:61], v[60:61], v[96:97]
	v_pk_mul_f32 v[56:57], v[56:57], v[100:101]
	v_pk_mul_f32 v[52:53], v[52:53], v[104:105]
	v_pk_mul_f32 v[62:63], v[62:63], v[98:99]
	v_pk_mul_f32 v[58:59], v[58:59], v[102:103]
	v_pk_mul_f32 v[54:55], v[54:55], v[106:107]
	v_pk_mul_f32 v[50:51], v[50:51], v[110:111]
	v_pk_mul_f32 v[48:49], v[48:49], v[108:109]
	v_pk_mul_f32 v[44:45], v[44:45], v[96:97]
	v_pk_mul_f32 v[40:41], v[40:41], v[100:101]
	v_pk_mul_f32 v[36:37], v[36:37], v[104:105]
	v_pk_mul_f32 v[46:47], v[46:47], v[98:99]
	v_pk_mul_f32 v[42:43], v[42:43], v[102:103]
	v_pk_mul_f32 v[38:39], v[38:39], v[106:107]
	v_pk_mul_f32 v[34:35], v[34:35], v[110:111]
	v_pk_mul_f32 v[32:33], v[32:33], v[108:109]
	v_pk_mul_f32 v[28:29], v[28:29], v[96:97]
	v_pk_mul_f32 v[24:25], v[24:25], v[100:101]
	v_pk_mul_f32 v[20:21], v[20:21], v[104:105]
	v_pk_mul_f32 v[30:31], v[30:31], v[98:99]
	v_pk_mul_f32 v[26:27], v[26:27], v[102:103]
	v_pk_mul_f32 v[22:23], v[22:23], v[106:107]
	v_pk_mul_f32 v[18:19], v[18:19], v[110:111]
	v_pk_mul_f32 v[16:17], v[16:17], v[108:109]
	s_branch .LBB0_2554

; #define SBAR() __builtin_amdgcn_sched_barrier(0)
; #define PK4(P, BASE, OUT) do { u32x4 w = {cvtb(P[BASE + 0], P[BASE + 1]), cvtb(P[BASE + 2], P[BASE + 3]), \
;     cvtb(P[BASE + 4], P[BASE + 5]), cvtb(P[BASE + 6], P[BASE + 7])}; OUT = *reinterpret_cast<bf16x8*>(&w); } while (0)
; __device__ __forceinline__ void finishSM(f32x16& p0, f32x16& p1, float alpha, float& l_reg, bf16x8& pa0, bf16x8& pa1, bf16x8& pa2, bf16x8& pa3) {
; #pragma unroll
;   for (int r = 0; r < 16; ++r) p1[r] = __builtin_amdgcn_exp2f(p1[r]);
;   float ps = 0;
; #pragma unroll
;   for (int r = 0; r < 16; ++r) ps += p0[r];
; #pragma unroll
;   for (int r = 0; r < 16; ++r) ps += p1[r];
;   { auto rr = __builtin_amdgcn_permlane32_swap(__float_as_uint(ps), __float_as_uint(ps), false, false);
;     ps = __uint_as_float(rr[0]) + __uint_as_float(rr[1]); }
;   l_reg = l_reg * alpha + ps;
;     ...
;   PK4(p0, 0, pa0); PK4(p0, 8, pa1); PK4(p1, 0, pa2); PK4(p1, 8, pa3);
;     ...
; }
; template <int NQK, int SD, bool MI> ...
;     ...
;   finishSM(pB0, pB1, alB, l_reg, pa0, pa1, pa2, pa3); SBAR();
;   pv_d0(o, vb0 + rc * SHM_V, pa0, pa1, pa2, pa3);
;     ...
;   if (hi == 0) li_l[r32] = l_reg; asm volatile("s_waitcnt lgkmcnt(0)" ::: "memory");
.LBB0_2554:
	v_cndmask_b32_e64 v96, v115, v178, s[8:9]
	v_mul_f32_e32 v96, 0xbdd53b94, v96
	v_fmamk_f32 v80, v80, 0x3dd53b94, v96
	v_exp_f32_e32 v80, v80
	v_fmamk_f32 v81, v81, 0x3dd53b94, v96
	v_exp_f32_e32 v81, v81
	v_fmamk_f32 v82, v82, 0x3dd53b94, v96
	v_exp_f32_e32 v82, v82
	v_fmamk_f32 v83, v83, 0x3dd53b94, v96
	v_exp_f32_e32 v83, v83
	v_fmamk_f32 v84, v84, 0x3dd53b94, v96
	v_fmamk_f32 v64, v64, 0x3dd53b94, v96
	v_exp_f32_e32 v84, v84
	v_fmamk_f32 v85, v85, 0x3dd53b94, v96
	v_fmamk_f32 v86, v86, 0x3dd53b94, v96
	v_fmamk_f32 v87, v87, 0x3dd53b94, v96
	v_fmamk_f32 v88, v88, 0x3dd53b94, v96
	v_fmamk_f32 v89, v89, 0x3dd53b94, v96
	v_fmamk_f32 v90, v90, 0x3dd53b94, v96
	v_fmamk_f32 v91, v91, 0x3dd53b94, v96
	v_fmamk_f32 v92, v92, 0x3dd53b94, v96
	v_fmamk_f32 v93, v93, 0x3dd53b94, v96
	v_fmamk_f32 v94, v94, 0x3dd53b94, v96
	v_fmamk_f32 v95, v95, 0x3dd53b94, v96
	v_fmamk_f32 v65, v65, 0x3dd53b94, v96
	v_fmamk_f32 v66, v66, 0x3dd53b94, v96
	v_fmamk_f32 v67, v67, 0x3dd53b94, v96
	v_fmamk_f32 v68, v68, 0x3dd53b94, v96
	v_fmamk_f32 v69, v69, 0x3dd53b94, v96
	v_fmamk_f32 v70, v70, 0x3dd53b94, v96
	v_fmamk_f32 v71, v71, 0x3dd53b94, v96
	v_fmamk_f32 v72, v72, 0x3dd53b94, v96
	v_fmamk_f32 v73, v73, 0x3dd53b94, v96
	v_fmamk_f32 v74, v74, 0x3dd53b94, v96
	v_fmamk_f32 v75, v75, 0x3dd53b94, v96
	v_fmamk_f32 v76, v76, 0x3dd53b94, v96
	v_fmamk_f32 v77, v77, 0x3dd53b94, v96
	v_fmamk_f32 v78, v78, 0x3dd53b94, v96
	v_fmac_f32_e32 v96, 0x3dd53b94, v79
	v_exp_f32_e32 v79, v64
	v_add_f32_e32 v64, 0, v80
	v_exp_f32_e32 v85, v85
	v_add_f32_e32 v64, v81, v64
	v_exp_f32_e32 v86, v86
	v_add_f32_e32 v64, v82, v64
	v_exp_f32_e32 v87, v87
	v_add_f32_e32 v64, v83, v64
	v_exp_f32_e32 v88, v88
	v_add_f32_e32 v64, v84, v64
	v_exp_f32_e32 v89, v89
	v_add_f32_e32 v64, v85, v64
	v_exp_f32_e32 v90, v90
	v_add_f32_e32 v64, v86, v64
	v_exp_f32_e32 v91, v91
	v_add_f32_e32 v64, v87, v64
	v_exp_f32_e32 v92, v92
	v_add_f32_e32 v64, v88, v64
	v_exp_f32_e32 v93, v93
	v_add_f32_e32 v64, v89, v64
	v_exp_f32_e32 v94, v94
	v_add_f32_e32 v64, v90, v64
	v_exp_f32_e32 v95, v95
	v_add_f32_e32 v64, v91, v64
	v_add_f32_e32 v64, v92, v64
	v_exp_f32_e32 v97, v65
	v_add_f32_e32 v64, v93, v64
	v_exp_f32_e32 v98, v66
	v_add_f32_e32 v64, v94, v64
	v_exp_f32_e32 v99, v67
	v_add_f32_e32 v64, v95, v64
	v_exp_f32_e32 v100, v68
	v_add_f32_e32 v64, v79, v64
	v_exp_f32_e32 v101, v69
	v_add_f32_e32 v64, v97, v64
	v_exp_f32_e32 v102, v70
	v_add_f32_e32 v64, v98, v64
	v_exp_f32_e32 v103, v71
	v_add_f32_e32 v64, v99, v64
	v_exp_f32_e32 v104, v72
	v_add_f32_e32 v64, v100, v64
	v_exp_f32_e32 v105, v73
	v_add_f32_e32 v64, v101, v64
	v_exp_f32_e32 v106, v74
	v_add_f32_e32 v64, v102, v64
	v_exp_f32_e32 v107, v75
	v_add_f32_e32 v64, v103, v64
	v_exp_f32_e32 v108, v76
	v_add_f32_e32 v64, v104, v64
	v_exp_f32_e32 v109, v77
	v_add_f32_e32 v64, v105, v64
	v_exp_f32_e32 v110, v78
	v_add_f32_e32 v64, v106, v64
	v_exp_f32_e32 v96, v96
	v_add_f32_e32 v64, v107, v64
	v_add_f32_e32 v64, v108, v64
	v_add_f32_e32 v64, v109, v64
	v_add_f32_e32 v64, v110, v64
	v_add_f32_e32 v64, v96, v64
	v_mov_b32_e32 v65, v64
	s_nop 1
	v_permlane32_swap_b32_e32 v64, v65
	v_cvt_pk_bf16_f32 v66, v80, v81
	v_cvt_pk_bf16_f32 v67, v82, v83
	v_cvt_pk_bf16_f32 v68, v84, v85
	v_cvt_pk_bf16_f32 v69, v86, v87
	v_cvt_pk_bf16_f32 v70, v88, v89
	v_cvt_pk_bf16_f32 v71, v90, v91
	v_cvt_pk_bf16_f32 v72, v92, v93
	v_cvt_pk_bf16_f32 v73, v94, v95
	v_cvt_pk_bf16_f32 v74, v79, v97
	v_cvt_pk_bf16_f32 v75, v98, v99
	v_cvt_pk_bf16_f32 v76, v100, v101
	v_cvt_pk_bf16_f32 v77, v102, v103
	v_cvt_pk_bf16_f32 v78, v104, v105
	v_cvt_pk_bf16_f32 v79, v106, v107
	v_cvt_pk_bf16_f32 v80, v108, v109
	v_cvt_pk_bf16_f32 v81, v110, v96
	ds_read_b64_tr_b16 v[82:83], v169 offset:0
	ds_read_b64_tr_b16 v[84:85], v169 offset:0x800
	ds_read_b64_tr_b16 v[86:87], v169 offset:0x1000
	ds_read_b64_tr_b16 v[88:89], v169 offset:0x1800
	ds_read_b64_tr_b16 v[90:91], v169 offset:0x2000
	ds_read_b64_tr_b16 v[92:93], v169 offset:0x2800
	ds_read_b64_tr_b16 v[94:95], v169 offset:0x3000
	ds_read_b64_tr_b16 v[96:97], v169 offset:0x3800
	s_waitcnt lgkmcnt(6)
	s_nop 0
	v_mfma_f32_32x32x16_bf16 v[0:15], v[66:69], v[82:85], v[0:15]
	ds_read_b64_tr_b16 v[82:83], v169 offset:0x200
	ds_read_b64_tr_b16 v[84:85], v169 offset:0xa00
	s_waitcnt lgkmcnt(6)
	v_mfma_f32_32x32x16_bf16 v[0:15], v[70:73], v[86:89], v[0:15]
	ds_read_b64_tr_b16 v[86:87], v169 offset:0x1200
	ds_read_b64_tr_b16 v[88:89], v169 offset:0x1a00
	s_waitcnt lgkmcnt(6)
	v_mfma_f32_32x32x16_bf16 v[0:15], v[74:77], v[90:93], v[0:15]
	ds_read_b64_tr_b16 v[90:91], v169 offset:0x2200
	ds_read_b64_tr_b16 v[92:93], v169 offset:0x2a00
	s_waitcnt lgkmcnt(6)
	v_mfma_f32_32x32x16_bf16 v[0:15], v[78:81], v[94:97], v[0:15]
	ds_read_b64_tr_b16 v[94:95], v169 offset:0x3200
	ds_read_b64_tr_b16 v[96:97], v169 offset:0x3a00
	s_waitcnt lgkmcnt(6)
	v_mfma_f32_32x32x16_bf16 v[48:63], v[66:69], v[82:85], v[48:63]
	ds_read_b64_tr_b16 v[82:83], v169 offset:0x400
	ds_read_b64_tr_b16 v[84:85], v169 offset:0xc00
	s_waitcnt lgkmcnt(6)
	v_mfma_f32_32x32x16_bf16 v[48:63], v[70:73], v[86:89], v[48:63]
	ds_read_b64_tr_b16 v[86:87], v169 offset:0x1400
	ds_read_b64_tr_b16 v[88:89], v169 offset:0x1c00
	s_waitcnt lgkmcnt(6)
	v_mfma_f32_32x32x16_bf16 v[48:63], v[74:77], v[90:93], v[48:63]
	ds_read_b64_tr_b16 v[90:91], v169 offset:0x2400
	ds_read_b64_tr_b16 v[92:93], v169 offset:0x2c00
	s_waitcnt lgkmcnt(6)
	v_mfma_f32_32x32x16_bf16 v[48:63], v[78:81], v[94:97], v[48:63]
	ds_read_b64_tr_b16 v[94:95], v169 offset:0x3400
	ds_read_b64_tr_b16 v[96:97], v169 offset:0x3c00
	s_waitcnt lgkmcnt(6)
	v_mfma_f32_32x32x16_bf16 v[32:47], v[66:69], v[82:85], v[32:47]
	ds_read_b64_tr_b16 v[82:83], v169 offset:0x600
	ds_read_b64_tr_b16 v[84:85], v169 offset:0xe00
	s_waitcnt lgkmcnt(6)
	v_mfma_f32_32x32x16_bf16 v[32:47], v[70:73], v[86:89], v[32:47]
	ds_read_b64_tr_b16 v[86:87], v169 offset:0x1600
	ds_read_b64_tr_b16 v[88:89], v169 offset:0x1e00
	s_waitcnt lgkmcnt(6)
	v_mfma_f32_32x32x16_bf16 v[32:47], v[74:77], v[90:93], v[32:47]
	ds_read_b64_tr_b16 v[90:91], v169 offset:0x2600
	ds_read_b64_tr_b16 v[92:93], v169 offset:0x2e00
	s_waitcnt lgkmcnt(6)
	v_mfma_f32_32x32x16_bf16 v[32:47], v[78:81], v[94:97], v[32:47]
	ds_read_b64_tr_b16 v[94:95], v169 offset:0x3600
	ds_read_b64_tr_b16 v[96:97], v169 offset:0x3e00
	s_waitcnt lgkmcnt(0)
	v_mfma_f32_32x32x16_bf16 v[16:31], v[66:69], v[82:85], v[16:31]
	v_mfma_f32_32x32x16_bf16 v[16:31], v[70:73], v[86:89], v[16:31]
	v_mfma_f32_32x32x16_bf16 v[16:31], v[74:77], v[90:93], v[16:31]
	v_mfma_f32_32x32x16_bf16 v[16:31], v[78:81], v[94:97], v[16:31]
	s_and_saveexec_b64 s[8:9], s[6:7]
	s_cbranch_execz .LBB0_2515
	v_add_f32_e32 v66, v112, v113
	v_fmac_f32_e32 v66, v167, v180
	v_add_f32_e32 v64, v64, v65
	v_fmac_f32_e32 v64, v66, v114
	ds_write_b32 v166, v64
	s_branch .LBB0_2515
